# GEMM K-loops: LDS-DMA issue balanced 2/4/4/6 per phase (RA1 refill moved from phase II to the head of phase III, phase II wait vmcnt(6))
# baseline (speedup 1.0000x reference)
; #define PG8_STAGE(bufoff, gbase, voff) do { _Pragma("unroll") for (int _i = 0; _i < 2; ++_i) \
;         __builtin_amdgcn_global_load_lds((const unsigned*)((const char*)(gbase) + (voff)[_i]), (LAS unsigned*)(lds + (bufoff) + ldsw + _i * 8192), 16, 0, 0); } while (0)
; #define PG8_LDA(dst, b, h) do { _Pragma("unroll") for (int m = 0; m < 4; ++m) _Pragma("unroll") for (int k = 0; k < 2; ++k) dst[m][k] = *(const LAS bf16x8*)(lds + PG8_SA(b, h) + aoff + m * 2048 + k * 1024); } while (0)
; #define PG8_LDB(dst, b, h) do { _Pragma("unroll") for (int n = 0; n < 2; ++n) _Pragma("unroll") for (int k = 0; k < 2; ++k) dst[n][k] = *(const LAS bf16x8*)(lds + PG8_SB(b, h) + boff + n * 2048 + k * 1024); } while (0)
; #define PG8_WAIT_V(n) asm volatile("s_waitcnt vmcnt(" #n ")" ::: "memory")
; #define PG8_WAIT_L(n) asm volatile("s_waitcnt lgkmcnt(" #n ")" ::: "memory")
; #define PG8_BAR __builtin_amdgcn_s_barrier()
; #define PG8_SCHED __builtin_amdgcn_sched_barrier(0)
; template <class Epi>
; __device__ __forceinline__ void gemm_phase(LAS unsigned char* lds, const Gemm g, const StaticOrder& S, const Epi& E) {
;     ...
;         const bool has_next = S.next(ui + 1, nxt);
;         const char* nA = has_next ? (const char*)g.A + (size_t)nxt.pm * tstepA + (size_t)nxt.kt0 * kstep : cA; const char* nB = has_next ? (const char*)g.Bt + (size_t)nxt.pn * tstepB + (size_t)nxt.kt0 * kstep : cB;
;         const int nt = cur.nkt;
;         for (int t = 0; t < nt; t += 2) {
;             const bool last = (t == nt - 2);
;             const char* a1 = cA + (size_t)(t + 1) * kstep;
;             const char* a2 = last ? nA : cA + (size_t)(t + 2) * kstep; const char* b2 = last ? nB : cB + (size_t)(t + 2) * kstep;
;             const char* a3 = a2 + kstep; const char* b3 = b2 + kstep;
;             PG8_LDB(B0, 0, 0); PG8_SCHED; PG8_LDA(At, 0, 0); PG8_STAGE(PG8_SA(1, 1), a1 + hstepA, voffA);
;             PG8_WAIT_L(8); PG8_BAR; PG8_WAIT_L(0); PG8_MMA(0, 0, At, B0); PG8_BAR; PG8_SCHED;
;             PG8_LDB(B1, 0, 1); PG8_STAGE(PG8_SB(0, 0), b2, voffB);
;             PG8_BAR; PG8_WAIT_L(0); PG8_MMA(0, 1, At, B1); PG8_BAR;
;             PG8_LDA(At, 0, 1); PG8_STAGE(PG8_SA(0, 0), a2, voffA);
;             PG8_BAR; PG8_WAIT_L(0); PG8_MMA(1, 0, At, B0); PG8_BAR; PG8_SCHED;
;             PG8_STAGE(PG8_SB(0, 1), b2 + hstepB, voffB);
;             PG8_WAIT_V(6); PG8_BAR; PG8_MMA(1, 1, At, B1); PG8_BAR;
.LBB0_118:
	s_ashr_i32 s55, s54, 31
	v_cmp_lt_i64_e32 vcc, s[56:57], v[142:143]
	s_lshl_b64 s[56:57], s[54:55], 19
	s_add_u32 s9, s52, s56
	s_addc_u32 s31, s53, s57
	s_and_b64 s[56:57], vcc, exec
	s_cselect_b32 s57, s31, s63
	s_cselect_b32 s56, s9, s62
	s_ashr_i32 s31, s30, 31
	s_lshl_b64 s[58:59], s[30:31], 19
	s_add_u32 s9, s92, s58
	s_addc_u32 s31, s93, s59
	s_and_b64 s[58:59], vcc, exec
	s_cselect_b32 s59, s31, s65
	s_cselect_b32 s58, s9, s64
	s_add_u32 s62, s62, 0x40080
	s_addc_u32 s63, s63, 0
	s_add_u32 s9, s64, 0x100
	s_addc_u32 s31, s65, 0
	s_mov_b32 s33, -2
	s_add_u32 s55, s62, 0xfffc0080
	s_addc_u32 s61, s63, -1
	s_cmp_eq_u32 s33, 12
	s_cselect_b32 s67, s57, s61
	s_cselect_b32 s66, s56, s55
	s_cselect_b32 s65, s59, s31
	s_cselect_b32 s64, s58, s9
	ds_read_b128 v[146:149], v154
	ds_read_b128 v[158:161], v154 offset:1024
	ds_read_b128 v[162:165], v154 offset:2048
	ds_read_b128 v[166:169], v154 offset:3072
	ds_read_b128 v[170:173], v155
	ds_read_b128 v[174:177], v155 offset:1024
	ds_read_b128 v[178:181], v155 offset:2048
	ds_read_b128 v[182:185], v155 offset:3072
	ds_read_b128 v[186:189], v155 offset:4096
	ds_read_b128 v[190:193], v155 offset:5120
	ds_read_b128 v[194:197], v155 offset:6144
	ds_read_b128 v[198:201], v155 offset:7168
	ds_read_b128 v[202:205], v156
	ds_read_b128 v[206:209], v156 offset:1024
	ds_read_b128 v[210:213], v156 offset:2048
	ds_read_b128 v[214:217], v156 offset:3072
	s_add_i32 m0, s68, 0xc000
	v_lshl_add_u64 v[242:243], s[62:63], 0, v[138:139]
	global_load_lds_dwordx4 v[242:243], off
	s_add_i32 m0, s68, 0xe000
	v_lshl_add_u64 v[242:243], s[62:63], 0, v[140:141]
	global_load_lds_dwordx4 v[242:243], off
	s_waitcnt vmcnt(8) lgkmcnt(0)
	s_barrier
	v_mfma_f32_16x16x32_bf16 v[124:127], v[146:149], v[170:173], 0
	v_mfma_f32_16x16x32_bf16 v[120:123], v[162:165], v[170:173], 0
	v_mfma_f32_16x16x32_bf16 v[108:111], v[146:149], v[178:181], 0
	v_mfma_f32_16x16x32_bf16 v[104:107], v[162:165], v[178:181], 0
	v_mfma_f32_16x16x32_bf16 v[92:95], v[146:149], v[186:189], 0
	v_mfma_f32_16x16x32_bf16 v[88:91], v[162:165], v[186:189], 0
	v_mfma_f32_16x16x32_bf16 v[76:79], v[146:149], v[194:197], 0
	v_mfma_f32_16x16x32_bf16 v[72:75], v[162:165], v[194:197], 0
	v_mfma_f32_16x16x32_bf16 v[124:127], v[158:161], v[174:177], v[124:127]
	v_mfma_f32_16x16x32_bf16 v[120:123], v[166:169], v[174:177], v[120:123]
	v_mfma_f32_16x16x32_bf16 v[108:111], v[158:161], v[182:185], v[108:111]
	v_mfma_f32_16x16x32_bf16 v[104:107], v[166:169], v[182:185], v[104:107]
	v_mfma_f32_16x16x32_bf16 v[92:95], v[158:161], v[190:193], v[92:95]
	v_mfma_f32_16x16x32_bf16 v[88:91], v[166:169], v[190:193], v[88:91]
	v_mfma_f32_16x16x32_bf16 v[76:79], v[158:161], v[198:201], v[76:79]
	v_mfma_f32_16x16x32_bf16 v[72:75], v[166:169], v[198:201], v[72:75]
	v_mfma_f32_16x16x32_bf16 v[116:119], v[202:205], v[170:173], 0
	v_mfma_f32_16x16x32_bf16 v[112:115], v[210:213], v[170:173], 0
	v_mfma_f32_16x16x32_bf16 v[100:103], v[202:205], v[178:181], 0
	v_mfma_f32_16x16x32_bf16 v[96:99], v[210:213], v[178:181], 0
	v_mfma_f32_16x16x32_bf16 v[84:87], v[202:205], v[186:189], 0
	v_mfma_f32_16x16x32_bf16 v[80:83], v[210:213], v[186:189], 0
	v_mfma_f32_16x16x32_bf16 v[68:71], v[202:205], v[194:197], 0
	v_mfma_f32_16x16x32_bf16 v[64:67], v[210:213], v[194:197], 0
	v_mfma_f32_16x16x32_bf16 v[116:119], v[206:209], v[174:177], v[116:119]
	v_mfma_f32_16x16x32_bf16 v[112:115], v[214:217], v[174:177], v[112:115]
	v_mfma_f32_16x16x32_bf16 v[100:103], v[206:209], v[182:185], v[100:103]
	v_mfma_f32_16x16x32_bf16 v[96:99], v[214:217], v[182:185], v[96:99]
	v_mfma_f32_16x16x32_bf16 v[84:87], v[206:209], v[190:193], v[84:87]
	v_mfma_f32_16x16x32_bf16 v[80:83], v[214:217], v[190:193], v[80:83]
	v_mfma_f32_16x16x32_bf16 v[68:71], v[206:209], v[198:201], v[68:71]
	v_mfma_f32_16x16x32_bf16 v[64:67], v[214:217], v[198:201], v[64:67]
	s_barrier
	ds_read_b128 v[170:173], v155 offset:16384
	ds_read_b128 v[174:177], v155 offset:17408
	ds_read_b128 v[178:181], v155 offset:18432
	ds_read_b128 v[182:185], v155 offset:19456
	ds_read_b128 v[186:189], v155 offset:20480
	ds_read_b128 v[190:193], v155 offset:21504
	ds_read_b128 v[194:197], v155 offset:22528
	ds_read_b128 v[198:201], v155 offset:23552
	s_add_i32 s55, s78, s35
	s_mov_b32 m0, s55
	v_lshl_add_u64 v[218:219], s[64:65], 0, v[132:133]
	global_load_lds_dwordx4 v[218:219], off
	s_add_i32 m0, s55, 0x2000
	v_lshl_add_u64 v[220:221], s[64:65], 0, v[136:137]
	global_load_lds_dwordx4 v[220:221], off
	s_mov_b32 m0, s68
	v_lshl_add_u64 v[222:223], s[66:67], 0, v[130:131]
	global_load_lds_dwordx4 v[222:223], off
	s_mov_b32 m0, s69
	v_lshl_add_u64 v[224:225], s[66:67], 0, v[134:135]
	global_load_lds_dwordx4 v[224:225], off
	s_waitcnt vmcnt(6) lgkmcnt(0)
	s_barrier
; #define PG8_STAGE(bufoff, gbase, voff) do { _Pragma("unroll") for (int _i = 0; _i < 2; ++_i) \
;         __builtin_amdgcn_global_load_lds((const unsigned*)((const char*)(gbase) + (voff)[_i]), (LAS unsigned*)(lds + (bufoff) + ldsw + _i * 8192), 16, 0, 0); } while (0)
; #define PG8_LDA(dst, b, h) do { _Pragma("unroll") for (int m = 0; m < 4; ++m) _Pragma("unroll") for (int k = 0; k < 2; ++k) dst[m][k] = *(const LAS bf16x8*)(lds + PG8_SA(b, h) + aoff + m * 2048 + k * 1024); } while (0)
; #define PG8_LDB(dst, b, h) do { _Pragma("unroll") for (int n = 0; n < 2; ++n) _Pragma("unroll") for (int k = 0; k < 2; ++k) dst[n][k] = *(const LAS bf16x8*)(lds + PG8_SB(b, h) + boff + n * 2048 + k * 1024); } while (0)
; #define PG8_MMA(ai, bj, At, Bt) do { __builtin_amdgcn_s_setprio(1); _Pragma("unroll") for (int m = 0; m < 4; ++m) _Pragma("unroll") for (int n = 0; n < 2; ++n) _Pragma("unroll") for (int k = 0; k < 2; ++k) \
;         acc[ai][bj][m][n] = __builtin_amdgcn_mfma_f32_16x16x32_bf16(Bt[n][k], At[m][k], acc[ai][bj][m][n], 0, 0, 0); __builtin_amdgcn_s_setprio(0); } while (0)
; #define PG8_WAIT_V(n) asm volatile("s_waitcnt vmcnt(" #n ")" ::: "memory")
; #define PG8_WAIT_L(n) asm volatile("s_waitcnt lgkmcnt(" #n ")" ::: "memory")
; #define PG8_BAR __builtin_amdgcn_s_barrier()
; #define PG8_SCHED __builtin_amdgcn_sched_barrier(0)
; template <class Epi>
; __device__ __forceinline__ void gemm_phase(LAS unsigned char* lds, const Gemm g, const StaticOrder& S, const Epi& E) {
;     ...
;             PG8_BAR; PG8_WAIT_L(0); PG8_MMA(0, 1, At, B1); PG8_BAR;
;             PG8_LDA(At, 0, 1); PG8_STAGE(PG8_SA(0, 0), a2, voffA);
;             PG8_BAR; PG8_WAIT_L(0); PG8_MMA(1, 0, At, B0); PG8_BAR; PG8_SCHED;
;             PG8_STAGE(PG8_SB(0, 1), b2 + hstepB, voffB);
;             PG8_WAIT_V(6); PG8_BAR; PG8_MMA(1, 1, At, B1); PG8_BAR;
;             PG8_LDB(B0, 1, 0); PG8_SCHED; PG8_LDA(At, 1, 0); PG8_STAGE(PG8_SA(0, 1), a2 + hstepA, voffA);
;             PG8_WAIT_L(8); PG8_BAR; PG8_WAIT_L(0); PG8_MMA(0, 0, At, B0); PG8_BAR; PG8_SCHED;
;             PG8_LDB(B1, 1, 1); PG8_STAGE(PG8_SB(1, 0), b3, voffB);
;             PG8_BAR; PG8_WAIT_L(0); PG8_MMA(0, 1, At, B1); PG8_BAR;
;             PG8_LDA(At, 1, 1); PG8_STAGE(PG8_SA(1, 0), a3, voffA);
;             PG8_BAR; PG8_WAIT_L(0); PG8_MMA(1, 0, At, B0); PG8_BAR; PG8_SCHED;
	v_mfma_f32_16x16x32_bf16 v[60:63], v[146:149], v[170:173], 0
	v_mfma_f32_16x16x32_bf16 v[56:59], v[162:165], v[170:173], 0
	v_mfma_f32_16x16x32_bf16 v[44:47], v[146:149], v[178:181], 0
	v_mfma_f32_16x16x32_bf16 v[40:43], v[162:165], v[178:181], 0
	v_mfma_f32_16x16x32_bf16 v[28:31], v[146:149], v[186:189], 0
	v_mfma_f32_16x16x32_bf16 v[24:27], v[162:165], v[186:189], 0
	v_mfma_f32_16x16x32_bf16 v[12:15], v[146:149], v[194:197], 0
	v_mfma_f32_16x16x32_bf16 v[8:11], v[162:165], v[194:197], 0
	v_mfma_f32_16x16x32_bf16 v[60:63], v[158:161], v[174:177], v[60:63]
	v_mfma_f32_16x16x32_bf16 v[56:59], v[166:169], v[174:177], v[56:59]
	v_mfma_f32_16x16x32_bf16 v[44:47], v[158:161], v[182:185], v[44:47]
	v_mfma_f32_16x16x32_bf16 v[40:43], v[166:169], v[182:185], v[40:43]
	v_mfma_f32_16x16x32_bf16 v[28:31], v[158:161], v[190:193], v[28:31]
	v_mfma_f32_16x16x32_bf16 v[24:27], v[166:169], v[190:193], v[24:27]
	v_mfma_f32_16x16x32_bf16 v[12:15], v[158:161], v[198:201], v[12:15]
	v_mfma_f32_16x16x32_bf16 v[8:11], v[166:169], v[198:201], v[8:11]
	v_mfma_f32_16x16x32_bf16 v[52:55], v[202:205], v[170:173], 0
	v_mfma_f32_16x16x32_bf16 v[48:51], v[210:213], v[170:173], 0
	v_mfma_f32_16x16x32_bf16 v[36:39], v[202:205], v[178:181], 0
	v_mfma_f32_16x16x32_bf16 v[32:35], v[210:213], v[178:181], 0
	v_mfma_f32_16x16x32_bf16 v[20:23], v[202:205], v[186:189], 0
	v_mfma_f32_16x16x32_bf16 v[16:19], v[210:213], v[186:189], 0
	v_mfma_f32_16x16x32_bf16 v[4:7], v[202:205], v[194:197], 0
	v_mfma_f32_16x16x32_bf16 v[0:3], v[210:213], v[194:197], 0
	v_mfma_f32_16x16x32_bf16 v[52:55], v[206:209], v[174:177], v[52:55]
	v_mfma_f32_16x16x32_bf16 v[48:51], v[214:217], v[174:177], v[48:51]
	v_mfma_f32_16x16x32_bf16 v[36:39], v[206:209], v[182:185], v[36:39]
	v_mfma_f32_16x16x32_bf16 v[32:35], v[214:217], v[182:185], v[32:35]
	v_mfma_f32_16x16x32_bf16 v[20:23], v[206:209], v[190:193], v[20:23]
	v_mfma_f32_16x16x32_bf16 v[16:19], v[214:217], v[190:193], v[16:19]
	v_mfma_f32_16x16x32_bf16 v[4:7], v[206:209], v[198:201], v[4:7]
	v_mfma_f32_16x16x32_bf16 v[0:3], v[214:217], v[198:201], v[0:3]
	s_barrier
	s_add_i32 s55, 0, 0x18000
	v_add_u32_e32 v157, s55, v152
	ds_read_b128 v[146:149], v157
	ds_read_b128 v[158:161], v157 offset:1024
	ds_read_b128 v[162:165], v157 offset:2048
	ds_read_b128 v[166:169], v157 offset:3072
	ds_read_b128 v[170:173], v155 offset:32768
	ds_read_b128 v[174:177], v155 offset:33792
	ds_read_b128 v[178:181], v155 offset:34816
	ds_read_b128 v[182:185], v155 offset:35840
	ds_read_b128 v[186:189], v155 offset:36864
	ds_read_b128 v[190:193], v155 offset:37888
	ds_read_b128 v[194:197], v155 offset:38912
	ds_read_b128 v[198:201], v155 offset:39936
	s_add_i32 s98, 0, 0x1c000
	v_add_u32_e32 v246, s98, v152
	ds_read_b128 v[202:205], v246
	ds_read_b128 v[206:209], v246 offset:1024
	ds_read_b128 v[210:213], v246 offset:2048
	ds_read_b128 v[214:217], v246 offset:3072
	s_add_u32 s100, s64, 0x40000
	s_addc_u32 s101, s65, 0
	s_add_i32 s99, s79, s35
	s_mov_b32 m0, s99
	v_lshl_add_u64 v[240:241], s[100:101], 0, v[132:133]
	global_load_lds_dwordx4 v[240:241], off
	s_add_i32 m0, s99, 0x2000
	v_lshl_add_u64 v[240:241], s[100:101], 0, v[136:137]
	global_load_lds_dwordx4 v[240:241], off
	s_add_u32 s66, s66, 0x40000
	s_addc_u32 s67, s67, 0
	s_mov_b32 m0, s70
	v_lshl_add_u64 v[244:245], s[66:67], 0, v[130:131]
	global_load_lds_dwordx4 v[244:245], off
	s_mov_b32 m0, s71
	v_lshl_add_u64 v[244:245], s[66:67], 0, v[134:135]
	global_load_lds_dwordx4 v[244:245], off
	s_waitcnt vmcnt(8) lgkmcnt(0)
	s_barrier
	v_mfma_f32_16x16x32_bf16 v[124:127], v[146:149], v[170:173], v[124:127]
	v_mfma_f32_16x16x32_bf16 v[120:123], v[162:165], v[170:173], v[120:123]
	v_mfma_f32_16x16x32_bf16 v[108:111], v[146:149], v[178:181], v[108:111]
	v_mfma_f32_16x16x32_bf16 v[104:107], v[162:165], v[178:181], v[104:107]
	v_mfma_f32_16x16x32_bf16 v[92:95], v[146:149], v[186:189], v[92:95]
	v_mfma_f32_16x16x32_bf16 v[88:91], v[162:165], v[186:189], v[88:91]
	v_mfma_f32_16x16x32_bf16 v[76:79], v[146:149], v[194:197], v[76:79]
	v_mfma_f32_16x16x32_bf16 v[72:75], v[162:165], v[194:197], v[72:75]
	v_mfma_f32_16x16x32_bf16 v[124:127], v[158:161], v[174:177], v[124:127]
	v_mfma_f32_16x16x32_bf16 v[120:123], v[166:169], v[174:177], v[120:123]
	v_mfma_f32_16x16x32_bf16 v[108:111], v[158:161], v[182:185], v[108:111]
	v_mfma_f32_16x16x32_bf16 v[104:107], v[166:169], v[182:185], v[104:107]
	v_mfma_f32_16x16x32_bf16 v[92:95], v[158:161], v[190:193], v[92:95]
	v_mfma_f32_16x16x32_bf16 v[88:91], v[166:169], v[190:193], v[88:91]
	v_mfma_f32_16x16x32_bf16 v[76:79], v[158:161], v[198:201], v[76:79]
	v_mfma_f32_16x16x32_bf16 v[72:75], v[166:169], v[198:201], v[72:75]
	v_mfma_f32_16x16x32_bf16 v[116:119], v[202:205], v[170:173], v[116:119]
	v_mfma_f32_16x16x32_bf16 v[112:115], v[210:213], v[170:173], v[112:115]
	v_mfma_f32_16x16x32_bf16 v[100:103], v[202:205], v[178:181], v[100:103]
	v_mfma_f32_16x16x32_bf16 v[96:99], v[210:213], v[178:181], v[96:99]
	v_mfma_f32_16x16x32_bf16 v[84:87], v[202:205], v[186:189], v[84:87]
	v_mfma_f32_16x16x32_bf16 v[80:83], v[210:213], v[186:189], v[80:83]
	v_mfma_f32_16x16x32_bf16 v[68:71], v[202:205], v[194:197], v[68:71]
	v_mfma_f32_16x16x32_bf16 v[64:67], v[210:213], v[194:197], v[64:67]
	v_mfma_f32_16x16x32_bf16 v[116:119], v[206:209], v[174:177], v[116:119]
	v_mfma_f32_16x16x32_bf16 v[112:115], v[214:217], v[174:177], v[112:115]
	v_mfma_f32_16x16x32_bf16 v[100:103], v[206:209], v[182:185], v[100:103]
	v_mfma_f32_16x16x32_bf16 v[96:99], v[214:217], v[182:185], v[96:99]
	v_mfma_f32_16x16x32_bf16 v[84:87], v[206:209], v[190:193], v[84:87]
	v_mfma_f32_16x16x32_bf16 v[80:83], v[214:217], v[190:193], v[80:83]
	v_mfma_f32_16x16x32_bf16 v[68:71], v[206:209], v[198:201], v[68:71]
	v_mfma_f32_16x16x32_bf16 v[64:67], v[214:217], v[198:201], v[64:67]
	s_barrier
; #define PG8_STAGE(bufoff, gbase, voff) do { _Pragma("unroll") for (int _i = 0; _i < 2; ++_i) \
;         __builtin_amdgcn_global_load_lds((const unsigned*)((const char*)(gbase) + (voff)[_i]), (LAS unsigned*)(lds + (bufoff) + ldsw + _i * 8192), 16, 0, 0); } while (0)
; #define PG8_LDA(dst, b, h) do { _Pragma("unroll") for (int m = 0; m < 4; ++m) _Pragma("unroll") for (int k = 0; k < 2; ++k) dst[m][k] = *(const LAS bf16x8*)(lds + PG8_SA(b, h) + aoff + m * 2048 + k * 1024); } while (0)
; #define PG8_WAIT_V(n) asm volatile("s_waitcnt vmcnt(" #n ")" ::: "memory")
; #define PG8_WAIT_L(n) asm volatile("s_waitcnt lgkmcnt(" #n ")" ::: "memory")
; template <class Epi>
; __device__ __forceinline__ void gemm_phase(LAS unsigned char* lds, const Gemm g, const StaticOrder& S, const Epi& E) {
;     ...
;         for (int t = 0; t < nt; t += 2) {
;             const bool last = (t == nt - 2);
;             const char* a1 = cA + (size_t)(t + 1) * kstep;
;             const char* a2 = last ? nA : cA + (size_t)(t + 2) * kstep; const char* b2 = last ? nB : cB + (size_t)(t + 2) * kstep;
;             const char* a3 = a2 + kstep; const char* b3 = b2 + kstep;
;             PG8_LDB(B0, 0, 0); PG8_SCHED; PG8_LDA(At, 0, 0); PG8_STAGE(PG8_SA(1, 1), a1 + hstepA, voffA);
;             PG8_WAIT_L(8); PG8_BAR; PG8_WAIT_L(0); PG8_MMA(0, 0, At, B0); PG8_BAR; PG8_SCHED;
;             PG8_LDB(B1, 0, 1); PG8_STAGE(PG8_SB(0, 0), b2, voffB);
;             PG8_BAR; PG8_WAIT_L(0); PG8_MMA(0, 1, At, B1); PG8_BAR;
;             PG8_LDA(At, 0, 1); PG8_STAGE(PG8_SA(0, 0), a2, voffA);
;             PG8_BAR; PG8_WAIT_L(0); PG8_MMA(1, 0, At, B0); PG8_BAR; PG8_SCHED;
;             PG8_STAGE(PG8_SB(0, 1), b2 + hstepB, voffB);
;             PG8_WAIT_V(6); PG8_BAR; PG8_MMA(1, 1, At, B1); PG8_BAR;
;             PG8_LDB(B0, 1, 0); PG8_SCHED; PG8_LDA(At, 1, 0); PG8_STAGE(PG8_SA(0, 1), a2 + hstepA, voffA);
;             PG8_WAIT_L(8); PG8_BAR; PG8_WAIT_L(0); PG8_MMA(0, 0, At, B0); PG8_BAR; PG8_SCHED;
;             PG8_LDB(B1, 1, 1); PG8_STAGE(PG8_SB(1, 0), b3, voffB);
;             PG8_BAR; PG8_WAIT_L(0); PG8_MMA(0, 1, At, B1); PG8_BAR;
;             PG8_LDA(At, 1, 1); PG8_STAGE(PG8_SA(1, 0), a3, voffA);
;             PG8_BAR; PG8_WAIT_L(0); PG8_MMA(1, 0, At, B0); PG8_BAR; PG8_SCHED;
;             PG8_STAGE(PG8_SB(1, 1), b3 + hstepB, voffB);
;             PG8_WAIT_V(6); PG8_BAR; PG8_MMA(1, 1, At, B1); PG8_BAR;
	ds_read_b128 v[170:173], v155 offset:49152
	ds_read_b128 v[174:177], v155 offset:50176
	ds_read_b128 v[178:181], v155 offset:51200
	ds_read_b128 v[182:185], v155 offset:52224
	ds_read_b128 v[186:189], v155 offset:53248
	ds_read_b128 v[190:193], v155 offset:54272
	ds_read_b128 v[194:197], v155 offset:55296
	ds_read_b128 v[198:201], v155 offset:56320
	s_add_i32 s55, s55, s35
	s_mov_b32 m0, s55
	v_lshl_add_u64 v[218:219], v[218:219], 0, s[28:29]
	global_load_lds_dwordx4 v[218:219], off
	s_add_i32 m0, s55, 0x2000
	v_lshl_add_u64 v[218:219], v[220:221], 0, s[28:29]
	global_load_lds_dwordx4 v[218:219], off
	s_mov_b32 m0, s73
	v_lshl_add_u64 v[218:219], v[222:223], 0, s[28:29]
	global_load_lds_dwordx4 v[218:219], off
	s_mov_b32 m0, s74
	v_lshl_add_u64 v[218:219], v[224:225], 0, s[28:29]
	global_load_lds_dwordx4 v[218:219], off
	s_add_u32 s64, s64, 0x40080
	s_addc_u32 s65, s65, 0
	s_add_i32 s55, s98, s35
	s_mov_b32 m0, s55
	v_lshl_add_u64 v[240:241], s[64:65], 0, v[132:133]
	global_load_lds_dwordx4 v[240:241], off
	s_add_i32 m0, s55, 0x2000
	v_lshl_add_u64 v[240:241], s[64:65], 0, v[136:137]
	global_load_lds_dwordx4 v[240:241], off
	s_waitcnt vmcnt(8) lgkmcnt(0)
	s_barrier
	v_mfma_f32_16x16x32_bf16 v[60:63], v[146:149], v[170:173], v[60:63]
	v_mfma_f32_16x16x32_bf16 v[56:59], v[162:165], v[170:173], v[56:59]
	v_mfma_f32_16x16x32_bf16 v[44:47], v[146:149], v[178:181], v[44:47]
	v_mfma_f32_16x16x32_bf16 v[40:43], v[162:165], v[178:181], v[40:43]
	v_mfma_f32_16x16x32_bf16 v[28:31], v[146:149], v[186:189], v[28:31]
	v_mfma_f32_16x16x32_bf16 v[24:27], v[162:165], v[186:189], v[24:27]
	v_mfma_f32_16x16x32_bf16 v[12:15], v[146:149], v[194:197], v[12:15]
	v_mfma_f32_16x16x32_bf16 v[8:11], v[162:165], v[194:197], v[8:11]
	v_mfma_f32_16x16x32_bf16 v[60:63], v[158:161], v[174:177], v[60:63]
	v_mfma_f32_16x16x32_bf16 v[56:59], v[166:169], v[174:177], v[56:59]
	v_mfma_f32_16x16x32_bf16 v[44:47], v[158:161], v[182:185], v[44:47]
	v_mfma_f32_16x16x32_bf16 v[40:43], v[166:169], v[182:185], v[40:43]
	v_mfma_f32_16x16x32_bf16 v[28:31], v[158:161], v[190:193], v[28:31]
	v_mfma_f32_16x16x32_bf16 v[24:27], v[166:169], v[190:193], v[24:27]
	v_mfma_f32_16x16x32_bf16 v[12:15], v[158:161], v[198:201], v[12:15]
	v_mfma_f32_16x16x32_bf16 v[8:11], v[166:169], v[198:201], v[8:11]
	v_mfma_f32_16x16x32_bf16 v[52:55], v[202:205], v[170:173], v[52:55]
	v_mfma_f32_16x16x32_bf16 v[48:51], v[210:213], v[170:173], v[48:51]
	v_mfma_f32_16x16x32_bf16 v[36:39], v[202:205], v[178:181], v[36:39]
	v_mfma_f32_16x16x32_bf16 v[32:35], v[210:213], v[178:181], v[32:35]
	v_mfma_f32_16x16x32_bf16 v[20:23], v[202:205], v[186:189], v[20:23]
	v_mfma_f32_16x16x32_bf16 v[16:19], v[210:213], v[186:189], v[16:19]
	v_mfma_f32_16x16x32_bf16 v[4:7], v[202:205], v[194:197], v[4:7]
	v_mfma_f32_16x16x32_bf16 v[0:3], v[210:213], v[194:197], v[0:3]
	v_mfma_f32_16x16x32_bf16 v[52:55], v[206:209], v[174:177], v[52:55]
	v_mfma_f32_16x16x32_bf16 v[48:51], v[214:217], v[174:177], v[48:51]
	v_mfma_f32_16x16x32_bf16 v[36:39], v[206:209], v[182:185], v[36:39]
	v_mfma_f32_16x16x32_bf16 v[32:35], v[214:217], v[182:185], v[32:35]
	v_mfma_f32_16x16x32_bf16 v[20:23], v[206:209], v[190:193], v[20:23]
	v_mfma_f32_16x16x32_bf16 v[16:19], v[214:217], v[190:193], v[16:19]
	v_mfma_f32_16x16x32_bf16 v[4:7], v[206:209], v[198:201], v[4:7]
	v_mfma_f32_16x16x32_bf16 v[0:3], v[214:217], v[198:201], v[0:3]
	s_add_i32 s33, s33, 2
	s_add_u32 s62, s62, 0x100
	s_addc_u32 s63, s63, 0
	s_add_u32 s9, s9, 0x100
	s_addc_u32 s31, s31, 0
	s_cmp_gt_u32 s33, 13
	s_barrier
.LBB0_119:
	s_add_u32 s55, s62, 0xfffc0080
	s_addc_u32 s61, s63, -1
	s_cmp_eq_u32 s33, 12
	s_cselect_b32 s67, s57, s61
	s_cselect_b32 s66, s56, s55
	s_cselect_b32 s65, s59, s31
	s_cselect_b32 s64, s58, s9
	ds_read_b128 v[146:149], v154
	ds_read_b128 v[158:161], v154 offset:1024
	ds_read_b128 v[162:165], v154 offset:2048
	ds_read_b128 v[166:169], v154 offset:3072
	ds_read_b128 v[170:173], v155
	ds_read_b128 v[174:177], v155 offset:1024
	ds_read_b128 v[178:181], v155 offset:2048
	ds_read_b128 v[182:185], v155 offset:3072
	ds_read_b128 v[186:189], v155 offset:4096
	ds_read_b128 v[190:193], v155 offset:5120
	ds_read_b128 v[194:197], v155 offset:6144
	ds_read_b128 v[198:201], v155 offset:7168
	ds_read_b128 v[202:205], v156
	ds_read_b128 v[206:209], v156 offset:1024
	ds_read_b128 v[210:213], v156 offset:2048
	ds_read_b128 v[214:217], v156 offset:3072
	s_add_i32 m0, s68, 0xc000
	v_lshl_add_u64 v[242:243], s[62:63], 0, v[138:139]
	global_load_lds_dwordx4 v[242:243], off
	s_add_i32 m0, s68, 0xe000
	v_lshl_add_u64 v[242:243], s[62:63], 0, v[140:141]
	global_load_lds_dwordx4 v[242:243], off
	s_waitcnt vmcnt(8) lgkmcnt(0)
	s_barrier
; #define PG8_STAGE(bufoff, gbase, voff) do { _Pragma("unroll") for (int _i = 0; _i < 2; ++_i) \
;         __builtin_amdgcn_global_load_lds((const unsigned*)((const char*)(gbase) + (voff)[_i]), (LAS unsigned*)(lds + (bufoff) + ldsw + _i * 8192), 16, 0, 0); } while (0)
; #define PG8_LDA(dst, b, h) do { _Pragma("unroll") for (int m = 0; m < 4; ++m) _Pragma("unroll") for (int k = 0; k < 2; ++k) dst[m][k] = *(const LAS bf16x8*)(lds + PG8_SA(b, h) + aoff + m * 2048 + k * 1024); } while (0)
; #define PG8_LDB(dst, b, h) do { _Pragma("unroll") for (int n = 0; n < 2; ++n) _Pragma("unroll") for (int k = 0; k < 2; ++k) dst[n][k] = *(const LAS bf16x8*)(lds + PG8_SB(b, h) + boff + n * 2048 + k * 1024); } while (0)
; #define PG8_MMA(ai, bj, At, Bt) do { __builtin_amdgcn_s_setprio(1); _Pragma("unroll") for (int m = 0; m < 4; ++m) _Pragma("unroll") for (int n = 0; n < 2; ++n) _Pragma("unroll") for (int k = 0; k < 2; ++k) \
;         acc[ai][bj][m][n] = __builtin_amdgcn_mfma_f32_16x16x32_bf16(Bt[n][k], At[m][k], acc[ai][bj][m][n], 0, 0, 0); __builtin_amdgcn_s_setprio(0); } while (0)
; #define PG8_WAIT_V(n) asm volatile("s_waitcnt vmcnt(" #n ")" ::: "memory")
; #define PG8_WAIT_L(n) asm volatile("s_waitcnt lgkmcnt(" #n ")" ::: "memory")
; template <class Epi>
; __device__ __forceinline__ void gemm_phase(LAS unsigned char* lds, const Gemm g, const StaticOrder& S, const Epi& E) {
;     ...
;         for (int t = 0; t < nt; t += 2) {
;             const bool last = (t == nt - 2);
;             const char* a1 = cA + (size_t)(t + 1) * kstep;
;             const char* a2 = last ? nA : cA + (size_t)(t + 2) * kstep; const char* b2 = last ? nB : cB + (size_t)(t + 2) * kstep;
;             const char* a3 = a2 + kstep; const char* b3 = b2 + kstep;
;             PG8_LDB(B0, 0, 0); PG8_SCHED; PG8_LDA(At, 0, 0); PG8_STAGE(PG8_SA(1, 1), a1 + hstepA, voffA);
;             PG8_WAIT_L(8); PG8_BAR; PG8_WAIT_L(0); PG8_MMA(0, 0, At, B0); PG8_BAR; PG8_SCHED;
;             PG8_LDB(B1, 0, 1); PG8_STAGE(PG8_SB(0, 0), b2, voffB);
;             PG8_BAR; PG8_WAIT_L(0); PG8_MMA(0, 1, At, B1); PG8_BAR;
;             PG8_LDA(At, 0, 1); PG8_STAGE(PG8_SA(0, 0), a2, voffA);
;             PG8_BAR; PG8_WAIT_L(0); PG8_MMA(1, 0, At, B0); PG8_BAR; PG8_SCHED;
;             PG8_STAGE(PG8_SB(0, 1), b2 + hstepB, voffB);
;             PG8_WAIT_V(6); PG8_BAR; PG8_MMA(1, 1, At, B1); PG8_BAR;
	v_mfma_f32_16x16x32_bf16 v[124:127], v[146:149], v[170:173], v[124:127]
	v_mfma_f32_16x16x32_bf16 v[120:123], v[162:165], v[170:173], v[120:123]
	v_mfma_f32_16x16x32_bf16 v[108:111], v[146:149], v[178:181], v[108:111]
	v_mfma_f32_16x16x32_bf16 v[104:107], v[162:165], v[178:181], v[104:107]
	v_mfma_f32_16x16x32_bf16 v[92:95], v[146:149], v[186:189], v[92:95]
	v_mfma_f32_16x16x32_bf16 v[88:91], v[162:165], v[186:189], v[88:91]
	v_mfma_f32_16x16x32_bf16 v[76:79], v[146:149], v[194:197], v[76:79]
	v_mfma_f32_16x16x32_bf16 v[72:75], v[162:165], v[194:197], v[72:75]
	v_mfma_f32_16x16x32_bf16 v[124:127], v[158:161], v[174:177], v[124:127]
	v_mfma_f32_16x16x32_bf16 v[120:123], v[166:169], v[174:177], v[120:123]
	v_mfma_f32_16x16x32_bf16 v[108:111], v[158:161], v[182:185], v[108:111]
	v_mfma_f32_16x16x32_bf16 v[104:107], v[166:169], v[182:185], v[104:107]
	v_mfma_f32_16x16x32_bf16 v[92:95], v[158:161], v[190:193], v[92:95]
	v_mfma_f32_16x16x32_bf16 v[88:91], v[166:169], v[190:193], v[88:91]
	v_mfma_f32_16x16x32_bf16 v[76:79], v[158:161], v[198:201], v[76:79]
	v_mfma_f32_16x16x32_bf16 v[72:75], v[166:169], v[198:201], v[72:75]
	v_mfma_f32_16x16x32_bf16 v[116:119], v[202:205], v[170:173], v[116:119]
	v_mfma_f32_16x16x32_bf16 v[112:115], v[210:213], v[170:173], v[112:115]
	v_mfma_f32_16x16x32_bf16 v[100:103], v[202:205], v[178:181], v[100:103]
	v_mfma_f32_16x16x32_bf16 v[96:99], v[210:213], v[178:181], v[96:99]
	v_mfma_f32_16x16x32_bf16 v[84:87], v[202:205], v[186:189], v[84:87]
	v_mfma_f32_16x16x32_bf16 v[80:83], v[210:213], v[186:189], v[80:83]
	v_mfma_f32_16x16x32_bf16 v[68:71], v[202:205], v[194:197], v[68:71]
	v_mfma_f32_16x16x32_bf16 v[64:67], v[210:213], v[194:197], v[64:67]
	v_mfma_f32_16x16x32_bf16 v[116:119], v[206:209], v[174:177], v[116:119]
	v_mfma_f32_16x16x32_bf16 v[112:115], v[214:217], v[174:177], v[112:115]
	v_mfma_f32_16x16x32_bf16 v[100:103], v[206:209], v[182:185], v[100:103]
	v_mfma_f32_16x16x32_bf16 v[96:99], v[214:217], v[182:185], v[96:99]
	v_mfma_f32_16x16x32_bf16 v[84:87], v[206:209], v[190:193], v[84:87]
	v_mfma_f32_16x16x32_bf16 v[80:83], v[214:217], v[190:193], v[80:83]
	v_mfma_f32_16x16x32_bf16 v[68:71], v[206:209], v[198:201], v[68:71]
	v_mfma_f32_16x16x32_bf16 v[64:67], v[214:217], v[198:201], v[64:67]
	s_barrier
	ds_read_b128 v[170:173], v155 offset:16384
	ds_read_b128 v[174:177], v155 offset:17408
	ds_read_b128 v[178:181], v155 offset:18432
	ds_read_b128 v[182:185], v155 offset:19456
	ds_read_b128 v[186:189], v155 offset:20480
	ds_read_b128 v[190:193], v155 offset:21504
	ds_read_b128 v[194:197], v155 offset:22528
	ds_read_b128 v[198:201], v155 offset:23552
	s_add_i32 s55, s78, s35
	s_mov_b32 m0, s55
	v_lshl_add_u64 v[218:219], s[64:65], 0, v[132:133]
	global_load_lds_dwordx4 v[218:219], off
	s_add_i32 m0, s55, 0x2000
	v_lshl_add_u64 v[220:221], s[64:65], 0, v[136:137]
	global_load_lds_dwordx4 v[220:221], off
	s_mov_b32 m0, s68
	v_lshl_add_u64 v[222:223], s[66:67], 0, v[130:131]
	global_load_lds_dwordx4 v[222:223], off
	s_mov_b32 m0, s69
	v_lshl_add_u64 v[224:225], s[66:67], 0, v[134:135]
	global_load_lds_dwordx4 v[224:225], off
	s_waitcnt vmcnt(6) lgkmcnt(0)
	s_barrier
	v_mfma_f32_16x16x32_bf16 v[60:63], v[146:149], v[170:173], v[60:63]
	v_mfma_f32_16x16x32_bf16 v[56:59], v[162:165], v[170:173], v[56:59]
	v_mfma_f32_16x16x32_bf16 v[44:47], v[146:149], v[178:181], v[44:47]
	v_mfma_f32_16x16x32_bf16 v[40:43], v[162:165], v[178:181], v[40:43]
	v_mfma_f32_16x16x32_bf16 v[28:31], v[146:149], v[186:189], v[28:31]
	v_mfma_f32_16x16x32_bf16 v[24:27], v[162:165], v[186:189], v[24:27]
	v_mfma_f32_16x16x32_bf16 v[12:15], v[146:149], v[194:197], v[12:15]
	v_mfma_f32_16x16x32_bf16 v[8:11], v[162:165], v[194:197], v[8:11]
	v_mfma_f32_16x16x32_bf16 v[60:63], v[158:161], v[174:177], v[60:63]
	v_mfma_f32_16x16x32_bf16 v[56:59], v[166:169], v[174:177], v[56:59]
	v_mfma_f32_16x16x32_bf16 v[44:47], v[158:161], v[182:185], v[44:47]
	v_mfma_f32_16x16x32_bf16 v[40:43], v[166:169], v[182:185], v[40:43]
	v_mfma_f32_16x16x32_bf16 v[28:31], v[158:161], v[190:193], v[28:31]
	v_mfma_f32_16x16x32_bf16 v[24:27], v[166:169], v[190:193], v[24:27]
	v_mfma_f32_16x16x32_bf16 v[12:15], v[158:161], v[198:201], v[12:15]
	v_mfma_f32_16x16x32_bf16 v[8:11], v[166:169], v[198:201], v[8:11]
	v_mfma_f32_16x16x32_bf16 v[52:55], v[202:205], v[170:173], v[52:55]
	v_mfma_f32_16x16x32_bf16 v[48:51], v[210:213], v[170:173], v[48:51]
	v_mfma_f32_16x16x32_bf16 v[36:39], v[202:205], v[178:181], v[36:39]
	v_mfma_f32_16x16x32_bf16 v[32:35], v[210:213], v[178:181], v[32:35]
	v_mfma_f32_16x16x32_bf16 v[20:23], v[202:205], v[186:189], v[20:23]
	v_mfma_f32_16x16x32_bf16 v[16:19], v[210:213], v[186:189], v[16:19]
	v_mfma_f32_16x16x32_bf16 v[4:7], v[202:205], v[194:197], v[4:7]
	v_mfma_f32_16x16x32_bf16 v[0:3], v[210:213], v[194:197], v[0:3]
	v_mfma_f32_16x16x32_bf16 v[52:55], v[206:209], v[174:177], v[52:55]
	v_mfma_f32_16x16x32_bf16 v[48:51], v[214:217], v[174:177], v[48:51]
	v_mfma_f32_16x16x32_bf16 v[36:39], v[206:209], v[182:185], v[36:39]
	v_mfma_f32_16x16x32_bf16 v[32:35], v[214:217], v[182:185], v[32:35]
	v_mfma_f32_16x16x32_bf16 v[20:23], v[206:209], v[190:193], v[20:23]
	v_mfma_f32_16x16x32_bf16 v[16:19], v[214:217], v[190:193], v[16:19]
	v_mfma_f32_16x16x32_bf16 v[4:7], v[206:209], v[198:201], v[4:7]
	v_mfma_f32_16x16x32_bf16 v[0:3], v[214:217], v[198:201], v[0:3]
	s_barrier
; #define PG8_STAGE(bufoff, gbase, voff) do { _Pragma("unroll") for (int _i = 0; _i < 2; ++_i) \
;         __builtin_amdgcn_global_load_lds((const unsigned*)((const char*)(gbase) + (voff)[_i]), (LAS unsigned*)(lds + (bufoff) + ldsw + _i * 8192), 16, 0, 0); } while (0)
; #define PG8_LDA(dst, b, h) do { _Pragma("unroll") for (int m = 0; m < 4; ++m) _Pragma("unroll") for (int k = 0; k < 2; ++k) dst[m][k] = *(const LAS bf16x8*)(lds + PG8_SA(b, h) + aoff + m * 2048 + k * 1024); } while (0)
; #define PG8_LDB(dst, b, h) do { _Pragma("unroll") for (int n = 0; n < 2; ++n) _Pragma("unroll") for (int k = 0; k < 2; ++k) dst[n][k] = *(const LAS bf16x8*)(lds + PG8_SB(b, h) + boff + n * 2048 + k * 1024); } while (0)
; #define PG8_MMA(ai, bj, At, Bt) do { __builtin_amdgcn_s_setprio(1); _Pragma("unroll") for (int m = 0; m < 4; ++m) _Pragma("unroll") for (int n = 0; n < 2; ++n) _Pragma("unroll") for (int k = 0; k < 2; ++k) \
;         acc[ai][bj][m][n] = __builtin_amdgcn_mfma_f32_16x16x32_bf16(Bt[n][k], At[m][k], acc[ai][bj][m][n], 0, 0, 0); __builtin_amdgcn_s_setprio(0); } while (0)
; #define PG8_WAIT_V(n) asm volatile("s_waitcnt vmcnt(" #n ")" ::: "memory")
; #define PG8_WAIT_L(n) asm volatile("s_waitcnt lgkmcnt(" #n ")" ::: "memory")
; #define PG8_BAR __builtin_amdgcn_s_barrier()
; #define PG8_SCHED __builtin_amdgcn_sched_barrier(0)
; template <class Epi>
; __device__ __forceinline__ void gemm_phase(LAS unsigned char* lds, const Gemm g, const StaticOrder& S, const Epi& E) {
;     ...
;             PG8_LDB(B0, 1, 0); PG8_SCHED; PG8_LDA(At, 1, 0); PG8_STAGE(PG8_SA(0, 1), a2 + hstepA, voffA);
;             PG8_WAIT_L(8); PG8_BAR; PG8_WAIT_L(0); PG8_MMA(0, 0, At, B0); PG8_BAR; PG8_SCHED;
;             PG8_LDB(B1, 1, 1); PG8_STAGE(PG8_SB(1, 0), b3, voffB);
;             PG8_BAR; PG8_WAIT_L(0); PG8_MMA(0, 1, At, B1); PG8_BAR;
;             PG8_LDA(At, 1, 1); PG8_STAGE(PG8_SA(1, 0), a3, voffA);
;             PG8_BAR; PG8_WAIT_L(0); PG8_MMA(1, 0, At, B0); PG8_BAR; PG8_SCHED;
;             PG8_STAGE(PG8_SB(1, 1), b3 + hstepB, voffB);
;             PG8_WAIT_V(6); PG8_BAR; PG8_MMA(1, 1, At, B1); PG8_BAR;
	s_add_i32 s55, 0, 0x18000
	v_add_u32_e32 v157, s55, v152
	ds_read_b128 v[146:149], v157
	ds_read_b128 v[158:161], v157 offset:1024
	ds_read_b128 v[162:165], v157 offset:2048
	ds_read_b128 v[166:169], v157 offset:3072
	ds_read_b128 v[170:173], v155 offset:32768
	ds_read_b128 v[174:177], v155 offset:33792
	ds_read_b128 v[178:181], v155 offset:34816
	ds_read_b128 v[182:185], v155 offset:35840
	ds_read_b128 v[186:189], v155 offset:36864
	ds_read_b128 v[190:193], v155 offset:37888
	ds_read_b128 v[194:197], v155 offset:38912
	ds_read_b128 v[198:201], v155 offset:39936
	s_add_i32 s98, 0, 0x1c000
	v_add_u32_e32 v246, s98, v152
	ds_read_b128 v[202:205], v246
	ds_read_b128 v[206:209], v246 offset:1024
	ds_read_b128 v[210:213], v246 offset:2048
	ds_read_b128 v[214:217], v246 offset:3072
	s_add_u32 s100, s64, 0x40000
	s_addc_u32 s101, s65, 0
	s_add_i32 s99, s79, s35
	s_mov_b32 m0, s99
	v_lshl_add_u64 v[240:241], s[100:101], 0, v[132:133]
	global_load_lds_dwordx4 v[240:241], off
	s_add_i32 m0, s99, 0x2000
	v_lshl_add_u64 v[240:241], s[100:101], 0, v[136:137]
	global_load_lds_dwordx4 v[240:241], off
	s_add_u32 s66, s66, 0x40000
	s_addc_u32 s67, s67, 0
	s_mov_b32 m0, s70
	v_lshl_add_u64 v[244:245], s[66:67], 0, v[130:131]
	global_load_lds_dwordx4 v[244:245], off
	s_mov_b32 m0, s71
	v_lshl_add_u64 v[244:245], s[66:67], 0, v[134:135]
	global_load_lds_dwordx4 v[244:245], off
	s_waitcnt vmcnt(8) lgkmcnt(0)
	s_barrier
	v_mfma_f32_16x16x32_bf16 v[124:127], v[146:149], v[170:173], v[124:127]
	v_mfma_f32_16x16x32_bf16 v[120:123], v[162:165], v[170:173], v[120:123]
	v_mfma_f32_16x16x32_bf16 v[108:111], v[146:149], v[178:181], v[108:111]
	v_mfma_f32_16x16x32_bf16 v[104:107], v[162:165], v[178:181], v[104:107]
	v_mfma_f32_16x16x32_bf16 v[92:95], v[146:149], v[186:189], v[92:95]
	v_mfma_f32_16x16x32_bf16 v[88:91], v[162:165], v[186:189], v[88:91]
	v_mfma_f32_16x16x32_bf16 v[76:79], v[146:149], v[194:197], v[76:79]
	v_mfma_f32_16x16x32_bf16 v[72:75], v[162:165], v[194:197], v[72:75]
	v_mfma_f32_16x16x32_bf16 v[124:127], v[158:161], v[174:177], v[124:127]
	v_mfma_f32_16x16x32_bf16 v[120:123], v[166:169], v[174:177], v[120:123]
	v_mfma_f32_16x16x32_bf16 v[108:111], v[158:161], v[182:185], v[108:111]
	v_mfma_f32_16x16x32_bf16 v[104:107], v[166:169], v[182:185], v[104:107]
	v_mfma_f32_16x16x32_bf16 v[92:95], v[158:161], v[190:193], v[92:95]
	v_mfma_f32_16x16x32_bf16 v[88:91], v[166:169], v[190:193], v[88:91]
	v_mfma_f32_16x16x32_bf16 v[76:79], v[158:161], v[198:201], v[76:79]
	v_mfma_f32_16x16x32_bf16 v[72:75], v[166:169], v[198:201], v[72:75]
	v_mfma_f32_16x16x32_bf16 v[116:119], v[202:205], v[170:173], v[116:119]
	v_mfma_f32_16x16x32_bf16 v[112:115], v[210:213], v[170:173], v[112:115]
	v_mfma_f32_16x16x32_bf16 v[100:103], v[202:205], v[178:181], v[100:103]
	v_mfma_f32_16x16x32_bf16 v[96:99], v[210:213], v[178:181], v[96:99]
	v_mfma_f32_16x16x32_bf16 v[84:87], v[202:205], v[186:189], v[84:87]
	v_mfma_f32_16x16x32_bf16 v[80:83], v[210:213], v[186:189], v[80:83]
	v_mfma_f32_16x16x32_bf16 v[68:71], v[202:205], v[194:197], v[68:71]
	v_mfma_f32_16x16x32_bf16 v[64:67], v[210:213], v[194:197], v[64:67]
	v_mfma_f32_16x16x32_bf16 v[116:119], v[206:209], v[174:177], v[116:119]
	v_mfma_f32_16x16x32_bf16 v[112:115], v[214:217], v[174:177], v[112:115]
	v_mfma_f32_16x16x32_bf16 v[100:103], v[206:209], v[182:185], v[100:103]
	v_mfma_f32_16x16x32_bf16 v[96:99], v[214:217], v[182:185], v[96:99]
	v_mfma_f32_16x16x32_bf16 v[84:87], v[206:209], v[190:193], v[84:87]
	v_mfma_f32_16x16x32_bf16 v[80:83], v[214:217], v[190:193], v[80:83]
	v_mfma_f32_16x16x32_bf16 v[68:71], v[206:209], v[198:201], v[68:71]
	v_mfma_f32_16x16x32_bf16 v[64:67], v[214:217], v[198:201], v[64:67]
	s_barrier
	ds_read_b128 v[170:173], v155 offset:49152
	ds_read_b128 v[174:177], v155 offset:50176
	ds_read_b128 v[178:181], v155 offset:51200
	ds_read_b128 v[182:185], v155 offset:52224
	ds_read_b128 v[186:189], v155 offset:53248
	ds_read_b128 v[190:193], v155 offset:54272
	ds_read_b128 v[194:197], v155 offset:55296
	ds_read_b128 v[198:201], v155 offset:56320
	s_add_i32 s55, s55, s35
	s_mov_b32 m0, s55
	v_lshl_add_u64 v[218:219], v[218:219], 0, s[28:29]
	global_load_lds_dwordx4 v[218:219], off
	s_add_i32 m0, s55, 0x2000
	v_lshl_add_u64 v[218:219], v[220:221], 0, s[28:29]
	global_load_lds_dwordx4 v[218:219], off
	s_mov_b32 m0, s73
	v_lshl_add_u64 v[218:219], v[222:223], 0, s[28:29]
	global_load_lds_dwordx4 v[218:219], off
	s_mov_b32 m0, s74
	v_lshl_add_u64 v[218:219], v[224:225], 0, s[28:29]
	global_load_lds_dwordx4 v[218:219], off
	s_add_u32 s64, s64, 0x40080
	s_addc_u32 s65, s65, 0
	s_add_i32 s55, s98, s35
	s_mov_b32 m0, s55
	v_lshl_add_u64 v[240:241], s[64:65], 0, v[132:133]
	global_load_lds_dwordx4 v[240:241], off
	s_add_i32 m0, s55, 0x2000
	v_lshl_add_u64 v[240:241], s[64:65], 0, v[136:137]
	global_load_lds_dwordx4 v[240:241], off
	s_waitcnt vmcnt(8) lgkmcnt(0)
	s_barrier
; __device__ __forceinline__ unsigned pk2(float lo, float hi) { unsigned r; asm("v_cvt_pk_bf16_f32 %0, %1, %2" : "=v"(r) : "v"(lo), "v"(hi)); return r; }
; __device__ __forceinline__ float gelu_t(float x) { return x * __builtin_amdgcn_rcpf(1.f + __expf(-1.5957691216057308f * (x + 0.044715f * x * x * x))); }
; #define PG8_MMA(ai, bj, At, Bt) do { __builtin_amdgcn_s_setprio(1); _Pragma("unroll") for (int m = 0; m < 4; ++m) _Pragma("unroll") for (int n = 0; n < 2; ++n) _Pragma("unroll") for (int k = 0; k < 2; ++k) \
;         acc[ai][bj][m][n] = __builtin_amdgcn_mfma_f32_16x16x32_bf16(Bt[n][k], At[m][k], acc[ai][bj][m][n], 0, 0, 0); __builtin_amdgcn_s_setprio(0); } while (0)
; #define PG8_WAIT_V(n) asm volatile("s_waitcnt vmcnt(" #n ")" ::: "memory")
; #define PG8_BAR __builtin_amdgcn_s_barrier()
;     __device__ __forceinline__ void operator()(const f32x4 (&acc)[2][2][4][2], const Unit& u, int wr, int wc, int fr, int fq) const {
;     ...
;                 for (int bj = 0; bj < 2; ++bj) { f32x4 v0 = acc[ai][bj][m][0], v1 = acc[ai][bj][m][1];
;                     if (col0 + bj * HALF >= gelu_from) { v0 = (f32x4){gelu_t(v0.x), gelu_t(v0.y), gelu_t(v0.z), gelu_t(v0.w)}; v1 = (f32x4){gelu_t(v1.x), gelu_t(v1.y), gelu_t(v1.z), gelu_t(v1.w)}; }
;                     u32x4 w; w.x = pk2(v0[0], v0[1]); w.y = pk2(v0[2], v0[3]); w.z = pk2(v1[0], v1[1]); w.w = pk2(v1[2], v1[3]);
;                     *(u32x4*)(rowp + bj * HALF) = w;
; template <class Epi>
; __device__ __forceinline__ void gemm_phase(LAS unsigned char* lds, const Gemm g, const StaticOrder& S, const Epi& E) {
;     ...
;             PG8_WAIT_V(6); PG8_BAR; PG8_MMA(1, 1, At, B1); PG8_BAR;
;         }
	v_mfma_f32_16x16x32_bf16 v[60:63], v[146:149], v[170:173], v[60:63]
	v_mfma_f32_16x16x32_bf16 v[56:59], v[162:165], v[170:173], v[56:59]
	v_mfma_f32_16x16x32_bf16 v[44:47], v[146:149], v[178:181], v[44:47]
	v_mfma_f32_16x16x32_bf16 v[40:43], v[162:165], v[178:181], v[40:43]
	v_mfma_f32_16x16x32_bf16 v[28:31], v[146:149], v[186:189], v[28:31]
	v_mfma_f32_16x16x32_bf16 v[24:27], v[162:165], v[186:189], v[24:27]
	v_mfma_f32_16x16x32_bf16 v[12:15], v[146:149], v[194:197], v[12:15]
	v_mfma_f32_16x16x32_bf16 v[8:11], v[162:165], v[194:197], v[8:11]
	v_mfma_f32_16x16x32_bf16 v[60:63], v[158:161], v[174:177], v[60:63]
	v_mfma_f32_16x16x32_bf16 v[56:59], v[166:169], v[174:177], v[56:59]
	v_mfma_f32_16x16x32_bf16 v[44:47], v[158:161], v[182:185], v[44:47]
	v_mfma_f32_16x16x32_bf16 v[40:43], v[166:169], v[182:185], v[40:43]
	v_mfma_f32_16x16x32_bf16 v[28:31], v[158:161], v[190:193], v[28:31]
	v_mfma_f32_16x16x32_bf16 v[24:27], v[166:169], v[190:193], v[24:27]
	v_mfma_f32_16x16x32_bf16 v[12:15], v[158:161], v[198:201], v[12:15]
	v_mfma_f32_16x16x32_bf16 v[8:11], v[166:169], v[198:201], v[8:11]
	v_mfma_f32_16x16x32_bf16 v[52:55], v[202:205], v[170:173], v[52:55]
	v_mfma_f32_16x16x32_bf16 v[48:51], v[210:213], v[170:173], v[48:51]
	v_mfma_f32_16x16x32_bf16 v[36:39], v[202:205], v[178:181], v[36:39]
	v_mfma_f32_16x16x32_bf16 v[32:35], v[210:213], v[178:181], v[32:35]
	v_mfma_f32_16x16x32_bf16 v[20:23], v[202:205], v[186:189], v[20:23]
	v_mfma_f32_16x16x32_bf16 v[16:19], v[210:213], v[186:189], v[16:19]
	v_mfma_f32_16x16x32_bf16 v[4:7], v[202:205], v[194:197], v[4:7]
	v_mfma_f32_16x16x32_bf16 v[0:3], v[210:213], v[194:197], v[0:3]
	v_mfma_f32_16x16x32_bf16 v[52:55], v[206:209], v[174:177], v[52:55]
	v_mfma_f32_16x16x32_bf16 v[48:51], v[214:217], v[174:177], v[48:51]
	v_mfma_f32_16x16x32_bf16 v[36:39], v[206:209], v[182:185], v[36:39]
	v_mfma_f32_16x16x32_bf16 v[32:35], v[214:217], v[182:185], v[32:35]
	v_mfma_f32_16x16x32_bf16 v[20:23], v[206:209], v[190:193], v[20:23]
	v_mfma_f32_16x16x32_bf16 v[16:19], v[214:217], v[190:193], v[16:19]
	v_mfma_f32_16x16x32_bf16 v[4:7], v[206:209], v[198:201], v[4:7]
	v_mfma_f32_16x16x32_bf16 v[0:3], v[214:217], v[198:201], v[0:3]
	s_add_i32 s33, s33, 2
	s_add_u32 s62, s62, 0x100
	s_addc_u32 s63, s63, 0
	s_add_u32 s9, s9, 0x100
	s_addc_u32 s31, s31, 0
	s_cmp_gt_u32 s33, 13
	s_barrier
	s_cbranch_scc0 .LBB0_119
	v_lshl_or_b32 v146, s60, 8, v153
	v_cmp_lt_i32_e32 vcc, s80, v146
	s_and_saveexec_b64 s[60:61], vcc
	s_cbranch_execz .LBB0_122
	v_mul_f32_e32 v148, 0x3d372713, v125
	v_mul_f32_e32 v148, v125, v148
	v_fma_f32 v148, v125, v148, v125
	v_mul_f32_e32 v147, 0x3d372713, v124
	v_mul_f32_e32 v148, 0xbfcc422a, v148
	v_mul_f32_e32 v147, v124, v147
	v_mul_f32_e32 v148, 0x3fb8aa3b, v148
	v_fma_f32 v147, v124, v147, v124
	v_exp_f32_e32 v149, v148
	v_mul_f32_e32 v148, 0x3d372713, v126
	v_mul_f32_e32 v147, 0xbfcc422a, v147
	v_mul_f32_e32 v148, v126, v148
	v_mul_f32_e32 v147, 0x3fb8aa3b, v147
	v_fma_f32 v148, v126, v148, v126
	v_exp_f32_e32 v147, v147
	v_mul_f32_e32 v148, 0xbfcc422a, v148
	v_mul_f32_e32 v148, 0x3fb8aa3b, v148
	v_exp_f32_e32 v157, v148
	v_add_f32_e32 v147, 1.0, v147
	v_rcp_f32_e32 v148, v147
	v_add_f32_e32 v147, 1.0, v149
	v_rcp_f32_e32 v149, v147
	v_add_f32_e32 v147, 1.0, v157
	v_mul_f32_e32 v157, 0x3d372713, v127
	v_mul_f32_e32 v157, v127, v157
	v_mul_f32_e32 v158, 0x3d372713, v120
	v_fma_f32 v157, v127, v157, v127
	v_mul_f32_e32 v158, v120, v158
	v_mul_f32_e32 v157, 0xbfcc422a, v157
	v_fma_f32 v158, v120, v158, v120
	v_mul_f32_e32 v157, 0x3fb8aa3b, v157
	v_mul_f32_e32 v158, 0xbfcc422a, v158
	v_exp_f32_e32 v157, v157
	v_mul_f32_e32 v158, 0x3fb8aa3b, v158
	v_exp_f32_e32 v160, v158
	v_rcp_f32_e32 v158, v147
	v_add_f32_e32 v147, 1.0, v157
	v_rcp_f32_e32 v159, v147
	v_add_f32_e32 v147, 1.0, v160
	v_mul_f32_e32 v157, 0x3d372713, v122
	v_rcp_f32_e32 v160, v147
	v_mul_f32_e32 v147, 0x3d372713, v121
	v_mul_f32_e32 v157, v122, v157
	v_mul_f32_e32 v161, 0x3d372713, v123
	v_mul_f32_e32 v147, v121, v147
	v_fma_f32 v157, v122, v157, v122
	v_mul_f32_e32 v161, v123, v161
	v_fma_f32 v147, v121, v147, v121
	v_mul_f32_e32 v157, 0xbfcc422a, v157
	v_fma_f32 v161, v123, v161, v123
	v_mul_f32_e32 v147, 0xbfcc422a, v147
	v_mul_f32_e32 v157, 0x3fb8aa3b, v157
	v_mul_f32_e32 v161, 0xbfcc422a, v161
	v_mul_f32_e32 v147, 0x3fb8aa3b, v147
	v_exp_f32_e32 v157, v157
	v_mul_f32_e32 v161, 0x3fb8aa3b, v161
	v_exp_f32_e32 v147, v147
	v_exp_f32_e32 v161, v161
	v_add_f32_e32 v157, 1.0, v157
	v_rcp_f32_e32 v162, v157
	v_add_f32_e32 v147, 1.0, v147
	v_add_f32_e32 v157, 1.0, v161
	v_rcp_f32_e32 v163, v157
	v_rcp_f32_e32 v161, v147
	v_pk_mul_f32 v[126:127], v[126:127], v[158:159]
	v_pk_mul_f32 v[124:125], v[124:125], v[148:149]
	v_pk_mul_f32 v[122:123], v[122:123], v[162:163]
	v_pk_mul_f32 v[120:121], v[120:121], v[160:161]

; #define PG8_STAGE(bufoff, gbase, voff) do { _Pragma("unroll") for (int _i = 0; _i < 2; ++_i) \
;         __builtin_amdgcn_global_load_lds((const unsigned*)((const char*)(gbase) + (voff)[_i]), (LAS unsigned*)(lds + (bufoff) + ldsw + _i * 8192), 16, 0, 0); } while (0)
; #define PG8_LDA(dst, b, h) do { _Pragma("unroll") for (int m = 0; m < 4; ++m) _Pragma("unroll") for (int k = 0; k < 2; ++k) dst[m][k] = *(const LAS bf16x8*)(lds + PG8_SA(b, h) + aoff + m * 2048 + k * 1024); } while (0)
; #define PG8_LDB(dst, b, h) do { _Pragma("unroll") for (int n = 0; n < 2; ++n) _Pragma("unroll") for (int k = 0; k < 2; ++k) dst[n][k] = *(const LAS bf16x8*)(lds + PG8_SB(b, h) + boff + n * 2048 + k * 1024); } while (0)
; #define PG8_WAIT_V(n) asm volatile("s_waitcnt vmcnt(" #n ")" ::: "memory")
; #define PG8_WAIT_L(n) asm volatile("s_waitcnt lgkmcnt(" #n ")" ::: "memory")
; #define PG8_BAR __builtin_amdgcn_s_barrier()
; #define PG8_SCHED __builtin_amdgcn_sched_barrier(0)
; template <class Epi>
; __device__ __forceinline__ void gemm_phase(LAS unsigned char* lds, const Gemm g, const StaticOrder& S, const Epi& E) {
;     ...
;         const bool has_next = S.next(ui + 1, nxt);
;         const char* nA = has_next ? (const char*)g.A + (size_t)nxt.pm * tstepA + (size_t)nxt.kt0 * kstep : cA; const char* nB = has_next ? (const char*)g.Bt + (size_t)nxt.pn * tstepB + (size_t)nxt.kt0 * kstep : cB;
;         const int nt = cur.nkt;
;         for (int t = 0; t < nt; t += 2) {
;             const bool last = (t == nt - 2);
;             const char* a1 = cA + (size_t)(t + 1) * kstep;
;             const char* a2 = last ? nA : cA + (size_t)(t + 2) * kstep; const char* b2 = last ? nB : cB + (size_t)(t + 2) * kstep;
;             const char* a3 = a2 + kstep; const char* b3 = b2 + kstep;
;             PG8_LDB(B0, 0, 0); PG8_SCHED; PG8_LDA(At, 0, 0); PG8_STAGE(PG8_SA(1, 1), a1 + hstepA, voffA);
;             PG8_WAIT_L(8); PG8_BAR; PG8_WAIT_L(0); PG8_MMA(0, 0, At, B0); PG8_BAR; PG8_SCHED;
;             PG8_LDB(B1, 0, 1); PG8_STAGE(PG8_SB(0, 0), b2, voffB);
;             PG8_BAR; PG8_WAIT_L(0); PG8_MMA(0, 1, At, B1); PG8_BAR;
;             PG8_LDA(At, 0, 1); PG8_STAGE(PG8_SA(0, 0), a2, voffA);
;             PG8_BAR; PG8_WAIT_L(0); PG8_MMA(1, 0, At, B0); PG8_BAR; PG8_SCHED;
;             PG8_STAGE(PG8_SB(0, 1), b2 + hstepB, voffB);
;             PG8_WAIT_V(6); PG8_BAR; PG8_MMA(1, 1, At, B1); PG8_BAR;
.LBB0_455:
	s_add_i32 s21, s84, -2
	s_add_u32 s64, s64, 0x40080
	s_addc_u32 s65, s65, 0
	s_add_u32 s31, s66, 0x100
	s_addc_u32 s57, s67, 0
	s_mov_b32 s59, 0
	s_add_i32 s85, s59, 2
	s_add_u32 s66, s64, 0xfffc0080
	s_addc_u32 s67, s65, -1
	s_cmp_eq_u32 s21, s59
	s_cselect_b32 s69, s63, s67
	s_cselect_b32 s68, s62, s66
	s_cselect_b32 s67, s1, s57
	s_cselect_b32 s66, s0, s31
	ds_read_b128 v[144:147], v158
	ds_read_b128 v[148:151], v158 offset:1024
	ds_read_b128 v[162:165], v158 offset:2048
	ds_read_b128 v[166:169], v158 offset:3072
	ds_read_b128 v[170:173], v159
	ds_read_b128 v[174:177], v159 offset:1024
	ds_read_b128 v[178:181], v159 offset:2048
	ds_read_b128 v[182:185], v159 offset:3072
	ds_read_b128 v[186:189], v159 offset:4096
	ds_read_b128 v[190:193], v159 offset:5120
	ds_read_b128 v[194:197], v159 offset:6144
	ds_read_b128 v[198:201], v159 offset:7168
	ds_read_b128 v[202:205], v160
	ds_read_b128 v[206:209], v160 offset:1024
	ds_read_b128 v[210:213], v160 offset:2048
	ds_read_b128 v[214:217], v160 offset:3072
	s_add_i32 m0, s35, 0xc000
	v_lshl_add_u64 v[152:153], s[64:65], 0, v[138:139]
	global_load_lds_dwordx4 v[152:153], off
	s_add_i32 m0, s35, 0xe000
	v_lshl_add_u64 v[152:153], s[64:65], 0, v[140:141]
	global_load_lds_dwordx4 v[152:153], off
	s_waitcnt vmcnt(8) lgkmcnt(0)
	s_barrier
	v_mfma_f32_16x16x32_bf16 v[124:127], v[144:147], v[170:173], 0
	v_mfma_f32_16x16x32_bf16 v[120:123], v[162:165], v[170:173], 0
	v_mfma_f32_16x16x32_bf16 v[116:119], v[144:147], v[178:181], 0
	v_mfma_f32_16x16x32_bf16 v[108:111], v[162:165], v[178:181], 0
	v_mfma_f32_16x16x32_bf16 v[100:103], v[144:147], v[186:189], 0
	v_mfma_f32_16x16x32_bf16 v[92:95], v[162:165], v[186:189], 0
	v_mfma_f32_16x16x32_bf16 v[84:87], v[144:147], v[194:197], 0
	v_mfma_f32_16x16x32_bf16 v[76:79], v[162:165], v[194:197], 0
	v_mfma_f32_16x16x32_bf16 v[124:127], v[148:151], v[174:177], v[124:127]
	v_mfma_f32_16x16x32_bf16 v[120:123], v[166:169], v[174:177], v[120:123]
	v_mfma_f32_16x16x32_bf16 v[116:119], v[148:151], v[182:185], v[116:119]
	v_mfma_f32_16x16x32_bf16 v[108:111], v[166:169], v[182:185], v[108:111]
	v_mfma_f32_16x16x32_bf16 v[100:103], v[148:151], v[190:193], v[100:103]
	v_mfma_f32_16x16x32_bf16 v[92:95], v[166:169], v[190:193], v[92:95]
	v_mfma_f32_16x16x32_bf16 v[84:87], v[148:151], v[198:201], v[84:87]
	v_mfma_f32_16x16x32_bf16 v[76:79], v[166:169], v[198:201], v[76:79]
	v_mfma_f32_16x16x32_bf16 v[112:115], v[202:205], v[170:173], 0
	v_mfma_f32_16x16x32_bf16 v[104:107], v[210:213], v[170:173], 0
	v_mfma_f32_16x16x32_bf16 v[96:99], v[202:205], v[178:181], 0
	v_mfma_f32_16x16x32_bf16 v[88:91], v[210:213], v[178:181], 0
	v_mfma_f32_16x16x32_bf16 v[80:83], v[202:205], v[186:189], 0
	v_mfma_f32_16x16x32_bf16 v[72:75], v[210:213], v[186:189], 0
	v_mfma_f32_16x16x32_bf16 v[68:71], v[202:205], v[194:197], 0
	v_mfma_f32_16x16x32_bf16 v[64:67], v[210:213], v[194:197], 0
	v_mfma_f32_16x16x32_bf16 v[112:115], v[206:209], v[174:177], v[112:115]
	v_mfma_f32_16x16x32_bf16 v[104:107], v[214:217], v[174:177], v[104:107]
	v_mfma_f32_16x16x32_bf16 v[96:99], v[206:209], v[182:185], v[96:99]
	v_mfma_f32_16x16x32_bf16 v[88:91], v[214:217], v[182:185], v[88:91]
	v_mfma_f32_16x16x32_bf16 v[80:83], v[206:209], v[190:193], v[80:83]
	v_mfma_f32_16x16x32_bf16 v[72:75], v[214:217], v[190:193], v[72:75]
	v_mfma_f32_16x16x32_bf16 v[68:71], v[206:209], v[198:201], v[68:71]
	v_mfma_f32_16x16x32_bf16 v[64:67], v[214:217], v[198:201], v[64:67]
	s_barrier
	ds_read_b128 v[170:173], v159 offset:16384
	ds_read_b128 v[174:177], v159 offset:17408
	ds_read_b128 v[178:181], v159 offset:18432
	ds_read_b128 v[182:185], v159 offset:19456
	ds_read_b128 v[186:189], v159 offset:20480
	ds_read_b128 v[190:193], v159 offset:21504
	ds_read_b128 v[194:197], v159 offset:22528
	ds_read_b128 v[198:201], v159 offset:23552
	s_add_i32 s59, s78, s33
	s_mov_b32 m0, s59
	v_lshl_add_u64 v[152:153], s[66:67], 0, v[132:133]
	global_load_lds_dwordx4 v[152:153], off
	s_add_i32 m0, s59, 0x2000
	v_lshl_add_u64 v[218:219], s[66:67], 0, v[136:137]
	global_load_lds_dwordx4 v[218:219], off
	s_mov_b32 m0, s35
	v_lshl_add_u64 v[220:221], s[68:69], 0, v[130:131]
	global_load_lds_dwordx4 v[220:221], off
	s_mov_b32 m0, s70
	v_lshl_add_u64 v[222:223], s[68:69], 0, v[134:135]
	global_load_lds_dwordx4 v[222:223], off
	s_waitcnt vmcnt(6) lgkmcnt(0)
	s_barrier
	v_mfma_f32_16x16x32_bf16 v[60:63], v[144:147], v[170:173], 0
	v_mfma_f32_16x16x32_bf16 v[56:59], v[162:165], v[170:173], 0
	v_mfma_f32_16x16x32_bf16 v[52:55], v[144:147], v[178:181], 0
	v_mfma_f32_16x16x32_bf16 v[44:47], v[162:165], v[178:181], 0
	v_mfma_f32_16x16x32_bf16 v[36:39], v[144:147], v[186:189], 0
	v_mfma_f32_16x16x32_bf16 v[28:31], v[162:165], v[186:189], 0
	v_mfma_f32_16x16x32_bf16 v[20:23], v[144:147], v[194:197], 0
	v_mfma_f32_16x16x32_bf16 v[12:15], v[162:165], v[194:197], 0
	v_mfma_f32_16x16x32_bf16 v[60:63], v[148:151], v[174:177], v[60:63]
	v_mfma_f32_16x16x32_bf16 v[56:59], v[166:169], v[174:177], v[56:59]
	v_mfma_f32_16x16x32_bf16 v[52:55], v[148:151], v[182:185], v[52:55]
	v_mfma_f32_16x16x32_bf16 v[44:47], v[166:169], v[182:185], v[44:47]
	v_mfma_f32_16x16x32_bf16 v[36:39], v[148:151], v[190:193], v[36:39]
	v_mfma_f32_16x16x32_bf16 v[28:31], v[166:169], v[190:193], v[28:31]
	v_mfma_f32_16x16x32_bf16 v[20:23], v[148:151], v[198:201], v[20:23]
	v_mfma_f32_16x16x32_bf16 v[12:15], v[166:169], v[198:201], v[12:15]
	v_mfma_f32_16x16x32_bf16 v[48:51], v[202:205], v[170:173], 0
	v_mfma_f32_16x16x32_bf16 v[40:43], v[210:213], v[170:173], 0
	v_mfma_f32_16x16x32_bf16 v[32:35], v[202:205], v[178:181], 0
	v_mfma_f32_16x16x32_bf16 v[24:27], v[210:213], v[178:181], 0
	v_mfma_f32_16x16x32_bf16 v[16:19], v[202:205], v[186:189], 0
	v_mfma_f32_16x16x32_bf16 v[8:11], v[210:213], v[186:189], 0
	v_mfma_f32_16x16x32_bf16 v[4:7], v[202:205], v[194:197], 0
	v_mfma_f32_16x16x32_bf16 v[0:3], v[210:213], v[194:197], 0
	v_mfma_f32_16x16x32_bf16 v[48:51], v[206:209], v[174:177], v[48:51]
	v_mfma_f32_16x16x32_bf16 v[40:43], v[214:217], v[174:177], v[40:43]
	v_mfma_f32_16x16x32_bf16 v[32:35], v[206:209], v[182:185], v[32:35]
	v_mfma_f32_16x16x32_bf16 v[24:27], v[214:217], v[182:185], v[24:27]
	v_mfma_f32_16x16x32_bf16 v[16:19], v[206:209], v[190:193], v[16:19]
	v_mfma_f32_16x16x32_bf16 v[8:11], v[214:217], v[190:193], v[8:11]
	v_mfma_f32_16x16x32_bf16 v[4:7], v[206:209], v[198:201], v[4:7]
	v_mfma_f32_16x16x32_bf16 v[0:3], v[214:217], v[198:201], v[0:3]
	s_barrier
; #define PG8_STAGE(bufoff, gbase, voff) do { _Pragma("unroll") for (int _i = 0; _i < 2; ++_i) \
;         __builtin_amdgcn_global_load_lds((const unsigned*)((const char*)(gbase) + (voff)[_i]), (LAS unsigned*)(lds + (bufoff) + ldsw + _i * 8192), 16, 0, 0); } while (0)
; #define PG8_LDA(dst, b, h) do { _Pragma("unroll") for (int m = 0; m < 4; ++m) _Pragma("unroll") for (int k = 0; k < 2; ++k) dst[m][k] = *(const LAS bf16x8*)(lds + PG8_SA(b, h) + aoff + m * 2048 + k * 1024); } while (0)
; #define PG8_LDB(dst, b, h) do { _Pragma("unroll") for (int n = 0; n < 2; ++n) _Pragma("unroll") for (int k = 0; k < 2; ++k) dst[n][k] = *(const LAS bf16x8*)(lds + PG8_SB(b, h) + boff + n * 2048 + k * 1024); } while (0)
; #define PG8_MMA(ai, bj, At, Bt) do { __builtin_amdgcn_s_setprio(1); _Pragma("unroll") for (int m = 0; m < 4; ++m) _Pragma("unroll") for (int n = 0; n < 2; ++n) _Pragma("unroll") for (int k = 0; k < 2; ++k) \
;         acc[ai][bj][m][n] = __builtin_amdgcn_mfma_f32_16x16x32_bf16(Bt[n][k], At[m][k], acc[ai][bj][m][n], 0, 0, 0); __builtin_amdgcn_s_setprio(0); } while (0)
; #define PG8_WAIT_V(n) asm volatile("s_waitcnt vmcnt(" #n ")" ::: "memory")
; #define PG8_WAIT_L(n) asm volatile("s_waitcnt lgkmcnt(" #n ")" ::: "memory")
; #define PG8_BAR __builtin_amdgcn_s_barrier()
; #define PG8_SCHED __builtin_amdgcn_sched_barrier(0)
; template <class Epi>
; __device__ __forceinline__ void gemm_phase(LAS unsigned char* lds, const Gemm g, const StaticOrder& S, const Epi& E) {
;     ...
;             PG8_LDB(B0, 1, 0); PG8_SCHED; PG8_LDA(At, 1, 0); PG8_STAGE(PG8_SA(0, 1), a2 + hstepA, voffA);
;             PG8_WAIT_L(8); PG8_BAR; PG8_WAIT_L(0); PG8_MMA(0, 0, At, B0); PG8_BAR; PG8_SCHED;
;             PG8_LDB(B1, 1, 1); PG8_STAGE(PG8_SB(1, 0), b3, voffB);
;             PG8_BAR; PG8_WAIT_L(0); PG8_MMA(0, 1, At, B1); PG8_BAR;
;             PG8_LDA(At, 1, 1); PG8_STAGE(PG8_SA(1, 0), a3, voffA);
;             PG8_BAR; PG8_WAIT_L(0); PG8_MMA(1, 0, At, B0); PG8_BAR; PG8_SCHED;
;             PG8_STAGE(PG8_SB(1, 1), b3 + hstepB, voffB);
;             PG8_WAIT_V(6); PG8_BAR; PG8_MMA(1, 1, At, B1); PG8_BAR;
	s_add_i32 s59, 0, 0x18000
	v_add_u32_e32 v161, s59, v156
	ds_read_b128 v[144:147], v161
	ds_read_b128 v[148:151], v161 offset:1024
	ds_read_b128 v[162:165], v161 offset:2048
	ds_read_b128 v[166:169], v161 offset:3072
	ds_read_b128 v[170:173], v159 offset:32768
	ds_read_b128 v[174:177], v159 offset:33792
	ds_read_b128 v[178:181], v159 offset:34816
	ds_read_b128 v[182:185], v159 offset:35840
	ds_read_b128 v[186:189], v159 offset:36864
	ds_read_b128 v[190:193], v159 offset:37888
	ds_read_b128 v[194:197], v159 offset:38912
	ds_read_b128 v[198:201], v159 offset:39936
	s_add_i32 s98, 0, 0x1c000
	v_add_u32_e32 v246, s98, v156
	ds_read_b128 v[202:205], v246
	ds_read_b128 v[206:209], v246 offset:1024
	ds_read_b128 v[210:213], v246 offset:2048
	ds_read_b128 v[214:217], v246 offset:3072
	s_add_u32 s100, s66, 0x40000
	s_addc_u32 s101, s67, 0
	s_add_i32 s99, s79, s33
	s_mov_b32 m0, s99
	v_lshl_add_u64 v[240:241], s[100:101], 0, v[132:133]
	global_load_lds_dwordx4 v[240:241], off
	s_add_i32 m0, s99, 0x2000
	v_lshl_add_u64 v[240:241], s[100:101], 0, v[136:137]
	global_load_lds_dwordx4 v[240:241], off
	s_add_u32 s68, s68, 0x40000
	s_addc_u32 s69, s69, 0
	s_mov_b32 m0, s71
	v_lshl_add_u64 v[244:245], s[68:69], 0, v[130:131]
	global_load_lds_dwordx4 v[244:245], off
	s_mov_b32 m0, s72
	v_lshl_add_u64 v[244:245], s[68:69], 0, v[134:135]
	global_load_lds_dwordx4 v[244:245], off
	s_waitcnt vmcnt(8) lgkmcnt(0)
	s_barrier
	v_mfma_f32_16x16x32_bf16 v[124:127], v[144:147], v[170:173], v[124:127]
	v_mfma_f32_16x16x32_bf16 v[120:123], v[162:165], v[170:173], v[120:123]
	v_mfma_f32_16x16x32_bf16 v[116:119], v[144:147], v[178:181], v[116:119]
	v_mfma_f32_16x16x32_bf16 v[108:111], v[162:165], v[178:181], v[108:111]
	v_mfma_f32_16x16x32_bf16 v[100:103], v[144:147], v[186:189], v[100:103]
	v_mfma_f32_16x16x32_bf16 v[92:95], v[162:165], v[186:189], v[92:95]
	v_mfma_f32_16x16x32_bf16 v[84:87], v[144:147], v[194:197], v[84:87]
	v_mfma_f32_16x16x32_bf16 v[76:79], v[162:165], v[194:197], v[76:79]
	v_mfma_f32_16x16x32_bf16 v[124:127], v[148:151], v[174:177], v[124:127]
	v_mfma_f32_16x16x32_bf16 v[120:123], v[166:169], v[174:177], v[120:123]
	v_mfma_f32_16x16x32_bf16 v[116:119], v[148:151], v[182:185], v[116:119]
	v_mfma_f32_16x16x32_bf16 v[108:111], v[166:169], v[182:185], v[108:111]
	v_mfma_f32_16x16x32_bf16 v[100:103], v[148:151], v[190:193], v[100:103]
	v_mfma_f32_16x16x32_bf16 v[92:95], v[166:169], v[190:193], v[92:95]
	v_mfma_f32_16x16x32_bf16 v[84:87], v[148:151], v[198:201], v[84:87]
	v_mfma_f32_16x16x32_bf16 v[76:79], v[166:169], v[198:201], v[76:79]
	v_mfma_f32_16x16x32_bf16 v[112:115], v[202:205], v[170:173], v[112:115]
	v_mfma_f32_16x16x32_bf16 v[104:107], v[210:213], v[170:173], v[104:107]
	v_mfma_f32_16x16x32_bf16 v[96:99], v[202:205], v[178:181], v[96:99]
	v_mfma_f32_16x16x32_bf16 v[88:91], v[210:213], v[178:181], v[88:91]
	v_mfma_f32_16x16x32_bf16 v[80:83], v[202:205], v[186:189], v[80:83]
	v_mfma_f32_16x16x32_bf16 v[72:75], v[210:213], v[186:189], v[72:75]
	v_mfma_f32_16x16x32_bf16 v[68:71], v[202:205], v[194:197], v[68:71]
	v_mfma_f32_16x16x32_bf16 v[64:67], v[210:213], v[194:197], v[64:67]
	v_mfma_f32_16x16x32_bf16 v[112:115], v[206:209], v[174:177], v[112:115]
	v_mfma_f32_16x16x32_bf16 v[104:107], v[214:217], v[174:177], v[104:107]
	v_mfma_f32_16x16x32_bf16 v[96:99], v[206:209], v[182:185], v[96:99]
	v_mfma_f32_16x16x32_bf16 v[88:91], v[214:217], v[182:185], v[88:91]
	v_mfma_f32_16x16x32_bf16 v[80:83], v[206:209], v[190:193], v[80:83]
	v_mfma_f32_16x16x32_bf16 v[72:75], v[214:217], v[190:193], v[72:75]
	v_mfma_f32_16x16x32_bf16 v[68:71], v[206:209], v[198:201], v[68:71]
	v_mfma_f32_16x16x32_bf16 v[64:67], v[214:217], v[198:201], v[64:67]
	s_barrier
	ds_read_b128 v[170:173], v159 offset:49152
	ds_read_b128 v[174:177], v159 offset:50176
	ds_read_b128 v[178:181], v159 offset:51200
	ds_read_b128 v[182:185], v159 offset:52224
	ds_read_b128 v[186:189], v159 offset:53248
	ds_read_b128 v[190:193], v159 offset:54272
	ds_read_b128 v[194:197], v159 offset:55296
	ds_read_b128 v[198:201], v159 offset:56320
	s_add_i32 s59, s59, s33
	s_mov_b32 m0, s59
	v_lshl_add_u64 v[152:153], v[152:153], 0, s[12:13]
	global_load_lds_dwordx4 v[152:153], off
	s_add_i32 m0, s59, 0x2000
	v_lshl_add_u64 v[152:153], v[218:219], 0, s[12:13]
	global_load_lds_dwordx4 v[152:153], off
	s_mov_b32 m0, s73
	v_lshl_add_u64 v[152:153], v[220:221], 0, s[12:13]
	global_load_lds_dwordx4 v[152:153], off
	s_mov_b32 m0, s74
	v_lshl_add_u64 v[152:153], v[222:223], 0, s[12:13]
	global_load_lds_dwordx4 v[152:153], off
	s_add_u32 s66, s66, 0x40080
	s_addc_u32 s67, s67, 0
	s_add_i32 s59, s98, s33
	s_mov_b32 m0, s59
	v_lshl_add_u64 v[240:241], s[66:67], 0, v[132:133]
	global_load_lds_dwordx4 v[240:241], off
	s_add_i32 m0, s59, 0x2000
	v_lshl_add_u64 v[240:241], s[66:67], 0, v[136:137]
	global_load_lds_dwordx4 v[240:241], off
	s_waitcnt vmcnt(8) lgkmcnt(0)
	s_barrier
; #define PG8_STAGE(bufoff, gbase, voff) do { _Pragma("unroll") for (int _i = 0; _i < 2; ++_i) \
;         __builtin_amdgcn_global_load_lds((const unsigned*)((const char*)(gbase) + (voff)[_i]), (LAS unsigned*)(lds + (bufoff) + ldsw + _i * 8192), 16, 0, 0); } while (0)
; #define PG8_LDA(dst, b, h) do { _Pragma("unroll") for (int m = 0; m < 4; ++m) _Pragma("unroll") for (int k = 0; k < 2; ++k) dst[m][k] = *(const LAS bf16x8*)(lds + PG8_SA(b, h) + aoff + m * 2048 + k * 1024); } while (0)
; #define PG8_LDB(dst, b, h) do { _Pragma("unroll") for (int n = 0; n < 2; ++n) _Pragma("unroll") for (int k = 0; k < 2; ++k) dst[n][k] = *(const LAS bf16x8*)(lds + PG8_SB(b, h) + boff + n * 2048 + k * 1024); } while (0)
; #define PG8_MMA(ai, bj, At, Bt) do { __builtin_amdgcn_s_setprio(1); _Pragma("unroll") for (int m = 0; m < 4; ++m) _Pragma("unroll") for (int n = 0; n < 2; ++n) _Pragma("unroll") for (int k = 0; k < 2; ++k) \
;         acc[ai][bj][m][n] = __builtin_amdgcn_mfma_f32_16x16x32_bf16(Bt[n][k], At[m][k], acc[ai][bj][m][n], 0, 0, 0); __builtin_amdgcn_s_setprio(0); } while (0)
; #define PG8_WAIT_V(n) asm volatile("s_waitcnt vmcnt(" #n ")" ::: "memory")
; #define PG8_WAIT_L(n) asm volatile("s_waitcnt lgkmcnt(" #n ")" ::: "memory")
; template <class Epi>
; __device__ __forceinline__ void gemm_phase(LAS unsigned char* lds, const Gemm g, const StaticOrder& S, const Epi& E) {
;     ...
;         for (int t = 0; t < nt; t += 2) {
;             const bool last = (t == nt - 2);
;             const char* a1 = cA + (size_t)(t + 1) * kstep;
;             const char* a2 = last ? nA : cA + (size_t)(t + 2) * kstep; const char* b2 = last ? nB : cB + (size_t)(t + 2) * kstep;
;             const char* a3 = a2 + kstep; const char* b3 = b2 + kstep;
;             PG8_LDB(B0, 0, 0); PG8_SCHED; PG8_LDA(At, 0, 0); PG8_STAGE(PG8_SA(1, 1), a1 + hstepA, voffA);
;             PG8_WAIT_L(8); PG8_BAR; PG8_WAIT_L(0); PG8_MMA(0, 0, At, B0); PG8_BAR; PG8_SCHED;
;             PG8_LDB(B1, 0, 1); PG8_STAGE(PG8_SB(0, 0), b2, voffB);
;             PG8_BAR; PG8_WAIT_L(0); PG8_MMA(0, 1, At, B1); PG8_BAR;
;             PG8_LDA(At, 0, 1); PG8_STAGE(PG8_SA(0, 0), a2, voffA);
;             PG8_BAR; PG8_WAIT_L(0); PG8_MMA(1, 0, At, B0); PG8_BAR; PG8_SCHED;
;             PG8_STAGE(PG8_SB(0, 1), b2 + hstepB, voffB);
;             PG8_WAIT_V(6); PG8_BAR; PG8_MMA(1, 1, At, B1); PG8_BAR;
	v_mfma_f32_16x16x32_bf16 v[60:63], v[144:147], v[170:173], v[60:63]
	v_mfma_f32_16x16x32_bf16 v[56:59], v[162:165], v[170:173], v[56:59]
	v_mfma_f32_16x16x32_bf16 v[52:55], v[144:147], v[178:181], v[52:55]
	v_mfma_f32_16x16x32_bf16 v[44:47], v[162:165], v[178:181], v[44:47]
	v_mfma_f32_16x16x32_bf16 v[36:39], v[144:147], v[186:189], v[36:39]
	v_mfma_f32_16x16x32_bf16 v[28:31], v[162:165], v[186:189], v[28:31]
	v_mfma_f32_16x16x32_bf16 v[20:23], v[144:147], v[194:197], v[20:23]
	v_mfma_f32_16x16x32_bf16 v[12:15], v[162:165], v[194:197], v[12:15]
	v_mfma_f32_16x16x32_bf16 v[60:63], v[148:151], v[174:177], v[60:63]
	v_mfma_f32_16x16x32_bf16 v[56:59], v[166:169], v[174:177], v[56:59]
	v_mfma_f32_16x16x32_bf16 v[52:55], v[148:151], v[182:185], v[52:55]
	v_mfma_f32_16x16x32_bf16 v[44:47], v[166:169], v[182:185], v[44:47]
	v_mfma_f32_16x16x32_bf16 v[36:39], v[148:151], v[190:193], v[36:39]
	v_mfma_f32_16x16x32_bf16 v[28:31], v[166:169], v[190:193], v[28:31]
	v_mfma_f32_16x16x32_bf16 v[20:23], v[148:151], v[198:201], v[20:23]
	v_mfma_f32_16x16x32_bf16 v[12:15], v[166:169], v[198:201], v[12:15]
	v_mfma_f32_16x16x32_bf16 v[48:51], v[202:205], v[170:173], v[48:51]
	v_mfma_f32_16x16x32_bf16 v[40:43], v[210:213], v[170:173], v[40:43]
	v_mfma_f32_16x16x32_bf16 v[32:35], v[202:205], v[178:181], v[32:35]
	v_mfma_f32_16x16x32_bf16 v[24:27], v[210:213], v[178:181], v[24:27]
	v_mfma_f32_16x16x32_bf16 v[16:19], v[202:205], v[186:189], v[16:19]
	v_mfma_f32_16x16x32_bf16 v[8:11], v[210:213], v[186:189], v[8:11]
	v_mfma_f32_16x16x32_bf16 v[4:7], v[202:205], v[194:197], v[4:7]
	v_mfma_f32_16x16x32_bf16 v[0:3], v[210:213], v[194:197], v[0:3]
	v_mfma_f32_16x16x32_bf16 v[48:51], v[206:209], v[174:177], v[48:51]
	v_mfma_f32_16x16x32_bf16 v[40:43], v[214:217], v[174:177], v[40:43]
	v_mfma_f32_16x16x32_bf16 v[32:35], v[206:209], v[182:185], v[32:35]
	v_mfma_f32_16x16x32_bf16 v[24:27], v[214:217], v[182:185], v[24:27]
	v_mfma_f32_16x16x32_bf16 v[16:19], v[206:209], v[190:193], v[16:19]
	v_mfma_f32_16x16x32_bf16 v[8:11], v[214:217], v[190:193], v[8:11]
	v_mfma_f32_16x16x32_bf16 v[4:7], v[206:209], v[198:201], v[4:7]
	v_mfma_f32_16x16x32_bf16 v[0:3], v[214:217], v[198:201], v[0:3]
	s_add_u32 s64, s64, 0x100
	s_addc_u32 s65, s65, 0
	s_add_u32 s31, s31, 0x100
	s_addc_u32 s57, s57, 0
	s_cmp_ge_i32 s85, s84
	s_mov_b32 s59, s85
	s_barrier
.LBB0_456:
	s_add_i32 s85, s59, 2
	s_add_u32 s66, s64, 0xfffc0080
	s_addc_u32 s67, s65, -1
	s_cmp_eq_u32 s21, s59
	s_cselect_b32 s69, s63, s67
	s_cselect_b32 s68, s62, s66
	s_cselect_b32 s67, s1, s57
	s_cselect_b32 s66, s0, s31
	ds_read_b128 v[144:147], v158
	ds_read_b128 v[148:151], v158 offset:1024
	ds_read_b128 v[162:165], v158 offset:2048
	ds_read_b128 v[166:169], v158 offset:3072
	ds_read_b128 v[170:173], v159
	ds_read_b128 v[174:177], v159 offset:1024
	ds_read_b128 v[178:181], v159 offset:2048
	ds_read_b128 v[182:185], v159 offset:3072
	ds_read_b128 v[186:189], v159 offset:4096
	ds_read_b128 v[190:193], v159 offset:5120
	ds_read_b128 v[194:197], v159 offset:6144
	ds_read_b128 v[198:201], v159 offset:7168
	ds_read_b128 v[202:205], v160
	ds_read_b128 v[206:209], v160 offset:1024
	ds_read_b128 v[210:213], v160 offset:2048
	ds_read_b128 v[214:217], v160 offset:3072
	s_add_i32 m0, s35, 0xc000
	v_lshl_add_u64 v[152:153], s[64:65], 0, v[138:139]
	global_load_lds_dwordx4 v[152:153], off
	s_add_i32 m0, s35, 0xe000
	v_lshl_add_u64 v[152:153], s[64:65], 0, v[140:141]
	global_load_lds_dwordx4 v[152:153], off
	s_waitcnt vmcnt(8) lgkmcnt(0)
	s_barrier
	v_mfma_f32_16x16x32_bf16 v[124:127], v[144:147], v[170:173], v[124:127]
	v_mfma_f32_16x16x32_bf16 v[120:123], v[162:165], v[170:173], v[120:123]
	v_mfma_f32_16x16x32_bf16 v[116:119], v[144:147], v[178:181], v[116:119]
	v_mfma_f32_16x16x32_bf16 v[108:111], v[162:165], v[178:181], v[108:111]
	v_mfma_f32_16x16x32_bf16 v[100:103], v[144:147], v[186:189], v[100:103]
	v_mfma_f32_16x16x32_bf16 v[92:95], v[162:165], v[186:189], v[92:95]
	v_mfma_f32_16x16x32_bf16 v[84:87], v[144:147], v[194:197], v[84:87]
	v_mfma_f32_16x16x32_bf16 v[76:79], v[162:165], v[194:197], v[76:79]
	v_mfma_f32_16x16x32_bf16 v[124:127], v[148:151], v[174:177], v[124:127]
	v_mfma_f32_16x16x32_bf16 v[120:123], v[166:169], v[174:177], v[120:123]
	v_mfma_f32_16x16x32_bf16 v[116:119], v[148:151], v[182:185], v[116:119]
	v_mfma_f32_16x16x32_bf16 v[108:111], v[166:169], v[182:185], v[108:111]
	v_mfma_f32_16x16x32_bf16 v[100:103], v[148:151], v[190:193], v[100:103]
	v_mfma_f32_16x16x32_bf16 v[92:95], v[166:169], v[190:193], v[92:95]
	v_mfma_f32_16x16x32_bf16 v[84:87], v[148:151], v[198:201], v[84:87]
	v_mfma_f32_16x16x32_bf16 v[76:79], v[166:169], v[198:201], v[76:79]
	v_mfma_f32_16x16x32_bf16 v[112:115], v[202:205], v[170:173], v[112:115]
	v_mfma_f32_16x16x32_bf16 v[104:107], v[210:213], v[170:173], v[104:107]
	v_mfma_f32_16x16x32_bf16 v[96:99], v[202:205], v[178:181], v[96:99]
	v_mfma_f32_16x16x32_bf16 v[88:91], v[210:213], v[178:181], v[88:91]
	v_mfma_f32_16x16x32_bf16 v[80:83], v[202:205], v[186:189], v[80:83]
	v_mfma_f32_16x16x32_bf16 v[72:75], v[210:213], v[186:189], v[72:75]
	v_mfma_f32_16x16x32_bf16 v[68:71], v[202:205], v[194:197], v[68:71]
	v_mfma_f32_16x16x32_bf16 v[64:67], v[210:213], v[194:197], v[64:67]
	v_mfma_f32_16x16x32_bf16 v[112:115], v[206:209], v[174:177], v[112:115]
	v_mfma_f32_16x16x32_bf16 v[104:107], v[214:217], v[174:177], v[104:107]
	v_mfma_f32_16x16x32_bf16 v[96:99], v[206:209], v[182:185], v[96:99]
	v_mfma_f32_16x16x32_bf16 v[88:91], v[214:217], v[182:185], v[88:91]
	v_mfma_f32_16x16x32_bf16 v[80:83], v[206:209], v[190:193], v[80:83]
	v_mfma_f32_16x16x32_bf16 v[72:75], v[214:217], v[190:193], v[72:75]
	v_mfma_f32_16x16x32_bf16 v[68:71], v[206:209], v[198:201], v[68:71]
	v_mfma_f32_16x16x32_bf16 v[64:67], v[214:217], v[198:201], v[64:67]
	s_barrier
; #define PG8_STAGE(bufoff, gbase, voff) do { _Pragma("unroll") for (int _i = 0; _i < 2; ++_i) \
;         __builtin_amdgcn_global_load_lds((const unsigned*)((const char*)(gbase) + (voff)[_i]), (LAS unsigned*)(lds + (bufoff) + ldsw + _i * 8192), 16, 0, 0); } while (0)
; #define PG8_LDA(dst, b, h) do { _Pragma("unroll") for (int m = 0; m < 4; ++m) _Pragma("unroll") for (int k = 0; k < 2; ++k) dst[m][k] = *(const LAS bf16x8*)(lds + PG8_SA(b, h) + aoff + m * 2048 + k * 1024); } while (0)
; #define PG8_LDB(dst, b, h) do { _Pragma("unroll") for (int n = 0; n < 2; ++n) _Pragma("unroll") for (int k = 0; k < 2; ++k) dst[n][k] = *(const LAS bf16x8*)(lds + PG8_SB(b, h) + boff + n * 2048 + k * 1024); } while (0)
; #define PG8_MMA(ai, bj, At, Bt) do { __builtin_amdgcn_s_setprio(1); _Pragma("unroll") for (int m = 0; m < 4; ++m) _Pragma("unroll") for (int n = 0; n < 2; ++n) _Pragma("unroll") for (int k = 0; k < 2; ++k) \
;         acc[ai][bj][m][n] = __builtin_amdgcn_mfma_f32_16x16x32_bf16(Bt[n][k], At[m][k], acc[ai][bj][m][n], 0, 0, 0); __builtin_amdgcn_s_setprio(0); } while (0)
; #define PG8_WAIT_V(n) asm volatile("s_waitcnt vmcnt(" #n ")" ::: "memory")
; #define PG8_BAR __builtin_amdgcn_s_barrier()
; template <class Epi>
; __device__ __forceinline__ void gemm_phase(LAS unsigned char* lds, const Gemm g, const StaticOrder& S, const Epi& E) {
;     ...
;             PG8_LDB(B1, 0, 1); PG8_STAGE(PG8_SB(0, 0), b2, voffB);
;             PG8_BAR; PG8_WAIT_L(0); PG8_MMA(0, 1, At, B1); PG8_BAR;
;             PG8_LDA(At, 0, 1); PG8_STAGE(PG8_SA(0, 0), a2, voffA);
;             PG8_BAR; PG8_WAIT_L(0); PG8_MMA(1, 0, At, B0); PG8_BAR; PG8_SCHED;
;             PG8_STAGE(PG8_SB(0, 1), b2 + hstepB, voffB);
;             PG8_WAIT_V(6); PG8_BAR; PG8_MMA(1, 1, At, B1); PG8_BAR;
;             PG8_LDB(B0, 1, 0); PG8_SCHED; PG8_LDA(At, 1, 0); PG8_STAGE(PG8_SA(0, 1), a2 + hstepA, voffA);
;             PG8_WAIT_L(8); PG8_BAR; PG8_WAIT_L(0); PG8_MMA(0, 0, At, B0); PG8_BAR; PG8_SCHED;
;             PG8_LDB(B1, 1, 1); PG8_STAGE(PG8_SB(1, 0), b3, voffB);
;             PG8_BAR; PG8_WAIT_L(0); PG8_MMA(0, 1, At, B1); PG8_BAR;
;             PG8_LDA(At, 1, 1); PG8_STAGE(PG8_SA(1, 0), a3, voffA);
;             PG8_BAR; PG8_WAIT_L(0); PG8_MMA(1, 0, At, B0); PG8_BAR; PG8_SCHED;
;             PG8_STAGE(PG8_SB(1, 1), b3 + hstepB, voffB);
;             PG8_WAIT_V(6); PG8_BAR; PG8_MMA(1, 1, At, B1); PG8_BAR;
	ds_read_b128 v[170:173], v159 offset:16384
	ds_read_b128 v[174:177], v159 offset:17408
	ds_read_b128 v[178:181], v159 offset:18432
	ds_read_b128 v[182:185], v159 offset:19456
	ds_read_b128 v[186:189], v159 offset:20480
	ds_read_b128 v[190:193], v159 offset:21504
	ds_read_b128 v[194:197], v159 offset:22528
	ds_read_b128 v[198:201], v159 offset:23552
	s_add_i32 s59, s78, s33
	s_mov_b32 m0, s59
	v_lshl_add_u64 v[152:153], s[66:67], 0, v[132:133]
	global_load_lds_dwordx4 v[152:153], off
	s_add_i32 m0, s59, 0x2000
	v_lshl_add_u64 v[218:219], s[66:67], 0, v[136:137]
	global_load_lds_dwordx4 v[218:219], off
	s_mov_b32 m0, s35
	v_lshl_add_u64 v[220:221], s[68:69], 0, v[130:131]
	global_load_lds_dwordx4 v[220:221], off
	s_mov_b32 m0, s70
	v_lshl_add_u64 v[222:223], s[68:69], 0, v[134:135]
	global_load_lds_dwordx4 v[222:223], off
	s_waitcnt vmcnt(6) lgkmcnt(0)
	s_barrier
	v_mfma_f32_16x16x32_bf16 v[60:63], v[144:147], v[170:173], v[60:63]
	v_mfma_f32_16x16x32_bf16 v[56:59], v[162:165], v[170:173], v[56:59]
	v_mfma_f32_16x16x32_bf16 v[52:55], v[144:147], v[178:181], v[52:55]
	v_mfma_f32_16x16x32_bf16 v[44:47], v[162:165], v[178:181], v[44:47]
	v_mfma_f32_16x16x32_bf16 v[36:39], v[144:147], v[186:189], v[36:39]
	v_mfma_f32_16x16x32_bf16 v[28:31], v[162:165], v[186:189], v[28:31]
	v_mfma_f32_16x16x32_bf16 v[20:23], v[144:147], v[194:197], v[20:23]
	v_mfma_f32_16x16x32_bf16 v[12:15], v[162:165], v[194:197], v[12:15]
	v_mfma_f32_16x16x32_bf16 v[60:63], v[148:151], v[174:177], v[60:63]
	v_mfma_f32_16x16x32_bf16 v[56:59], v[166:169], v[174:177], v[56:59]
	v_mfma_f32_16x16x32_bf16 v[52:55], v[148:151], v[182:185], v[52:55]
	v_mfma_f32_16x16x32_bf16 v[44:47], v[166:169], v[182:185], v[44:47]
	v_mfma_f32_16x16x32_bf16 v[36:39], v[148:151], v[190:193], v[36:39]
	v_mfma_f32_16x16x32_bf16 v[28:31], v[166:169], v[190:193], v[28:31]
	v_mfma_f32_16x16x32_bf16 v[20:23], v[148:151], v[198:201], v[20:23]
	v_mfma_f32_16x16x32_bf16 v[12:15], v[166:169], v[198:201], v[12:15]
	v_mfma_f32_16x16x32_bf16 v[48:51], v[202:205], v[170:173], v[48:51]
	v_mfma_f32_16x16x32_bf16 v[40:43], v[210:213], v[170:173], v[40:43]
	v_mfma_f32_16x16x32_bf16 v[32:35], v[202:205], v[178:181], v[32:35]
	v_mfma_f32_16x16x32_bf16 v[24:27], v[210:213], v[178:181], v[24:27]
	v_mfma_f32_16x16x32_bf16 v[16:19], v[202:205], v[186:189], v[16:19]
	v_mfma_f32_16x16x32_bf16 v[8:11], v[210:213], v[186:189], v[8:11]
	v_mfma_f32_16x16x32_bf16 v[4:7], v[202:205], v[194:197], v[4:7]
	v_mfma_f32_16x16x32_bf16 v[0:3], v[210:213], v[194:197], v[0:3]
	v_mfma_f32_16x16x32_bf16 v[48:51], v[206:209], v[174:177], v[48:51]
	v_mfma_f32_16x16x32_bf16 v[40:43], v[214:217], v[174:177], v[40:43]
	v_mfma_f32_16x16x32_bf16 v[32:35], v[206:209], v[182:185], v[32:35]
	v_mfma_f32_16x16x32_bf16 v[24:27], v[214:217], v[182:185], v[24:27]
	v_mfma_f32_16x16x32_bf16 v[16:19], v[206:209], v[190:193], v[16:19]
	v_mfma_f32_16x16x32_bf16 v[8:11], v[214:217], v[190:193], v[8:11]
	v_mfma_f32_16x16x32_bf16 v[4:7], v[206:209], v[198:201], v[4:7]
	v_mfma_f32_16x16x32_bf16 v[0:3], v[214:217], v[198:201], v[0:3]
	s_barrier
	s_add_i32 s59, 0, 0x18000
	v_add_u32_e32 v161, s59, v156
	ds_read_b128 v[144:147], v161
	ds_read_b128 v[148:151], v161 offset:1024
	ds_read_b128 v[162:165], v161 offset:2048
	ds_read_b128 v[166:169], v161 offset:3072
	ds_read_b128 v[170:173], v159 offset:32768
	ds_read_b128 v[174:177], v159 offset:33792
	ds_read_b128 v[178:181], v159 offset:34816
	ds_read_b128 v[182:185], v159 offset:35840
	ds_read_b128 v[186:189], v159 offset:36864
	ds_read_b128 v[190:193], v159 offset:37888
	ds_read_b128 v[194:197], v159 offset:38912
	ds_read_b128 v[198:201], v159 offset:39936
	s_add_i32 s98, 0, 0x1c000
	v_add_u32_e32 v246, s98, v156
	ds_read_b128 v[202:205], v246
	ds_read_b128 v[206:209], v246 offset:1024
	ds_read_b128 v[210:213], v246 offset:2048
	ds_read_b128 v[214:217], v246 offset:3072
	s_add_u32 s100, s66, 0x40000
	s_addc_u32 s101, s67, 0
	s_add_i32 s99, s79, s33
	s_mov_b32 m0, s99
	v_lshl_add_u64 v[240:241], s[100:101], 0, v[132:133]
	global_load_lds_dwordx4 v[240:241], off
	s_add_i32 m0, s99, 0x2000
	v_lshl_add_u64 v[240:241], s[100:101], 0, v[136:137]
	global_load_lds_dwordx4 v[240:241], off
	s_add_u32 s68, s68, 0x40000
	s_addc_u32 s69, s69, 0
	s_mov_b32 m0, s71
	v_lshl_add_u64 v[244:245], s[68:69], 0, v[130:131]
	global_load_lds_dwordx4 v[244:245], off
	s_mov_b32 m0, s72
	v_lshl_add_u64 v[244:245], s[68:69], 0, v[134:135]
	global_load_lds_dwordx4 v[244:245], off
	s_waitcnt vmcnt(8) lgkmcnt(0)
	s_barrier
	v_mfma_f32_16x16x32_bf16 v[124:127], v[144:147], v[170:173], v[124:127]
	v_mfma_f32_16x16x32_bf16 v[120:123], v[162:165], v[170:173], v[120:123]
	v_mfma_f32_16x16x32_bf16 v[116:119], v[144:147], v[178:181], v[116:119]
	v_mfma_f32_16x16x32_bf16 v[108:111], v[162:165], v[178:181], v[108:111]
	v_mfma_f32_16x16x32_bf16 v[100:103], v[144:147], v[186:189], v[100:103]
	v_mfma_f32_16x16x32_bf16 v[92:95], v[162:165], v[186:189], v[92:95]
	v_mfma_f32_16x16x32_bf16 v[84:87], v[144:147], v[194:197], v[84:87]
	v_mfma_f32_16x16x32_bf16 v[76:79], v[162:165], v[194:197], v[76:79]
	v_mfma_f32_16x16x32_bf16 v[124:127], v[148:151], v[174:177], v[124:127]
	v_mfma_f32_16x16x32_bf16 v[120:123], v[166:169], v[174:177], v[120:123]
	v_mfma_f32_16x16x32_bf16 v[116:119], v[148:151], v[182:185], v[116:119]
	v_mfma_f32_16x16x32_bf16 v[108:111], v[166:169], v[182:185], v[108:111]
	v_mfma_f32_16x16x32_bf16 v[100:103], v[148:151], v[190:193], v[100:103]
	v_mfma_f32_16x16x32_bf16 v[92:95], v[166:169], v[190:193], v[92:95]
	v_mfma_f32_16x16x32_bf16 v[84:87], v[148:151], v[198:201], v[84:87]
	v_mfma_f32_16x16x32_bf16 v[76:79], v[166:169], v[198:201], v[76:79]
	v_mfma_f32_16x16x32_bf16 v[112:115], v[202:205], v[170:173], v[112:115]
	v_mfma_f32_16x16x32_bf16 v[104:107], v[210:213], v[170:173], v[104:107]
	v_mfma_f32_16x16x32_bf16 v[96:99], v[202:205], v[178:181], v[96:99]
	v_mfma_f32_16x16x32_bf16 v[88:91], v[210:213], v[178:181], v[88:91]
	v_mfma_f32_16x16x32_bf16 v[80:83], v[202:205], v[186:189], v[80:83]
	v_mfma_f32_16x16x32_bf16 v[72:75], v[210:213], v[186:189], v[72:75]
	v_mfma_f32_16x16x32_bf16 v[68:71], v[202:205], v[194:197], v[68:71]
	v_mfma_f32_16x16x32_bf16 v[64:67], v[210:213], v[194:197], v[64:67]
	v_mfma_f32_16x16x32_bf16 v[112:115], v[206:209], v[174:177], v[112:115]
	v_mfma_f32_16x16x32_bf16 v[104:107], v[214:217], v[174:177], v[104:107]
	v_mfma_f32_16x16x32_bf16 v[96:99], v[206:209], v[182:185], v[96:99]
	v_mfma_f32_16x16x32_bf16 v[88:91], v[214:217], v[182:185], v[88:91]
	v_mfma_f32_16x16x32_bf16 v[80:83], v[206:209], v[190:193], v[80:83]
	v_mfma_f32_16x16x32_bf16 v[72:75], v[214:217], v[190:193], v[72:75]
	v_mfma_f32_16x16x32_bf16 v[68:71], v[206:209], v[198:201], v[68:71]
	v_mfma_f32_16x16x32_bf16 v[64:67], v[214:217], v[198:201], v[64:67]
	s_barrier
; #define PG8_STAGE(bufoff, gbase, voff) do { _Pragma("unroll") for (int _i = 0; _i < 2; ++_i) \
;         __builtin_amdgcn_global_load_lds((const unsigned*)((const char*)(gbase) + (voff)[_i]), (LAS unsigned*)(lds + (bufoff) + ldsw + _i * 8192), 16, 0, 0); } while (0)
; #define PG8_LDA(dst, b, h) do { _Pragma("unroll") for (int m = 0; m < 4; ++m) _Pragma("unroll") for (int k = 0; k < 2; ++k) dst[m][k] = *(const LAS bf16x8*)(lds + PG8_SA(b, h) + aoff + m * 2048 + k * 1024); } while (0)
; #define PG8_MMA(ai, bj, At, Bt) do { __builtin_amdgcn_s_setprio(1); _Pragma("unroll") for (int m = 0; m < 4; ++m) _Pragma("unroll") for (int n = 0; n < 2; ++n) _Pragma("unroll") for (int k = 0; k < 2; ++k) \
;         acc[ai][bj][m][n] = __builtin_amdgcn_mfma_f32_16x16x32_bf16(Bt[n][k], At[m][k], acc[ai][bj][m][n], 0, 0, 0); __builtin_amdgcn_s_setprio(0); } while (0)
; #define PG8_WAIT_V(n) asm volatile("s_waitcnt vmcnt(" #n ")" ::: "memory")
; #define PG8_WAIT_L(n) asm volatile("s_waitcnt lgkmcnt(" #n ")" ::: "memory")
; #define PG8_BAR __builtin_amdgcn_s_barrier()
; #define PG8_SCHED __builtin_amdgcn_sched_barrier(0)
; template <class Epi>
; __device__ __forceinline__ void gemm_phase(LAS unsigned char* lds, const Gemm g, const StaticOrder& S, const Epi& E) {
;     ...
;             PG8_LDA(At, 1, 1); PG8_STAGE(PG8_SA(1, 0), a3, voffA);
;             PG8_BAR; PG8_WAIT_L(0); PG8_MMA(1, 0, At, B0); PG8_BAR; PG8_SCHED;
;             PG8_STAGE(PG8_SB(1, 1), b3 + hstepB, voffB);
;             PG8_WAIT_V(6); PG8_BAR; PG8_MMA(1, 1, At, B1); PG8_BAR;
	ds_read_b128 v[170:173], v159 offset:49152
	ds_read_b128 v[174:177], v159 offset:50176
	ds_read_b128 v[178:181], v159 offset:51200
	ds_read_b128 v[182:185], v159 offset:52224
	ds_read_b128 v[186:189], v159 offset:53248
	ds_read_b128 v[190:193], v159 offset:54272
	ds_read_b128 v[194:197], v159 offset:55296
	ds_read_b128 v[198:201], v159 offset:56320
	s_add_i32 s59, s59, s33
	s_mov_b32 m0, s59
	v_lshl_add_u64 v[152:153], v[152:153], 0, s[12:13]
	global_load_lds_dwordx4 v[152:153], off
	s_add_i32 m0, s59, 0x2000
	v_lshl_add_u64 v[152:153], v[218:219], 0, s[12:13]
	global_load_lds_dwordx4 v[152:153], off
	s_mov_b32 m0, s73
	v_lshl_add_u64 v[152:153], v[220:221], 0, s[12:13]
	global_load_lds_dwordx4 v[152:153], off
	s_mov_b32 m0, s74
	v_lshl_add_u64 v[152:153], v[222:223], 0, s[12:13]
	global_load_lds_dwordx4 v[152:153], off
	s_add_u32 s66, s66, 0x40080
	s_addc_u32 s67, s67, 0
	s_add_i32 s59, s98, s33
	s_mov_b32 m0, s59
	v_lshl_add_u64 v[240:241], s[66:67], 0, v[132:133]
	global_load_lds_dwordx4 v[240:241], off
	s_add_i32 m0, s59, 0x2000
	v_lshl_add_u64 v[240:241], s[66:67], 0, v[136:137]
	global_load_lds_dwordx4 v[240:241], off
	s_waitcnt vmcnt(8) lgkmcnt(0)
	s_barrier
	v_mfma_f32_16x16x32_bf16 v[60:63], v[144:147], v[170:173], v[60:63]
	v_mfma_f32_16x16x32_bf16 v[56:59], v[162:165], v[170:173], v[56:59]
	v_mfma_f32_16x16x32_bf16 v[52:55], v[144:147], v[178:181], v[52:55]
	v_mfma_f32_16x16x32_bf16 v[44:47], v[162:165], v[178:181], v[44:47]
	v_mfma_f32_16x16x32_bf16 v[36:39], v[144:147], v[186:189], v[36:39]
	v_mfma_f32_16x16x32_bf16 v[28:31], v[162:165], v[186:189], v[28:31]
	v_mfma_f32_16x16x32_bf16 v[20:23], v[144:147], v[194:197], v[20:23]
	v_mfma_f32_16x16x32_bf16 v[12:15], v[162:165], v[194:197], v[12:15]
	v_mfma_f32_16x16x32_bf16 v[60:63], v[148:151], v[174:177], v[60:63]
	v_mfma_f32_16x16x32_bf16 v[56:59], v[166:169], v[174:177], v[56:59]
	v_mfma_f32_16x16x32_bf16 v[52:55], v[148:151], v[182:185], v[52:55]
	v_mfma_f32_16x16x32_bf16 v[44:47], v[166:169], v[182:185], v[44:47]
	v_mfma_f32_16x16x32_bf16 v[36:39], v[148:151], v[190:193], v[36:39]
	v_mfma_f32_16x16x32_bf16 v[28:31], v[166:169], v[190:193], v[28:31]
	v_mfma_f32_16x16x32_bf16 v[20:23], v[148:151], v[198:201], v[20:23]
	v_mfma_f32_16x16x32_bf16 v[12:15], v[166:169], v[198:201], v[12:15]
	v_mfma_f32_16x16x32_bf16 v[48:51], v[202:205], v[170:173], v[48:51]
	v_mfma_f32_16x16x32_bf16 v[40:43], v[210:213], v[170:173], v[40:43]
	v_mfma_f32_16x16x32_bf16 v[32:35], v[202:205], v[178:181], v[32:35]
	v_mfma_f32_16x16x32_bf16 v[24:27], v[210:213], v[178:181], v[24:27]
	v_mfma_f32_16x16x32_bf16 v[16:19], v[202:205], v[186:189], v[16:19]
	v_mfma_f32_16x16x32_bf16 v[8:11], v[210:213], v[186:189], v[8:11]
	v_mfma_f32_16x16x32_bf16 v[4:7], v[202:205], v[194:197], v[4:7]
	v_mfma_f32_16x16x32_bf16 v[0:3], v[210:213], v[194:197], v[0:3]
	v_mfma_f32_16x16x32_bf16 v[48:51], v[206:209], v[174:177], v[48:51]
	v_mfma_f32_16x16x32_bf16 v[40:43], v[214:217], v[174:177], v[40:43]
	v_mfma_f32_16x16x32_bf16 v[32:35], v[206:209], v[182:185], v[32:35]
	v_mfma_f32_16x16x32_bf16 v[24:27], v[214:217], v[182:185], v[24:27]
	v_mfma_f32_16x16x32_bf16 v[16:19], v[206:209], v[190:193], v[16:19]
	v_mfma_f32_16x16x32_bf16 v[8:11], v[214:217], v[190:193], v[8:11]
	v_mfma_f32_16x16x32_bf16 v[4:7], v[206:209], v[198:201], v[4:7]
	v_mfma_f32_16x16x32_bf16 v[0:3], v[214:217], v[198:201], v[0:3]
	s_add_u32 s64, s64, 0x100
	s_addc_u32 s65, s65, 0
	s_add_u32 s31, s31, 0x100
	s_addc_u32 s57, s57, 0
	s_cmp_ge_i32 s85, s84
	s_mov_b32 s59, s85
	s_barrier
	s_cbranch_scc0 .LBB0_456
;     __device__ __forceinline__ void operator()(const f32x4 (&acc)[2][2][4][2], const Unit& u, int wr, int wc, int fr, int fq) const {
;     ...
;         if (u.part) {
;             float* base = tailacc + (size_t)(u.part - 1) * slab - (size_t)tail_row0 * tail_ld;
; #pragma unroll
;             for (int ai = 0; ai < 2; ++ai)
; #pragma unroll
;                 for (int m = 0; m < 4; ++m) { float* rowp = base + (size_t)(row0 + ai * HALF + m * 16) * tail_ld + col0;
; #pragma unroll
;                     for (int bj = 0; bj < 2; ++bj)
; #pragma unroll
;                         for (int n = 0; n < 2; ++n) *(f32x4*)(rowp + bj * HALF + 4 * n) = acc[ai][bj][m][n]; }
	v_lshl_add_u32 v152, s8, 8, v155
	v_lshl_or_b32 v144, s30, 8, v157
	v_or_b32_e32 v150, 16, v152
	v_or_b32_e32 v148, 32, v152
	v_or_b32_e32 v146, 48, v152
	s_cmp_lg_u32 s81, 0
	v_ashrrev_i32_e32 v145, 31, v144
	v_ashrrev_i32_e32 v153, 31, v152
	v_ashrrev_i32_e32 v151, 31, v150
	v_ashrrev_i32_e32 v149, 31, v148
	v_ashrrev_i32_e32 v147, 31, v146
	s_cbranch_scc0 .LBB0_459
	s_add_i32 s8, s81, -1
	s_lshl_b64 s[30:31], s[8:9], 21
	s_add_u32 s30, s4, s30
	s_addc_u32 s31, s5, s31
	v_lshl_add_u64 v[162:163], v[144:145], 2, s[30:31]
	s_brev_b32 s30, 63
	s_mov_b32 s31, -1
	v_lshl_add_u64 v[162:163], v[162:163], 0, s[30:31]
	v_lshlrev_b64 v[164:165], 12, v[152:153]
	v_lshlrev_b64 v[166:167], 12, v[150:151]
	v_lshl_add_u64 v[164:165], v[162:163], 0, v[164:165]
	v_lshl_add_u64 v[166:167], v[162:163], 0, v[166:167]
	global_store_dwordx4 v[164:165], v[124:127], off
	global_store_dwordx4 v[164:165], v[120:123], off offset:16
	global_store_dwordx4 v[164:165], v[112:115], off offset:512
	global_store_dwordx4 v[164:165], v[104:107], off offset:528
	global_store_dwordx4 v[166:167], v[116:119], off
	global_store_dwordx4 v[166:167], v[108:111], off offset:16
	global_store_dwordx4 v[166:167], v[96:99], off offset:512
	global_store_dwordx4 v[166:167], v[88:91], off offset:528
	v_lshlrev_b64 v[166:167], 12, v[148:149]
	v_lshl_add_u64 v[166:167], v[162:163], 0, v[166:167]
	global_store_dwordx4 v[166:167], v[100:103], off
	global_store_dwordx4 v[166:167], v[92:95], off offset:16
	global_store_dwordx4 v[166:167], v[80:83], off offset:512
	global_store_dwordx4 v[166:167], v[72:75], off offset:528
	v_lshlrev_b64 v[166:167], 12, v[146:147]
	s_mov_b32 s8, 0x80000
	v_lshl_add_u64 v[162:163], v[162:163], 0, v[166:167]
	v_add_co_u32_e32 v166, vcc, s8, v164
	s_mov_b64 s[30:31], 0x80000
	s_nop 0
	v_addc_co_u32_e32 v167, vcc, 0, v165, vcc
	s_mov_b32 s8, 0x90000
	global_store_dwordx4 v[162:163], v[84:87], off
	global_store_dwordx4 v[162:163], v[76:79], off offset:16
	global_store_dwordx4 v[162:163], v[68:71], off offset:512
	global_store_dwordx4 v[162:163], v[64:67], off offset:528
	v_lshl_add_u64 v[162:163], v[164:165], 0, s[30:31]
	global_store_dwordx4 v[166:167], v[60:63], off
	global_store_dwordx4 v[162:163], v[56:59], off offset:16
	global_store_dwordx4 v[162:163], v[48:51], off offset:512
	global_store_dwordx4 v[162:163], v[40:43], off offset:528
	v_add_co_u32_e32 v166, vcc, s8, v164
	s_mov_b64 s[30:31], 0x90000
	s_nop 0
	v_addc_co_u32_e32 v167, vcc, 0, v165, vcc
	s_mov_b32 s8, 0xa0000
	v_lshl_add_u64 v[162:163], v[164:165], 0, s[30:31]
	global_store_dwordx4 v[166:167], v[52:55], off
	global_store_dwordx4 v[162:163], v[44:47], off offset:16
	global_store_dwordx4 v[162:163], v[32:35], off offset:512
	global_store_dwordx4 v[162:163], v[24:27], off offset:528
	s_mov_b64 s[30:31], 0xa0000
	v_add_co_u32_e32 v166, vcc, s8, v164
	v_lshl_add_u64 v[162:163], v[164:165], 0, s[30:31]
	s_nop 0
	v_addc_co_u32_e32 v167, vcc, 0, v165, vcc
	s_mov_b64 s[30:31], 0xb0000
	global_store_dwordx4 v[166:167], v[36:39], off
	global_store_dwordx4 v[162:163], v[28:31], off offset:16
	global_store_dwordx4 v[162:163], v[16:19], off offset:512
	global_store_dwordx4 v[162:163], v[8:11], off offset:528
	v_lshl_add_u64 v[162:163], v[164:165], 0, s[30:31]
	v_add_co_u32_e32 v164, vcc, 0xb0000, v164
	s_nop 1
	v_addc_co_u32_e32 v165, vcc, 0, v165, vcc
	global_store_dwordx4 v[164:165], v[20:23], off
	global_store_dwordx4 v[162:163], v[12:15], off offset:16
	global_store_dwordx4 v[162:163], v[4:7], off offset:512
	global_store_dwordx4 v[162:163], v[0:3], off offset:528
	s_cbranch_execnz .LBB0_441
	s_branch .LBB0_440

; #define PG8_STAGE(bufoff, gbase, voff) do { _Pragma("unroll") for (int _i = 0; _i < 2; ++_i) \
;         __builtin_amdgcn_global_load_lds((const unsigned*)((const char*)(gbase) + (voff)[_i]), (LAS unsigned*)(lds + (bufoff) + ldsw + _i * 8192), 16, 0, 0); } while (0)
; #define PG8_LDA(dst, b, h) do { _Pragma("unroll") for (int m = 0; m < 4; ++m) _Pragma("unroll") for (int k = 0; k < 2; ++k) dst[m][k] = *(const LAS bf16x8*)(lds + PG8_SA(b, h) + aoff + m * 2048 + k * 1024); } while (0)
; #define PG8_LDB(dst, b, h) do { _Pragma("unroll") for (int n = 0; n < 2; ++n) _Pragma("unroll") for (int k = 0; k < 2; ++k) dst[n][k] = *(const LAS bf16x8*)(lds + PG8_SB(b, h) + boff + n * 2048 + k * 1024); } while (0)
; #define PG8_WAIT_V(n) asm volatile("s_waitcnt vmcnt(" #n ")" ::: "memory")
; #define PG8_WAIT_L(n) asm volatile("s_waitcnt lgkmcnt(" #n ")" ::: "memory")
; #define PG8_BAR __builtin_amdgcn_s_barrier()
; #define PG8_SCHED __builtin_amdgcn_sched_barrier(0)
; template <class Epi>
; __device__ __forceinline__ void gemm_phase(LAS unsigned char* lds, const Gemm g, const StaticOrder& S, const Epi& E) {
;     ...
;         const bool has_next = S.next(ui + 1, nxt);
;         const char* nA = has_next ? (const char*)g.A + (size_t)nxt.pm * tstepA + (size_t)nxt.kt0 * kstep : cA; const char* nB = has_next ? (const char*)g.Bt + (size_t)nxt.pn * tstepB + (size_t)nxt.kt0 * kstep : cB;
;         const int nt = cur.nkt;
;         for (int t = 0; t < nt; t += 2) {
;             const bool last = (t == nt - 2);
;             const char* a1 = cA + (size_t)(t + 1) * kstep;
;             const char* a2 = last ? nA : cA + (size_t)(t + 2) * kstep; const char* b2 = last ? nB : cB + (size_t)(t + 2) * kstep;
;             const char* a3 = a2 + kstep; const char* b3 = b2 + kstep;
;             PG8_LDB(B0, 0, 0); PG8_SCHED; PG8_LDA(At, 0, 0); PG8_STAGE(PG8_SA(1, 1), a1 + hstepA, voffA);
;             PG8_WAIT_L(8); PG8_BAR; PG8_WAIT_L(0); PG8_MMA(0, 0, At, B0); PG8_BAR; PG8_SCHED;
;             PG8_LDB(B1, 0, 1); PG8_STAGE(PG8_SB(0, 0), b2, voffB);
;             PG8_BAR; PG8_WAIT_L(0); PG8_MMA(0, 1, At, B1); PG8_BAR;
;             PG8_LDA(At, 0, 1); PG8_STAGE(PG8_SA(0, 0), a2, voffA);
;             PG8_BAR; PG8_WAIT_L(0); PG8_MMA(1, 0, At, B0); PG8_BAR; PG8_SCHED;
;             PG8_STAGE(PG8_SB(0, 1), b2 + hstepB, voffB);
;             PG8_WAIT_V(6); PG8_BAR; PG8_MMA(1, 1, At, B1); PG8_BAR;
.LBB0_681:
	s_ashr_i32 s39, s38, 31
	v_cmp_lt_i64_e32 vcc, s[40:41], v[148:149]
	s_lshl_b64 s[40:41], s[38:39], 19
	s_add_u32 s37, s52, s40
	s_addc_u32 s39, s53, s41
	s_and_b64 s[40:41], vcc, exec
	s_cselect_b32 s41, s39, s61
	s_cselect_b32 s40, s37, s60
	s_ashr_i32 s37, s36, 31
	s_lshl_b64 s[56:57], s[36:37], 19
	s_add_u32 s37, s54, s56
	s_addc_u32 s39, s55, s57
	s_and_b64 s[56:57], vcc, exec
	s_cselect_b32 s57, s39, s63
	s_cselect_b32 s56, s37, s62
	s_add_u32 s60, s60, 0x40080
	s_addc_u32 s61, s61, 0
	s_add_u32 s37, s62, 0x100
	s_addc_u32 s39, s63, 0
	s_mov_b32 s78, -2
	s_add_u32 s62, s60, 0xfffc0080
	s_addc_u32 s63, s61, -1
	s_cmp_eq_u32 s78, 12
	s_cselect_b32 s65, s41, s63
	s_cselect_b32 s64, s40, s62
	s_cselect_b32 s63, s57, s39
	s_cselect_b32 s62, s56, s37
	ds_read_b128 v[152:155], v159
	ds_read_b128 v[162:165], v159 offset:1024
	ds_read_b128 v[166:169], v159 offset:2048
	ds_read_b128 v[170:173], v159 offset:3072
	ds_read_b128 v[174:177], v160
	ds_read_b128 v[178:181], v160 offset:1024
	ds_read_b128 v[182:185], v160 offset:2048
	ds_read_b128 v[186:189], v160 offset:3072
	ds_read_b128 v[190:193], v160 offset:4096
	ds_read_b128 v[194:197], v160 offset:5120
	ds_read_b128 v[198:201], v160 offset:6144
	ds_read_b128 v[202:205], v160 offset:7168
	ds_read_b128 v[206:209], v161
	ds_read_b128 v[210:213], v161 offset:1024
	ds_read_b128 v[214:217], v161 offset:2048
	ds_read_b128 v[218:221], v161 offset:3072
	s_add_i32 m0, s35, 0xc000
	v_lshl_add_u64 v[242:243], s[60:61], 0, v[144:145]
	global_load_lds_dwordx4 v[242:243], off
	s_add_i32 m0, s35, 0xe000
	v_lshl_add_u64 v[242:243], s[60:61], 0, v[146:147]
	global_load_lds_dwordx4 v[242:243], off
	s_waitcnt vmcnt(8) lgkmcnt(0)
	s_barrier
	v_mfma_f32_16x16x32_bf16 v[124:127], v[152:155], v[174:177], 0
	v_mfma_f32_16x16x32_bf16 v[120:123], v[166:169], v[174:177], 0
	v_mfma_f32_16x16x32_bf16 v[116:119], v[152:155], v[182:185], 0
	v_mfma_f32_16x16x32_bf16 v[108:111], v[166:169], v[182:185], 0
	v_mfma_f32_16x16x32_bf16 v[100:103], v[152:155], v[190:193], 0
	v_mfma_f32_16x16x32_bf16 v[92:95], v[166:169], v[190:193], 0
	v_mfma_f32_16x16x32_bf16 v[84:87], v[152:155], v[198:201], 0
	v_mfma_f32_16x16x32_bf16 v[76:79], v[166:169], v[198:201], 0
	v_mfma_f32_16x16x32_bf16 v[124:127], v[162:165], v[178:181], v[124:127]
	v_mfma_f32_16x16x32_bf16 v[120:123], v[170:173], v[178:181], v[120:123]
	v_mfma_f32_16x16x32_bf16 v[116:119], v[162:165], v[186:189], v[116:119]
	v_mfma_f32_16x16x32_bf16 v[108:111], v[170:173], v[186:189], v[108:111]
	v_mfma_f32_16x16x32_bf16 v[100:103], v[162:165], v[194:197], v[100:103]
	v_mfma_f32_16x16x32_bf16 v[92:95], v[170:173], v[194:197], v[92:95]
	v_mfma_f32_16x16x32_bf16 v[84:87], v[162:165], v[202:205], v[84:87]
	v_mfma_f32_16x16x32_bf16 v[76:79], v[170:173], v[202:205], v[76:79]
	v_mfma_f32_16x16x32_bf16 v[112:115], v[206:209], v[174:177], 0
	v_mfma_f32_16x16x32_bf16 v[104:107], v[214:217], v[174:177], 0
	v_mfma_f32_16x16x32_bf16 v[96:99], v[206:209], v[182:185], 0
	v_mfma_f32_16x16x32_bf16 v[88:91], v[214:217], v[182:185], 0
	v_mfma_f32_16x16x32_bf16 v[80:83], v[206:209], v[190:193], 0
	v_mfma_f32_16x16x32_bf16 v[72:75], v[214:217], v[190:193], 0
	v_mfma_f32_16x16x32_bf16 v[68:71], v[206:209], v[198:201], 0
	v_mfma_f32_16x16x32_bf16 v[64:67], v[214:217], v[198:201], 0
	v_mfma_f32_16x16x32_bf16 v[112:115], v[210:213], v[178:181], v[112:115]
	v_mfma_f32_16x16x32_bf16 v[104:107], v[218:221], v[178:181], v[104:107]
	v_mfma_f32_16x16x32_bf16 v[96:99], v[210:213], v[186:189], v[96:99]
	v_mfma_f32_16x16x32_bf16 v[88:91], v[218:221], v[186:189], v[88:91]
	v_mfma_f32_16x16x32_bf16 v[80:83], v[210:213], v[194:197], v[80:83]
	v_mfma_f32_16x16x32_bf16 v[72:75], v[218:221], v[194:197], v[72:75]
	v_mfma_f32_16x16x32_bf16 v[68:71], v[210:213], v[202:205], v[68:71]
	v_mfma_f32_16x16x32_bf16 v[64:67], v[218:221], v[202:205], v[64:67]
	s_barrier
	ds_read_b128 v[174:177], v160 offset:16384
	ds_read_b128 v[178:181], v160 offset:17408
	ds_read_b128 v[182:185], v160 offset:18432
	ds_read_b128 v[186:189], v160 offset:19456
	ds_read_b128 v[190:193], v160 offset:20480
	ds_read_b128 v[194:197], v160 offset:21504
	ds_read_b128 v[198:201], v160 offset:22528
	ds_read_b128 v[202:205], v160 offset:23552
	s_add_i32 s79, s75, s33
	s_mov_b32 m0, s79
	v_lshl_add_u64 v[222:223], s[62:63], 0, v[138:139]
	global_load_lds_dwordx4 v[222:223], off
	s_add_i32 m0, s79, 0x2000
	v_lshl_add_u64 v[224:225], s[62:63], 0, v[142:143]
	global_load_lds_dwordx4 v[224:225], off
	s_mov_b32 m0, s35
	v_lshl_add_u64 v[226:227], s[64:65], 0, v[136:137]
	global_load_lds_dwordx4 v[226:227], off
	s_mov_b32 m0, s66
	v_lshl_add_u64 v[228:229], s[64:65], 0, v[140:141]
	global_load_lds_dwordx4 v[228:229], off
	s_waitcnt vmcnt(6) lgkmcnt(0)
	s_barrier
; #define PG8_STAGE(bufoff, gbase, voff) do { _Pragma("unroll") for (int _i = 0; _i < 2; ++_i) \
;         __builtin_amdgcn_global_load_lds((const unsigned*)((const char*)(gbase) + (voff)[_i]), (LAS unsigned*)(lds + (bufoff) + ldsw + _i * 8192), 16, 0, 0); } while (0)
; #define PG8_LDA(dst, b, h) do { _Pragma("unroll") for (int m = 0; m < 4; ++m) _Pragma("unroll") for (int k = 0; k < 2; ++k) dst[m][k] = *(const LAS bf16x8*)(lds + PG8_SA(b, h) + aoff + m * 2048 + k * 1024); } while (0)
; #define PG8_LDB(dst, b, h) do { _Pragma("unroll") for (int n = 0; n < 2; ++n) _Pragma("unroll") for (int k = 0; k < 2; ++k) dst[n][k] = *(const LAS bf16x8*)(lds + PG8_SB(b, h) + boff + n * 2048 + k * 1024); } while (0)
; #define PG8_MMA(ai, bj, At, Bt) do { __builtin_amdgcn_s_setprio(1); _Pragma("unroll") for (int m = 0; m < 4; ++m) _Pragma("unroll") for (int n = 0; n < 2; ++n) _Pragma("unroll") for (int k = 0; k < 2; ++k) \
;         acc[ai][bj][m][n] = __builtin_amdgcn_mfma_f32_16x16x32_bf16(Bt[n][k], At[m][k], acc[ai][bj][m][n], 0, 0, 0); __builtin_amdgcn_s_setprio(0); } while (0)
; #define PG8_WAIT_V(n) asm volatile("s_waitcnt vmcnt(" #n ")" ::: "memory")
; #define PG8_WAIT_L(n) asm volatile("s_waitcnt lgkmcnt(" #n ")" ::: "memory")
; #define PG8_BAR __builtin_amdgcn_s_barrier()
; #define PG8_SCHED __builtin_amdgcn_sched_barrier(0)
; template <class Epi>
; __device__ __forceinline__ void gemm_phase(LAS unsigned char* lds, const Gemm g, const StaticOrder& S, const Epi& E) {
;     ...
;             PG8_BAR; PG8_WAIT_L(0); PG8_MMA(1, 0, At, B0); PG8_BAR; PG8_SCHED;
;             PG8_STAGE(PG8_SB(0, 1), b2 + hstepB, voffB);
;             PG8_WAIT_V(6); PG8_BAR; PG8_MMA(1, 1, At, B1); PG8_BAR;
;             PG8_LDB(B0, 1, 0); PG8_SCHED; PG8_LDA(At, 1, 0); PG8_STAGE(PG8_SA(0, 1), a2 + hstepA, voffA);
;             PG8_WAIT_L(8); PG8_BAR; PG8_WAIT_L(0); PG8_MMA(0, 0, At, B0); PG8_BAR; PG8_SCHED;
;             PG8_LDB(B1, 1, 1); PG8_STAGE(PG8_SB(1, 0), b3, voffB);
;             PG8_BAR; PG8_WAIT_L(0); PG8_MMA(0, 1, At, B1); PG8_BAR;
	v_mfma_f32_16x16x32_bf16 v[60:63], v[152:155], v[174:177], 0
	v_mfma_f32_16x16x32_bf16 v[56:59], v[166:169], v[174:177], 0
	v_mfma_f32_16x16x32_bf16 v[52:55], v[152:155], v[182:185], 0
	v_mfma_f32_16x16x32_bf16 v[44:47], v[166:169], v[182:185], 0
	v_mfma_f32_16x16x32_bf16 v[36:39], v[152:155], v[190:193], 0
	v_mfma_f32_16x16x32_bf16 v[28:31], v[166:169], v[190:193], 0
	v_mfma_f32_16x16x32_bf16 v[20:23], v[152:155], v[198:201], 0
	v_mfma_f32_16x16x32_bf16 v[12:15], v[166:169], v[198:201], 0
	v_mfma_f32_16x16x32_bf16 v[60:63], v[162:165], v[178:181], v[60:63]
	v_mfma_f32_16x16x32_bf16 v[56:59], v[170:173], v[178:181], v[56:59]
	v_mfma_f32_16x16x32_bf16 v[52:55], v[162:165], v[186:189], v[52:55]
	v_mfma_f32_16x16x32_bf16 v[44:47], v[170:173], v[186:189], v[44:47]
	v_mfma_f32_16x16x32_bf16 v[36:39], v[162:165], v[194:197], v[36:39]
	v_mfma_f32_16x16x32_bf16 v[28:31], v[170:173], v[194:197], v[28:31]
	v_mfma_f32_16x16x32_bf16 v[20:23], v[162:165], v[202:205], v[20:23]
	v_mfma_f32_16x16x32_bf16 v[12:15], v[170:173], v[202:205], v[12:15]
	v_mfma_f32_16x16x32_bf16 v[48:51], v[206:209], v[174:177], 0
	v_mfma_f32_16x16x32_bf16 v[40:43], v[214:217], v[174:177], 0
	v_mfma_f32_16x16x32_bf16 v[32:35], v[206:209], v[182:185], 0
	v_mfma_f32_16x16x32_bf16 v[24:27], v[214:217], v[182:185], 0
	v_mfma_f32_16x16x32_bf16 v[16:19], v[206:209], v[190:193], 0
	v_mfma_f32_16x16x32_bf16 v[8:11], v[214:217], v[190:193], 0
	v_mfma_f32_16x16x32_bf16 v[4:7], v[206:209], v[198:201], 0
	v_mfma_f32_16x16x32_bf16 v[0:3], v[214:217], v[198:201], 0
	v_mfma_f32_16x16x32_bf16 v[48:51], v[210:213], v[178:181], v[48:51]
	v_mfma_f32_16x16x32_bf16 v[40:43], v[218:221], v[178:181], v[40:43]
	v_mfma_f32_16x16x32_bf16 v[32:35], v[210:213], v[186:189], v[32:35]
	v_mfma_f32_16x16x32_bf16 v[24:27], v[218:221], v[186:189], v[24:27]
	v_mfma_f32_16x16x32_bf16 v[16:19], v[210:213], v[194:197], v[16:19]
	v_mfma_f32_16x16x32_bf16 v[8:11], v[218:221], v[194:197], v[8:11]
	v_mfma_f32_16x16x32_bf16 v[4:7], v[210:213], v[202:205], v[4:7]
	v_mfma_f32_16x16x32_bf16 v[0:3], v[218:221], v[202:205], v[0:3]
	s_barrier
	s_add_i32 s79, 0, 0x18000
	v_add_u32_e32 v170, s79, v156
	ds_read_b128 v[152:155], v170
	ds_read_b128 v[162:165], v170 offset:1024
	ds_read_b128 v[166:169], v170 offset:2048
	ds_read_b128 v[170:173], v170 offset:3072
	ds_read_b128 v[174:177], v160 offset:32768
	ds_read_b128 v[178:181], v160 offset:33792
	ds_read_b128 v[182:185], v160 offset:34816
	ds_read_b128 v[186:189], v160 offset:35840
	ds_read_b128 v[190:193], v160 offset:36864
	ds_read_b128 v[194:197], v160 offset:37888
	ds_read_b128 v[198:201], v160 offset:38912
	ds_read_b128 v[202:205], v160 offset:39936
	s_add_i32 s98, 0, 0x1c000
	v_add_u32_e32 v218, s98, v156
	ds_read_b128 v[206:209], v218
	ds_read_b128 v[210:213], v218 offset:1024
	ds_read_b128 v[214:217], v218 offset:2048
	ds_read_b128 v[218:221], v218 offset:3072
	s_add_u32 s100, s62, 0x40000
	s_addc_u32 s101, s63, 0
	s_add_i32 s99, s76, s33
	s_mov_b32 m0, s99
	v_lshl_add_u64 v[240:241], s[100:101], 0, v[138:139]
	global_load_lds_dwordx4 v[240:241], off
	s_add_i32 m0, s99, 0x2000
	v_lshl_add_u64 v[240:241], s[100:101], 0, v[142:143]
	global_load_lds_dwordx4 v[240:241], off
	s_add_u32 s64, s64, 0x40000
	s_addc_u32 s65, s65, 0
	s_mov_b32 m0, s67
	v_lshl_add_u64 v[244:245], s[64:65], 0, v[136:137]
	global_load_lds_dwordx4 v[244:245], off
	s_mov_b32 m0, s68
	v_lshl_add_u64 v[244:245], s[64:65], 0, v[140:141]
	global_load_lds_dwordx4 v[244:245], off
	s_waitcnt vmcnt(8) lgkmcnt(0)
	s_barrier
	v_mfma_f32_16x16x32_bf16 v[124:127], v[152:155], v[174:177], v[124:127]
	v_mfma_f32_16x16x32_bf16 v[120:123], v[166:169], v[174:177], v[120:123]
	v_mfma_f32_16x16x32_bf16 v[116:119], v[152:155], v[182:185], v[116:119]
	v_mfma_f32_16x16x32_bf16 v[108:111], v[166:169], v[182:185], v[108:111]
	v_mfma_f32_16x16x32_bf16 v[100:103], v[152:155], v[190:193], v[100:103]
	v_mfma_f32_16x16x32_bf16 v[92:95], v[166:169], v[190:193], v[92:95]
	v_mfma_f32_16x16x32_bf16 v[84:87], v[152:155], v[198:201], v[84:87]
	v_mfma_f32_16x16x32_bf16 v[76:79], v[166:169], v[198:201], v[76:79]
	v_mfma_f32_16x16x32_bf16 v[124:127], v[162:165], v[178:181], v[124:127]
	v_mfma_f32_16x16x32_bf16 v[120:123], v[170:173], v[178:181], v[120:123]
	v_mfma_f32_16x16x32_bf16 v[116:119], v[162:165], v[186:189], v[116:119]
	v_mfma_f32_16x16x32_bf16 v[108:111], v[170:173], v[186:189], v[108:111]
	v_mfma_f32_16x16x32_bf16 v[100:103], v[162:165], v[194:197], v[100:103]
	v_mfma_f32_16x16x32_bf16 v[92:95], v[170:173], v[194:197], v[92:95]
	v_mfma_f32_16x16x32_bf16 v[84:87], v[162:165], v[202:205], v[84:87]
	v_mfma_f32_16x16x32_bf16 v[76:79], v[170:173], v[202:205], v[76:79]
	v_mfma_f32_16x16x32_bf16 v[112:115], v[206:209], v[174:177], v[112:115]
	v_mfma_f32_16x16x32_bf16 v[104:107], v[214:217], v[174:177], v[104:107]
	v_mfma_f32_16x16x32_bf16 v[96:99], v[206:209], v[182:185], v[96:99]
	v_mfma_f32_16x16x32_bf16 v[88:91], v[214:217], v[182:185], v[88:91]
	v_mfma_f32_16x16x32_bf16 v[80:83], v[206:209], v[190:193], v[80:83]
	v_mfma_f32_16x16x32_bf16 v[72:75], v[214:217], v[190:193], v[72:75]
	v_mfma_f32_16x16x32_bf16 v[68:71], v[206:209], v[198:201], v[68:71]
	v_mfma_f32_16x16x32_bf16 v[64:67], v[214:217], v[198:201], v[64:67]
	v_mfma_f32_16x16x32_bf16 v[112:115], v[210:213], v[178:181], v[112:115]
	v_mfma_f32_16x16x32_bf16 v[104:107], v[218:221], v[178:181], v[104:107]
	v_mfma_f32_16x16x32_bf16 v[96:99], v[210:213], v[186:189], v[96:99]
	v_mfma_f32_16x16x32_bf16 v[88:91], v[218:221], v[186:189], v[88:91]
	v_mfma_f32_16x16x32_bf16 v[80:83], v[210:213], v[194:197], v[80:83]
	v_mfma_f32_16x16x32_bf16 v[72:75], v[218:221], v[194:197], v[72:75]
	v_mfma_f32_16x16x32_bf16 v[68:71], v[210:213], v[202:205], v[68:71]
	v_mfma_f32_16x16x32_bf16 v[64:67], v[218:221], v[202:205], v[64:67]
	s_barrier
; #define PG8_STAGE(bufoff, gbase, voff) do { _Pragma("unroll") for (int _i = 0; _i < 2; ++_i) \
;         __builtin_amdgcn_global_load_lds((const unsigned*)((const char*)(gbase) + (voff)[_i]), (LAS unsigned*)(lds + (bufoff) + ldsw + _i * 8192), 16, 0, 0); } while (0)
; #define PG8_LDA(dst, b, h) do { _Pragma("unroll") for (int m = 0; m < 4; ++m) _Pragma("unroll") for (int k = 0; k < 2; ++k) dst[m][k] = *(const LAS bf16x8*)(lds + PG8_SA(b, h) + aoff + m * 2048 + k * 1024); } while (0)
; #define PG8_LDB(dst, b, h) do { _Pragma("unroll") for (int n = 0; n < 2; ++n) _Pragma("unroll") for (int k = 0; k < 2; ++k) dst[n][k] = *(const LAS bf16x8*)(lds + PG8_SB(b, h) + boff + n * 2048 + k * 1024); } while (0)
; #define PG8_MMA(ai, bj, At, Bt) do { __builtin_amdgcn_s_setprio(1); _Pragma("unroll") for (int m = 0; m < 4; ++m) _Pragma("unroll") for (int n = 0; n < 2; ++n) _Pragma("unroll") for (int k = 0; k < 2; ++k) \
;         acc[ai][bj][m][n] = __builtin_amdgcn_mfma_f32_16x16x32_bf16(Bt[n][k], At[m][k], acc[ai][bj][m][n], 0, 0, 0); __builtin_amdgcn_s_setprio(0); } while (0)
; #define PG8_WAIT_V(n) asm volatile("s_waitcnt vmcnt(" #n ")" ::: "memory")
; #define PG8_WAIT_L(n) asm volatile("s_waitcnt lgkmcnt(" #n ")" ::: "memory")
; #define PG8_BAR __builtin_amdgcn_s_barrier()
; #define PG8_SCHED __builtin_amdgcn_sched_barrier(0)
; template <class Epi>
; __device__ __forceinline__ void gemm_phase(LAS unsigned char* lds, const Gemm g, const StaticOrder& S, const Epi& E) {
;     ...
;             PG8_LDB(B0, 0, 0); PG8_SCHED; PG8_LDA(At, 0, 0); PG8_STAGE(PG8_SA(1, 1), a1 + hstepA, voffA);
;             PG8_WAIT_L(8); PG8_BAR; PG8_WAIT_L(0); PG8_MMA(0, 0, At, B0); PG8_BAR; PG8_SCHED;
;     ...
;             PG8_LDA(At, 1, 1); PG8_STAGE(PG8_SA(1, 0), a3, voffA);
;             PG8_BAR; PG8_WAIT_L(0); PG8_MMA(1, 0, At, B0); PG8_BAR; PG8_SCHED;
;             PG8_STAGE(PG8_SB(1, 1), b3 + hstepB, voffB);
;             PG8_WAIT_V(6); PG8_BAR; PG8_MMA(1, 1, At, B1); PG8_BAR;
	ds_read_b128 v[174:177], v160 offset:49152
	ds_read_b128 v[178:181], v160 offset:50176
	ds_read_b128 v[182:185], v160 offset:51200
	ds_read_b128 v[186:189], v160 offset:52224
	ds_read_b128 v[190:193], v160 offset:53248
	ds_read_b128 v[194:197], v160 offset:54272
	ds_read_b128 v[198:201], v160 offset:55296
	ds_read_b128 v[202:205], v160 offset:56320
	s_add_i32 s65, s79, s33
	s_mov_b32 m0, s65
	v_lshl_add_u64 v[222:223], v[222:223], 0, s[28:29]
	global_load_lds_dwordx4 v[222:223], off
	s_add_i32 m0, s65, 0x2000
	v_lshl_add_u64 v[222:223], v[224:225], 0, s[28:29]
	global_load_lds_dwordx4 v[222:223], off
	s_mov_b32 m0, s71
	v_lshl_add_u64 v[222:223], v[226:227], 0, s[28:29]
	global_load_lds_dwordx4 v[222:223], off
	s_mov_b32 m0, s72
	v_lshl_add_u64 v[222:223], v[228:229], 0, s[28:29]
	global_load_lds_dwordx4 v[222:223], off
	s_add_u32 s62, s62, 0x40080
	s_addc_u32 s63, s63, 0
	s_add_i32 s64, s98, s33
	s_mov_b32 m0, s64
	v_lshl_add_u64 v[240:241], s[62:63], 0, v[138:139]
	global_load_lds_dwordx4 v[240:241], off
	s_add_i32 m0, s64, 0x2000
	v_lshl_add_u64 v[240:241], s[62:63], 0, v[142:143]
	global_load_lds_dwordx4 v[240:241], off
	s_waitcnt vmcnt(8) lgkmcnt(0)
	s_barrier
	v_mfma_f32_16x16x32_bf16 v[60:63], v[152:155], v[174:177], v[60:63]
	v_mfma_f32_16x16x32_bf16 v[56:59], v[166:169], v[174:177], v[56:59]
	v_mfma_f32_16x16x32_bf16 v[52:55], v[152:155], v[182:185], v[52:55]
	v_mfma_f32_16x16x32_bf16 v[44:47], v[166:169], v[182:185], v[44:47]
	v_mfma_f32_16x16x32_bf16 v[36:39], v[152:155], v[190:193], v[36:39]
	v_mfma_f32_16x16x32_bf16 v[28:31], v[166:169], v[190:193], v[28:31]
	v_mfma_f32_16x16x32_bf16 v[20:23], v[152:155], v[198:201], v[20:23]
	v_mfma_f32_16x16x32_bf16 v[12:15], v[166:169], v[198:201], v[12:15]
	v_mfma_f32_16x16x32_bf16 v[60:63], v[162:165], v[178:181], v[60:63]
	v_mfma_f32_16x16x32_bf16 v[56:59], v[170:173], v[178:181], v[56:59]
	v_mfma_f32_16x16x32_bf16 v[52:55], v[162:165], v[186:189], v[52:55]
	v_mfma_f32_16x16x32_bf16 v[44:47], v[170:173], v[186:189], v[44:47]
	v_mfma_f32_16x16x32_bf16 v[36:39], v[162:165], v[194:197], v[36:39]
	v_mfma_f32_16x16x32_bf16 v[28:31], v[170:173], v[194:197], v[28:31]
	v_mfma_f32_16x16x32_bf16 v[20:23], v[162:165], v[202:205], v[20:23]
	v_mfma_f32_16x16x32_bf16 v[12:15], v[170:173], v[202:205], v[12:15]
	v_mfma_f32_16x16x32_bf16 v[48:51], v[206:209], v[174:177], v[48:51]
	v_mfma_f32_16x16x32_bf16 v[40:43], v[214:217], v[174:177], v[40:43]
	v_mfma_f32_16x16x32_bf16 v[32:35], v[206:209], v[182:185], v[32:35]
	v_mfma_f32_16x16x32_bf16 v[24:27], v[214:217], v[182:185], v[24:27]
	v_mfma_f32_16x16x32_bf16 v[16:19], v[206:209], v[190:193], v[16:19]
	v_mfma_f32_16x16x32_bf16 v[8:11], v[214:217], v[190:193], v[8:11]
	v_mfma_f32_16x16x32_bf16 v[4:7], v[206:209], v[198:201], v[4:7]
	v_mfma_f32_16x16x32_bf16 v[0:3], v[214:217], v[198:201], v[0:3]
	v_mfma_f32_16x16x32_bf16 v[48:51], v[210:213], v[178:181], v[48:51]
	v_mfma_f32_16x16x32_bf16 v[40:43], v[218:221], v[178:181], v[40:43]
	v_mfma_f32_16x16x32_bf16 v[32:35], v[210:213], v[186:189], v[32:35]
	v_mfma_f32_16x16x32_bf16 v[24:27], v[218:221], v[186:189], v[24:27]
	v_mfma_f32_16x16x32_bf16 v[16:19], v[210:213], v[194:197], v[16:19]
	v_mfma_f32_16x16x32_bf16 v[8:11], v[218:221], v[194:197], v[8:11]
	v_mfma_f32_16x16x32_bf16 v[4:7], v[210:213], v[202:205], v[4:7]
	v_mfma_f32_16x16x32_bf16 v[0:3], v[218:221], v[202:205], v[0:3]
	s_add_i32 s78, s78, 2
	s_add_u32 s60, s60, 0x100
	s_addc_u32 s61, s61, 0
	s_add_u32 s37, s37, 0x100
	s_addc_u32 s39, s39, 0
	s_cmp_gt_u32 s78, 13
	s_barrier
.LBB0_682:
	s_add_u32 s62, s60, 0xfffc0080
	s_addc_u32 s63, s61, -1
	s_cmp_eq_u32 s78, 12
	s_cselect_b32 s65, s41, s63
	s_cselect_b32 s64, s40, s62
	s_cselect_b32 s63, s57, s39
	s_cselect_b32 s62, s56, s37
	ds_read_b128 v[152:155], v159
	ds_read_b128 v[162:165], v159 offset:1024
	ds_read_b128 v[166:169], v159 offset:2048
	ds_read_b128 v[170:173], v159 offset:3072
	ds_read_b128 v[174:177], v160
	ds_read_b128 v[178:181], v160 offset:1024
	ds_read_b128 v[182:185], v160 offset:2048
	ds_read_b128 v[186:189], v160 offset:3072
	ds_read_b128 v[190:193], v160 offset:4096
	ds_read_b128 v[194:197], v160 offset:5120
	ds_read_b128 v[198:201], v160 offset:6144
	ds_read_b128 v[202:205], v160 offset:7168
	ds_read_b128 v[206:209], v161
	ds_read_b128 v[210:213], v161 offset:1024
	ds_read_b128 v[214:217], v161 offset:2048
	ds_read_b128 v[218:221], v161 offset:3072
	s_add_i32 m0, s35, 0xc000
	v_lshl_add_u64 v[242:243], s[60:61], 0, v[144:145]
	global_load_lds_dwordx4 v[242:243], off
	s_add_i32 m0, s35, 0xe000
	v_lshl_add_u64 v[242:243], s[60:61], 0, v[146:147]
	global_load_lds_dwordx4 v[242:243], off
	s_waitcnt vmcnt(8) lgkmcnt(0)
	s_barrier
; #define PG8_STAGE(bufoff, gbase, voff) do { _Pragma("unroll") for (int _i = 0; _i < 2; ++_i) \
;         __builtin_amdgcn_global_load_lds((const unsigned*)((const char*)(gbase) + (voff)[_i]), (LAS unsigned*)(lds + (bufoff) + ldsw + _i * 8192), 16, 0, 0); } while (0)
; #define PG8_LDA(dst, b, h) do { _Pragma("unroll") for (int m = 0; m < 4; ++m) _Pragma("unroll") for (int k = 0; k < 2; ++k) dst[m][k] = *(const LAS bf16x8*)(lds + PG8_SA(b, h) + aoff + m * 2048 + k * 1024); } while (0)
; #define PG8_LDB(dst, b, h) do { _Pragma("unroll") for (int n = 0; n < 2; ++n) _Pragma("unroll") for (int k = 0; k < 2; ++k) dst[n][k] = *(const LAS bf16x8*)(lds + PG8_SB(b, h) + boff + n * 2048 + k * 1024); } while (0)
; #define PG8_MMA(ai, bj, At, Bt) do { __builtin_amdgcn_s_setprio(1); _Pragma("unroll") for (int m = 0; m < 4; ++m) _Pragma("unroll") for (int n = 0; n < 2; ++n) _Pragma("unroll") for (int k = 0; k < 2; ++k) \
;         acc[ai][bj][m][n] = __builtin_amdgcn_mfma_f32_16x16x32_bf16(Bt[n][k], At[m][k], acc[ai][bj][m][n], 0, 0, 0); __builtin_amdgcn_s_setprio(0); } while (0)
; #define PG8_WAIT_V(n) asm volatile("s_waitcnt vmcnt(" #n ")" ::: "memory")
; #define PG8_WAIT_L(n) asm volatile("s_waitcnt lgkmcnt(" #n ")" ::: "memory")
; #define PG8_BAR __builtin_amdgcn_s_barrier()
; #define PG8_SCHED __builtin_amdgcn_sched_barrier(0)
; template <class Epi>
; __device__ __forceinline__ void gemm_phase(LAS unsigned char* lds, const Gemm g, const StaticOrder& S, const Epi& E) {
;     ...
;             PG8_WAIT_L(8); PG8_BAR; PG8_WAIT_L(0); PG8_MMA(0, 0, At, B0); PG8_BAR; PG8_SCHED;
;             PG8_LDB(B1, 0, 1); PG8_STAGE(PG8_SB(0, 0), b2, voffB);
;             PG8_BAR; PG8_WAIT_L(0); PG8_MMA(0, 1, At, B1); PG8_BAR;
;             PG8_LDA(At, 0, 1); PG8_STAGE(PG8_SA(0, 0), a2, voffA);
;             PG8_BAR; PG8_WAIT_L(0); PG8_MMA(1, 0, At, B0); PG8_BAR; PG8_SCHED;
;             PG8_STAGE(PG8_SB(0, 1), b2 + hstepB, voffB);
;             PG8_WAIT_V(6); PG8_BAR; PG8_MMA(1, 1, At, B1); PG8_BAR;
	v_mfma_f32_16x16x32_bf16 v[124:127], v[152:155], v[174:177], v[124:127]
	v_mfma_f32_16x16x32_bf16 v[120:123], v[166:169], v[174:177], v[120:123]
	v_mfma_f32_16x16x32_bf16 v[116:119], v[152:155], v[182:185], v[116:119]
	v_mfma_f32_16x16x32_bf16 v[108:111], v[166:169], v[182:185], v[108:111]
	v_mfma_f32_16x16x32_bf16 v[100:103], v[152:155], v[190:193], v[100:103]
	v_mfma_f32_16x16x32_bf16 v[92:95], v[166:169], v[190:193], v[92:95]
	v_mfma_f32_16x16x32_bf16 v[84:87], v[152:155], v[198:201], v[84:87]
	v_mfma_f32_16x16x32_bf16 v[76:79], v[166:169], v[198:201], v[76:79]
	v_mfma_f32_16x16x32_bf16 v[124:127], v[162:165], v[178:181], v[124:127]
	v_mfma_f32_16x16x32_bf16 v[120:123], v[170:173], v[178:181], v[120:123]
	v_mfma_f32_16x16x32_bf16 v[116:119], v[162:165], v[186:189], v[116:119]
	v_mfma_f32_16x16x32_bf16 v[108:111], v[170:173], v[186:189], v[108:111]
	v_mfma_f32_16x16x32_bf16 v[100:103], v[162:165], v[194:197], v[100:103]
	v_mfma_f32_16x16x32_bf16 v[92:95], v[170:173], v[194:197], v[92:95]
	v_mfma_f32_16x16x32_bf16 v[84:87], v[162:165], v[202:205], v[84:87]
	v_mfma_f32_16x16x32_bf16 v[76:79], v[170:173], v[202:205], v[76:79]
	v_mfma_f32_16x16x32_bf16 v[112:115], v[206:209], v[174:177], v[112:115]
	v_mfma_f32_16x16x32_bf16 v[104:107], v[214:217], v[174:177], v[104:107]
	v_mfma_f32_16x16x32_bf16 v[96:99], v[206:209], v[182:185], v[96:99]
	v_mfma_f32_16x16x32_bf16 v[88:91], v[214:217], v[182:185], v[88:91]
	v_mfma_f32_16x16x32_bf16 v[80:83], v[206:209], v[190:193], v[80:83]
	v_mfma_f32_16x16x32_bf16 v[72:75], v[214:217], v[190:193], v[72:75]
	v_mfma_f32_16x16x32_bf16 v[68:71], v[206:209], v[198:201], v[68:71]
	v_mfma_f32_16x16x32_bf16 v[64:67], v[214:217], v[198:201], v[64:67]
	v_mfma_f32_16x16x32_bf16 v[112:115], v[210:213], v[178:181], v[112:115]
	v_mfma_f32_16x16x32_bf16 v[104:107], v[218:221], v[178:181], v[104:107]
	v_mfma_f32_16x16x32_bf16 v[96:99], v[210:213], v[186:189], v[96:99]
	v_mfma_f32_16x16x32_bf16 v[88:91], v[218:221], v[186:189], v[88:91]
	v_mfma_f32_16x16x32_bf16 v[80:83], v[210:213], v[194:197], v[80:83]
	v_mfma_f32_16x16x32_bf16 v[72:75], v[218:221], v[194:197], v[72:75]
	v_mfma_f32_16x16x32_bf16 v[68:71], v[210:213], v[202:205], v[68:71]
	v_mfma_f32_16x16x32_bf16 v[64:67], v[218:221], v[202:205], v[64:67]
	s_barrier
	ds_read_b128 v[174:177], v160 offset:16384
	ds_read_b128 v[178:181], v160 offset:17408
	ds_read_b128 v[182:185], v160 offset:18432
	ds_read_b128 v[186:189], v160 offset:19456
	ds_read_b128 v[190:193], v160 offset:20480
	ds_read_b128 v[194:197], v160 offset:21504
	ds_read_b128 v[198:201], v160 offset:22528
	ds_read_b128 v[202:205], v160 offset:23552
	s_add_i32 s79, s75, s33
	s_mov_b32 m0, s79
	v_lshl_add_u64 v[222:223], s[62:63], 0, v[138:139]
	global_load_lds_dwordx4 v[222:223], off
	s_add_i32 m0, s79, 0x2000
	v_lshl_add_u64 v[224:225], s[62:63], 0, v[142:143]
	global_load_lds_dwordx4 v[224:225], off
	s_mov_b32 m0, s35
	v_lshl_add_u64 v[226:227], s[64:65], 0, v[136:137]
	global_load_lds_dwordx4 v[226:227], off
	s_mov_b32 m0, s66
	v_lshl_add_u64 v[228:229], s[64:65], 0, v[140:141]
	global_load_lds_dwordx4 v[228:229], off
	s_waitcnt vmcnt(6) lgkmcnt(0)
	s_barrier
	v_mfma_f32_16x16x32_bf16 v[60:63], v[152:155], v[174:177], v[60:63]
	v_mfma_f32_16x16x32_bf16 v[56:59], v[166:169], v[174:177], v[56:59]
	v_mfma_f32_16x16x32_bf16 v[52:55], v[152:155], v[182:185], v[52:55]
	v_mfma_f32_16x16x32_bf16 v[44:47], v[166:169], v[182:185], v[44:47]
	v_mfma_f32_16x16x32_bf16 v[36:39], v[152:155], v[190:193], v[36:39]
	v_mfma_f32_16x16x32_bf16 v[28:31], v[166:169], v[190:193], v[28:31]
	v_mfma_f32_16x16x32_bf16 v[20:23], v[152:155], v[198:201], v[20:23]
	v_mfma_f32_16x16x32_bf16 v[12:15], v[166:169], v[198:201], v[12:15]
	v_mfma_f32_16x16x32_bf16 v[60:63], v[162:165], v[178:181], v[60:63]
	v_mfma_f32_16x16x32_bf16 v[56:59], v[170:173], v[178:181], v[56:59]
	v_mfma_f32_16x16x32_bf16 v[52:55], v[162:165], v[186:189], v[52:55]
	v_mfma_f32_16x16x32_bf16 v[44:47], v[170:173], v[186:189], v[44:47]
	v_mfma_f32_16x16x32_bf16 v[36:39], v[162:165], v[194:197], v[36:39]
	v_mfma_f32_16x16x32_bf16 v[28:31], v[170:173], v[194:197], v[28:31]
	v_mfma_f32_16x16x32_bf16 v[20:23], v[162:165], v[202:205], v[20:23]
	v_mfma_f32_16x16x32_bf16 v[12:15], v[170:173], v[202:205], v[12:15]
	v_mfma_f32_16x16x32_bf16 v[48:51], v[206:209], v[174:177], v[48:51]
	v_mfma_f32_16x16x32_bf16 v[40:43], v[214:217], v[174:177], v[40:43]
	v_mfma_f32_16x16x32_bf16 v[32:35], v[206:209], v[182:185], v[32:35]
	v_mfma_f32_16x16x32_bf16 v[24:27], v[214:217], v[182:185], v[24:27]
	v_mfma_f32_16x16x32_bf16 v[16:19], v[206:209], v[190:193], v[16:19]
	v_mfma_f32_16x16x32_bf16 v[8:11], v[214:217], v[190:193], v[8:11]
	v_mfma_f32_16x16x32_bf16 v[4:7], v[206:209], v[198:201], v[4:7]
	v_mfma_f32_16x16x32_bf16 v[0:3], v[214:217], v[198:201], v[0:3]
	v_mfma_f32_16x16x32_bf16 v[48:51], v[210:213], v[178:181], v[48:51]
	v_mfma_f32_16x16x32_bf16 v[40:43], v[218:221], v[178:181], v[40:43]
	v_mfma_f32_16x16x32_bf16 v[32:35], v[210:213], v[186:189], v[32:35]
	v_mfma_f32_16x16x32_bf16 v[24:27], v[218:221], v[186:189], v[24:27]
	v_mfma_f32_16x16x32_bf16 v[16:19], v[210:213], v[194:197], v[16:19]
	v_mfma_f32_16x16x32_bf16 v[8:11], v[218:221], v[194:197], v[8:11]
	v_mfma_f32_16x16x32_bf16 v[4:7], v[210:213], v[202:205], v[4:7]
	v_mfma_f32_16x16x32_bf16 v[0:3], v[218:221], v[202:205], v[0:3]
	s_barrier
; #define PG8_STAGE(bufoff, gbase, voff) do { _Pragma("unroll") for (int _i = 0; _i < 2; ++_i) \
;         __builtin_amdgcn_global_load_lds((const unsigned*)((const char*)(gbase) + (voff)[_i]), (LAS unsigned*)(lds + (bufoff) + ldsw + _i * 8192), 16, 0, 0); } while (0)
; #define PG8_LDA(dst, b, h) do { _Pragma("unroll") for (int m = 0; m < 4; ++m) _Pragma("unroll") for (int k = 0; k < 2; ++k) dst[m][k] = *(const LAS bf16x8*)(lds + PG8_SA(b, h) + aoff + m * 2048 + k * 1024); } while (0)
; #define PG8_LDB(dst, b, h) do { _Pragma("unroll") for (int n = 0; n < 2; ++n) _Pragma("unroll") for (int k = 0; k < 2; ++k) dst[n][k] = *(const LAS bf16x8*)(lds + PG8_SB(b, h) + boff + n * 2048 + k * 1024); } while (0)
; #define PG8_MMA(ai, bj, At, Bt) do { __builtin_amdgcn_s_setprio(1); _Pragma("unroll") for (int m = 0; m < 4; ++m) _Pragma("unroll") for (int n = 0; n < 2; ++n) _Pragma("unroll") for (int k = 0; k < 2; ++k) \
;         acc[ai][bj][m][n] = __builtin_amdgcn_mfma_f32_16x16x32_bf16(Bt[n][k], At[m][k], acc[ai][bj][m][n], 0, 0, 0); __builtin_amdgcn_s_setprio(0); } while (0)
; #define PG8_WAIT_V(n) asm volatile("s_waitcnt vmcnt(" #n ")" ::: "memory")
; #define PG8_WAIT_L(n) asm volatile("s_waitcnt lgkmcnt(" #n ")" ::: "memory")
; #define PG8_BAR __builtin_amdgcn_s_barrier()
; #define PG8_SCHED __builtin_amdgcn_sched_barrier(0)
; template <class Epi>
; __device__ __forceinline__ void gemm_phase(LAS unsigned char* lds, const Gemm g, const StaticOrder& S, const Epi& E) {
;     ...
;             PG8_LDB(B0, 1, 0); PG8_SCHED; PG8_LDA(At, 1, 0); PG8_STAGE(PG8_SA(0, 1), a2 + hstepA, voffA);
;             PG8_WAIT_L(8); PG8_BAR; PG8_WAIT_L(0); PG8_MMA(0, 0, At, B0); PG8_BAR; PG8_SCHED;
;             PG8_LDB(B1, 1, 1); PG8_STAGE(PG8_SB(1, 0), b3, voffB);
;             PG8_BAR; PG8_WAIT_L(0); PG8_MMA(0, 1, At, B1); PG8_BAR;
;             PG8_LDA(At, 1, 1); PG8_STAGE(PG8_SA(1, 0), a3, voffA);
;             PG8_BAR; PG8_WAIT_L(0); PG8_MMA(1, 0, At, B0); PG8_BAR; PG8_SCHED;
;             PG8_STAGE(PG8_SB(1, 1), b3 + hstepB, voffB);
;             PG8_WAIT_V(6); PG8_BAR; PG8_MMA(1, 1, At, B1); PG8_BAR;
	s_add_i32 s79, 0, 0x18000
	v_add_u32_e32 v170, s79, v156
	ds_read_b128 v[152:155], v170
	ds_read_b128 v[162:165], v170 offset:1024
	ds_read_b128 v[166:169], v170 offset:2048
	ds_read_b128 v[170:173], v170 offset:3072
	ds_read_b128 v[174:177], v160 offset:32768
	ds_read_b128 v[178:181], v160 offset:33792
	ds_read_b128 v[182:185], v160 offset:34816
	ds_read_b128 v[186:189], v160 offset:35840
	ds_read_b128 v[190:193], v160 offset:36864
	ds_read_b128 v[194:197], v160 offset:37888
	ds_read_b128 v[198:201], v160 offset:38912
	ds_read_b128 v[202:205], v160 offset:39936
	s_add_i32 s98, 0, 0x1c000
	v_add_u32_e32 v218, s98, v156
	ds_read_b128 v[206:209], v218
	ds_read_b128 v[210:213], v218 offset:1024
	ds_read_b128 v[214:217], v218 offset:2048
	ds_read_b128 v[218:221], v218 offset:3072
	s_add_u32 s100, s62, 0x40000
	s_addc_u32 s101, s63, 0
	s_add_i32 s99, s76, s33
	s_mov_b32 m0, s99
	v_lshl_add_u64 v[240:241], s[100:101], 0, v[138:139]
	global_load_lds_dwordx4 v[240:241], off
	s_add_i32 m0, s99, 0x2000
	v_lshl_add_u64 v[240:241], s[100:101], 0, v[142:143]
	global_load_lds_dwordx4 v[240:241], off
	s_add_u32 s64, s64, 0x40000
	s_addc_u32 s65, s65, 0
	s_mov_b32 m0, s67
	v_lshl_add_u64 v[244:245], s[64:65], 0, v[136:137]
	global_load_lds_dwordx4 v[244:245], off
	s_mov_b32 m0, s68
	v_lshl_add_u64 v[244:245], s[64:65], 0, v[140:141]
	global_load_lds_dwordx4 v[244:245], off
	s_waitcnt vmcnt(8) lgkmcnt(0)
	s_barrier
	v_mfma_f32_16x16x32_bf16 v[124:127], v[152:155], v[174:177], v[124:127]
	v_mfma_f32_16x16x32_bf16 v[120:123], v[166:169], v[174:177], v[120:123]
	v_mfma_f32_16x16x32_bf16 v[116:119], v[152:155], v[182:185], v[116:119]
	v_mfma_f32_16x16x32_bf16 v[108:111], v[166:169], v[182:185], v[108:111]
	v_mfma_f32_16x16x32_bf16 v[100:103], v[152:155], v[190:193], v[100:103]
	v_mfma_f32_16x16x32_bf16 v[92:95], v[166:169], v[190:193], v[92:95]
	v_mfma_f32_16x16x32_bf16 v[84:87], v[152:155], v[198:201], v[84:87]
	v_mfma_f32_16x16x32_bf16 v[76:79], v[166:169], v[198:201], v[76:79]
	v_mfma_f32_16x16x32_bf16 v[124:127], v[162:165], v[178:181], v[124:127]
	v_mfma_f32_16x16x32_bf16 v[120:123], v[170:173], v[178:181], v[120:123]
	v_mfma_f32_16x16x32_bf16 v[116:119], v[162:165], v[186:189], v[116:119]
	v_mfma_f32_16x16x32_bf16 v[108:111], v[170:173], v[186:189], v[108:111]
	v_mfma_f32_16x16x32_bf16 v[100:103], v[162:165], v[194:197], v[100:103]
	v_mfma_f32_16x16x32_bf16 v[92:95], v[170:173], v[194:197], v[92:95]
	v_mfma_f32_16x16x32_bf16 v[84:87], v[162:165], v[202:205], v[84:87]
	v_mfma_f32_16x16x32_bf16 v[76:79], v[170:173], v[202:205], v[76:79]
	v_mfma_f32_16x16x32_bf16 v[112:115], v[206:209], v[174:177], v[112:115]
	v_mfma_f32_16x16x32_bf16 v[104:107], v[214:217], v[174:177], v[104:107]
	v_mfma_f32_16x16x32_bf16 v[96:99], v[206:209], v[182:185], v[96:99]
	v_mfma_f32_16x16x32_bf16 v[88:91], v[214:217], v[182:185], v[88:91]
	v_mfma_f32_16x16x32_bf16 v[80:83], v[206:209], v[190:193], v[80:83]
	v_mfma_f32_16x16x32_bf16 v[72:75], v[214:217], v[190:193], v[72:75]
	v_mfma_f32_16x16x32_bf16 v[68:71], v[206:209], v[198:201], v[68:71]
	v_mfma_f32_16x16x32_bf16 v[64:67], v[214:217], v[198:201], v[64:67]
	v_mfma_f32_16x16x32_bf16 v[112:115], v[210:213], v[178:181], v[112:115]
	v_mfma_f32_16x16x32_bf16 v[104:107], v[218:221], v[178:181], v[104:107]
	v_mfma_f32_16x16x32_bf16 v[96:99], v[210:213], v[186:189], v[96:99]
	v_mfma_f32_16x16x32_bf16 v[88:91], v[218:221], v[186:189], v[88:91]
	v_mfma_f32_16x16x32_bf16 v[80:83], v[210:213], v[194:197], v[80:83]
	v_mfma_f32_16x16x32_bf16 v[72:75], v[218:221], v[194:197], v[72:75]
	v_mfma_f32_16x16x32_bf16 v[68:71], v[210:213], v[202:205], v[68:71]
	v_mfma_f32_16x16x32_bf16 v[64:67], v[218:221], v[202:205], v[64:67]
	s_barrier
	ds_read_b128 v[174:177], v160 offset:49152
	ds_read_b128 v[178:181], v160 offset:50176
	ds_read_b128 v[182:185], v160 offset:51200
	ds_read_b128 v[186:189], v160 offset:52224
	ds_read_b128 v[190:193], v160 offset:53248
	ds_read_b128 v[194:197], v160 offset:54272
	ds_read_b128 v[198:201], v160 offset:55296
	ds_read_b128 v[202:205], v160 offset:56320
	s_add_i32 s65, s79, s33
	s_mov_b32 m0, s65
	v_lshl_add_u64 v[222:223], v[222:223], 0, s[28:29]
	global_load_lds_dwordx4 v[222:223], off
	s_add_i32 m0, s65, 0x2000
	v_lshl_add_u64 v[222:223], v[224:225], 0, s[28:29]
	global_load_lds_dwordx4 v[222:223], off
	s_mov_b32 m0, s71
	v_lshl_add_u64 v[222:223], v[226:227], 0, s[28:29]
	global_load_lds_dwordx4 v[222:223], off
	s_mov_b32 m0, s72
	v_lshl_add_u64 v[222:223], v[228:229], 0, s[28:29]
	global_load_lds_dwordx4 v[222:223], off
	s_add_u32 s62, s62, 0x40080
	s_addc_u32 s63, s63, 0
	s_add_i32 s64, s98, s33
	s_mov_b32 m0, s64
	v_lshl_add_u64 v[240:241], s[62:63], 0, v[138:139]
	global_load_lds_dwordx4 v[240:241], off
	s_add_i32 m0, s64, 0x2000
	v_lshl_add_u64 v[240:241], s[62:63], 0, v[142:143]
	global_load_lds_dwordx4 v[240:241], off
	s_waitcnt vmcnt(8) lgkmcnt(0)
	s_barrier
; __device__ __forceinline__ unsigned pk2(float lo, float hi) { unsigned r; asm("v_cvt_pk_bf16_f32 %0, %1, %2" : "=v"(r) : "v"(lo), "v"(hi)); return r; }
; __device__ __forceinline__ float gelu_t(float x) { return x * __builtin_amdgcn_rcpf(1.f + __expf(-1.5957691216057308f * (x + 0.044715f * x * x * x))); }
; #define PG8_MMA(ai, bj, At, Bt) do { __builtin_amdgcn_s_setprio(1); _Pragma("unroll") for (int m = 0; m < 4; ++m) _Pragma("unroll") for (int n = 0; n < 2; ++n) _Pragma("unroll") for (int k = 0; k < 2; ++k) \
;         acc[ai][bj][m][n] = __builtin_amdgcn_mfma_f32_16x16x32_bf16(Bt[n][k], At[m][k], acc[ai][bj][m][n], 0, 0, 0); __builtin_amdgcn_s_setprio(0); } while (0)
; #define PG8_WAIT_V(n) asm volatile("s_waitcnt vmcnt(" #n ")" ::: "memory")
; #define PG8_BAR __builtin_amdgcn_s_barrier()
;     __device__ __forceinline__ void operator()(const f32x4 (&acc)[2][2][4][2], const Unit& u, int wr, int wc, int fr, int fq) const {
;     ...
;             for (int m = 0; m < 4; ++m) { const int row = row0 + ai * HALF + m * 16; u16* rowp = O + (size_t)row * ldc + col0;
; #pragma unroll
;                 for (int bj = 0; bj < 2; ++bj) { f32x4 v0 = acc[ai][bj][m][0], v1 = acc[ai][bj][m][1];
;                     if (col0 + bj * HALF >= gelu_from) { v0 = (f32x4){gelu_t(v0.x), gelu_t(v0.y), gelu_t(v0.z), gelu_t(v0.w)}; v1 = (f32x4){gelu_t(v1.x), gelu_t(v1.y), gelu_t(v1.z), gelu_t(v1.w)}; }
;                     u32x4 w; w.x = pk2(v0[0], v0[1]); w.y = pk2(v0[2], v0[3]); w.z = pk2(v1[0], v1[1]); w.w = pk2(v1[2], v1[3]);
;                     *(u32x4*)(rowp + bj * HALF) = w;
;                     if (halo != nullptr && m == 3 && fr >= 14) *(u32x4*)(halo + (size_t)((row >> 6) * 2 + (fr - 14)) * ldc + col0 + bj * HALF) = w; } }
; template <class Epi>
; __device__ __forceinline__ void gemm_phase(LAS unsigned char* lds, const Gemm g, const StaticOrder& S, const Epi& E) {
;     ...
;             PG8_WAIT_V(6); PG8_BAR; PG8_MMA(1, 1, At, B1); PG8_BAR;
;         }
;         E(acc, cur, wr, wc, fr, fq);
	v_mfma_f32_16x16x32_bf16 v[60:63], v[152:155], v[174:177], v[60:63]
	v_mfma_f32_16x16x32_bf16 v[56:59], v[166:169], v[174:177], v[56:59]
	v_mfma_f32_16x16x32_bf16 v[52:55], v[152:155], v[182:185], v[52:55]
	v_mfma_f32_16x16x32_bf16 v[44:47], v[166:169], v[182:185], v[44:47]
	v_mfma_f32_16x16x32_bf16 v[36:39], v[152:155], v[190:193], v[36:39]
	v_mfma_f32_16x16x32_bf16 v[28:31], v[166:169], v[190:193], v[28:31]
	v_mfma_f32_16x16x32_bf16 v[20:23], v[152:155], v[198:201], v[20:23]
	v_mfma_f32_16x16x32_bf16 v[12:15], v[166:169], v[198:201], v[12:15]
	v_mfma_f32_16x16x32_bf16 v[60:63], v[162:165], v[178:181], v[60:63]
	v_mfma_f32_16x16x32_bf16 v[56:59], v[170:173], v[178:181], v[56:59]
	v_mfma_f32_16x16x32_bf16 v[52:55], v[162:165], v[186:189], v[52:55]
	v_mfma_f32_16x16x32_bf16 v[44:47], v[170:173], v[186:189], v[44:47]
	v_mfma_f32_16x16x32_bf16 v[36:39], v[162:165], v[194:197], v[36:39]
	v_mfma_f32_16x16x32_bf16 v[28:31], v[170:173], v[194:197], v[28:31]
	v_mfma_f32_16x16x32_bf16 v[20:23], v[162:165], v[202:205], v[20:23]
	v_mfma_f32_16x16x32_bf16 v[12:15], v[170:173], v[202:205], v[12:15]
	v_mfma_f32_16x16x32_bf16 v[48:51], v[206:209], v[174:177], v[48:51]
	v_mfma_f32_16x16x32_bf16 v[40:43], v[214:217], v[174:177], v[40:43]
	v_mfma_f32_16x16x32_bf16 v[32:35], v[206:209], v[182:185], v[32:35]
	v_mfma_f32_16x16x32_bf16 v[24:27], v[214:217], v[182:185], v[24:27]
	v_mfma_f32_16x16x32_bf16 v[16:19], v[206:209], v[190:193], v[16:19]
	v_mfma_f32_16x16x32_bf16 v[8:11], v[214:217], v[190:193], v[8:11]
	v_mfma_f32_16x16x32_bf16 v[4:7], v[206:209], v[198:201], v[4:7]
	v_mfma_f32_16x16x32_bf16 v[0:3], v[214:217], v[198:201], v[0:3]
	v_mfma_f32_16x16x32_bf16 v[48:51], v[210:213], v[178:181], v[48:51]
	v_mfma_f32_16x16x32_bf16 v[40:43], v[218:221], v[178:181], v[40:43]
	v_mfma_f32_16x16x32_bf16 v[32:35], v[210:213], v[186:189], v[32:35]
	v_mfma_f32_16x16x32_bf16 v[24:27], v[218:221], v[186:189], v[24:27]
	v_mfma_f32_16x16x32_bf16 v[16:19], v[210:213], v[194:197], v[16:19]
	v_mfma_f32_16x16x32_bf16 v[8:11], v[218:221], v[194:197], v[8:11]
	v_mfma_f32_16x16x32_bf16 v[4:7], v[210:213], v[202:205], v[4:7]
	v_mfma_f32_16x16x32_bf16 v[0:3], v[218:221], v[202:205], v[0:3]
	s_add_i32 s78, s78, 2
	s_add_u32 s60, s60, 0x100
	s_addc_u32 s61, s61, 0
	s_add_u32 s37, s37, 0x100
	s_addc_u32 s39, s39, 0
	s_cmp_gt_u32 s78, 13
	s_barrier
	s_cbranch_scc0 .LBB0_682
	s_lshl_b32 s37, s58, 8
	s_add_i32 s37, s37, s70
	v_lshl_or_b32 v152, s59, 8, v158
	v_or_b32_e32 v162, s37, v135
	v_ashrrev_i32_e32 v153, 31, v152
	v_mov_b64_e32 v[164:165], s[4:5]
	v_mad_i64_i32 v[166:167], s[58:59], v162, s77, v[164:165]
	v_lshlrev_b64 v[154:155], 1, v[152:153]
	v_cvt_pk_bf16_f32 v112, v112, v113
	v_cvt_pk_bf16_f32 v113, v114, v115
	v_cvt_pk_bf16_f32 v114, v104, v105
	v_or_b32_e32 v104, 16, v162
	v_lshl_add_u64 v[166:167], v[166:167], 0, v[154:155]
	v_mad_i64_i32 v[104:105], s[58:59], v104, s77, v[164:165]
	v_cvt_pk_bf16_f32 v96, v96, v97
	v_cvt_pk_bf16_f32 v97, v98, v99
	v_cvt_pk_bf16_f32 v98, v88, v89
	v_or_b32_e32 v88, 32, v162
	v_cvt_pk_bf16_f32 v115, v106, v107
	global_store_dwordx4 v[166:167], v[112:115], off offset:256
	v_mad_i64_i32 v[88:89], s[58:59], v88, s77, v[164:165]
	s_nop 0
	v_lshl_add_u64 v[112:113], v[104:105], 0, v[154:155]
	v_cvt_pk_bf16_f32 v80, v80, v81
	v_cvt_pk_bf16_f32 v81, v82, v83
	v_cvt_pk_bf16_f32 v82, v72, v73
	v_or_b32_e32 v72, 48, v162
	s_ashr_i32 s37, s37, 5
	v_cvt_pk_bf16_f32 v99, v90, v91
	global_store_dwordx4 v[112:113], v[96:99], off offset:256
	v_mad_i64_i32 v[72:73], s[58:59], v72, s77, v[164:165]
	s_nop 0
	v_lshl_add_u64 v[96:97], v[88:89], 0, v[154:155]
	v_add_u32_e32 v163, s37, v157
	v_cvt_pk_bf16_f32 v83, v74, v75
	global_store_dwordx4 v[96:97], v[80:83], off offset:256
	v_cvt_pk_bf16_f32 v124, v124, v125
	v_cvt_pk_bf16_f32 v125, v126, v127
	v_cvt_pk_bf16_f32 v126, v120, v121
	v_cvt_pk_bf16_f32 v127, v122, v123
	global_store_dwordx4 v[166:167], v[124:127], off
	s_nop 0
	v_lshl_add_u64 v[80:81], v[72:73], 0, v[154:155]
	v_cvt_pk_bf16_f32 v104, v116, v117
	v_cvt_pk_bf16_f32 v105, v118, v119
	v_cvt_pk_bf16_f32 v106, v108, v109
	v_cvt_pk_bf16_f32 v107, v110, v111
	global_store_dwordx4 v[112:113], v[104:107], off
	v_cvt_pk_bf16_f32 v88, v100, v101
	v_cvt_pk_bf16_f32 v89, v102, v103
	v_cvt_pk_bf16_f32 v90, v92, v93
	v_cvt_pk_bf16_f32 v91, v94, v95
	global_store_dwordx4 v[96:97], v[88:91], off
	v_cvt_pk_bf16_f32 v72, v84, v85
	v_cvt_pk_bf16_f32 v73, v86, v87
	v_cvt_pk_bf16_f32 v74, v76, v77
	v_cvt_pk_bf16_f32 v75, v78, v79
	global_store_dwordx4 v[80:81], v[72:75], off
	s_and_saveexec_b64 s[58:59], s[0:1]
	s_cbranch_execz .LBB0_685
	v_mov_b64_e32 v[76:77], s[18:19]
	v_mad_i64_i32 v[76:77], s[60:61], v163, s77, v[76:77]
	v_lshl_add_u64 v[76:77], v[152:153], 1, v[76:77]
	global_store_dwordx4 v[76:77], v[72:75], off

; #define PG8_STAGE(bufoff, gbase, voff) do { _Pragma("unroll") for (int _i = 0; _i < 2; ++_i) \
;         __builtin_amdgcn_global_load_lds((const unsigned*)((const char*)(gbase) + (voff)[_i]), (LAS unsigned*)(lds + (bufoff) + ldsw + _i * 8192), 16, 0, 0); } while (0)
; #define PG8_LDA(dst, b, h) do { _Pragma("unroll") for (int m = 0; m < 4; ++m) _Pragma("unroll") for (int k = 0; k < 2; ++k) dst[m][k] = *(const LAS bf16x8*)(lds + PG8_SA(b, h) + aoff + m * 2048 + k * 1024); } while (0)
; #define PG8_LDB(dst, b, h) do { _Pragma("unroll") for (int n = 0; n < 2; ++n) _Pragma("unroll") for (int k = 0; k < 2; ++k) dst[n][k] = *(const LAS bf16x8*)(lds + PG8_SB(b, h) + boff + n * 2048 + k * 1024); } while (0)
; #define PG8_WAIT_V(n) asm volatile("s_waitcnt vmcnt(" #n ")" ::: "memory")
; #define PG8_WAIT_L(n) asm volatile("s_waitcnt lgkmcnt(" #n ")" ::: "memory")
; #define PG8_BAR __builtin_amdgcn_s_barrier()
; #define PG8_SCHED __builtin_amdgcn_sched_barrier(0)
; template <class Epi>
; __device__ __forceinline__ void gemm_phase(LAS unsigned char* lds, const Gemm g, const StaticOrder& S, const Epi& E) {
;     ...
;         const bool has_next = S.next(ui + 1, nxt);
;         const char* nA = has_next ? (const char*)g.A + (size_t)nxt.pm * tstepA + (size_t)nxt.kt0 * kstep : cA; const char* nB = has_next ? (const char*)g.Bt + (size_t)nxt.pn * tstepB + (size_t)nxt.kt0 * kstep : cB;
;         const int nt = cur.nkt;
;         for (int t = 0; t < nt; t += 2) {
;             const bool last = (t == nt - 2);
;             const char* a1 = cA + (size_t)(t + 1) * kstep;
;             const char* a2 = last ? nA : cA + (size_t)(t + 2) * kstep; const char* b2 = last ? nB : cB + (size_t)(t + 2) * kstep;
;             const char* a3 = a2 + kstep; const char* b3 = b2 + kstep;
;             PG8_LDB(B0, 0, 0); PG8_SCHED; PG8_LDA(At, 0, 0); PG8_STAGE(PG8_SA(1, 1), a1 + hstepA, voffA);
;             PG8_WAIT_L(8); PG8_BAR; PG8_WAIT_L(0); PG8_MMA(0, 0, At, B0); PG8_BAR; PG8_SCHED;
;             PG8_LDB(B1, 0, 1); PG8_STAGE(PG8_SB(0, 0), b2, voffB);
;             PG8_BAR; PG8_WAIT_L(0); PG8_MMA(0, 1, At, B1); PG8_BAR;
;             PG8_LDA(At, 0, 1); PG8_STAGE(PG8_SA(0, 0), a2, voffA);
;             PG8_BAR; PG8_WAIT_L(0); PG8_MMA(1, 0, At, B0); PG8_BAR; PG8_SCHED;
;             PG8_STAGE(PG8_SB(0, 1), b2 + hstepB, voffB);
;             PG8_WAIT_V(6); PG8_BAR; PG8_MMA(1, 1, At, B1); PG8_BAR;
.LBB0_909:
	s_add_i32 s18, s81, -2
	s_add_u32 s46, s46, 0x160080
	s_addc_u32 s47, s47, 0
	s_add_u32 s41, s54, 0x100
	s_addc_u32 s82, s55, 0
	s_mov_b32 s54, 0
	s_add_i32 s83, s54, 2
	s_add_u32 s55, s46, 0xffea0080
	s_addc_u32 s56, s47, -1
	s_cmp_eq_u32 s18, s54
	s_cselect_b32 s54, s0, s41
	s_cselect_b32 s57, s45, s56
	s_cselect_b32 s56, s44, s55
	s_cselect_b32 s55, s1, s82
	ds_read_b128 v[150:153], v170
	ds_read_b128 v[154:157], v170 offset:1024
	ds_read_b128 v[174:177], v170 offset:2048
	ds_read_b128 v[178:181], v170 offset:3072
	ds_read_b128 v[182:185], v171
	ds_read_b128 v[186:189], v171 offset:1024
	ds_read_b128 v[190:193], v171 offset:2048
	ds_read_b128 v[194:197], v171 offset:3072
	ds_read_b128 v[198:201], v171 offset:4096
	ds_read_b128 v[202:205], v171 offset:5120
	ds_read_b128 v[206:209], v171 offset:6144
	ds_read_b128 v[210:213], v171 offset:7168
	ds_read_b128 v[214:217], v172
	ds_read_b128 v[218:221], v172 offset:1024
	ds_read_b128 v[222:225], v172 offset:2048
	ds_read_b128 v[226:229], v172 offset:3072
	s_add_i32 m0, s33, 0xc000
	v_lshl_add_u64 v[158:159], s[46:47], 0, v[144:145]
	global_load_lds_dwordx4 v[158:159], off
	s_add_i32 m0, s33, 0xe000
	v_lshl_add_u64 v[158:159], s[46:47], 0, v[146:147]
	global_load_lds_dwordx4 v[158:159], off
	s_waitcnt vmcnt(8) lgkmcnt(0)
	s_barrier
	v_mfma_f32_16x16x32_bf16 v[124:127], v[150:153], v[182:185], 0
	v_mfma_f32_16x16x32_bf16 v[120:123], v[174:177], v[182:185], 0
	v_mfma_f32_16x16x32_bf16 v[116:119], v[150:153], v[190:193], 0
	v_mfma_f32_16x16x32_bf16 v[108:111], v[174:177], v[190:193], 0
	v_mfma_f32_16x16x32_bf16 v[100:103], v[150:153], v[198:201], 0
	v_mfma_f32_16x16x32_bf16 v[92:95], v[174:177], v[198:201], 0
	v_mfma_f32_16x16x32_bf16 v[84:87], v[150:153], v[206:209], 0
	v_mfma_f32_16x16x32_bf16 v[76:79], v[174:177], v[206:209], 0
	v_mfma_f32_16x16x32_bf16 v[124:127], v[154:157], v[186:189], v[124:127]
	v_mfma_f32_16x16x32_bf16 v[120:123], v[178:181], v[186:189], v[120:123]
	v_mfma_f32_16x16x32_bf16 v[116:119], v[154:157], v[194:197], v[116:119]
	v_mfma_f32_16x16x32_bf16 v[108:111], v[178:181], v[194:197], v[108:111]
	v_mfma_f32_16x16x32_bf16 v[100:103], v[154:157], v[202:205], v[100:103]
	v_mfma_f32_16x16x32_bf16 v[92:95], v[178:181], v[202:205], v[92:95]
	v_mfma_f32_16x16x32_bf16 v[84:87], v[154:157], v[210:213], v[84:87]
	v_mfma_f32_16x16x32_bf16 v[76:79], v[178:181], v[210:213], v[76:79]
	v_mfma_f32_16x16x32_bf16 v[112:115], v[214:217], v[182:185], 0
	v_mfma_f32_16x16x32_bf16 v[104:107], v[222:225], v[182:185], 0
	v_mfma_f32_16x16x32_bf16 v[96:99], v[214:217], v[190:193], 0
	v_mfma_f32_16x16x32_bf16 v[88:91], v[222:225], v[190:193], 0
	v_mfma_f32_16x16x32_bf16 v[80:83], v[214:217], v[198:201], 0
	v_mfma_f32_16x16x32_bf16 v[72:75], v[222:225], v[198:201], 0
	v_mfma_f32_16x16x32_bf16 v[68:71], v[214:217], v[206:209], 0
	v_mfma_f32_16x16x32_bf16 v[64:67], v[222:225], v[206:209], 0
	v_mfma_f32_16x16x32_bf16 v[112:115], v[218:221], v[186:189], v[112:115]
	v_mfma_f32_16x16x32_bf16 v[104:107], v[226:229], v[186:189], v[104:107]
	v_mfma_f32_16x16x32_bf16 v[96:99], v[218:221], v[194:197], v[96:99]
	v_mfma_f32_16x16x32_bf16 v[88:91], v[226:229], v[194:197], v[88:91]
	v_mfma_f32_16x16x32_bf16 v[80:83], v[218:221], v[202:205], v[80:83]
	v_mfma_f32_16x16x32_bf16 v[72:75], v[226:229], v[202:205], v[72:75]
	v_mfma_f32_16x16x32_bf16 v[68:71], v[218:221], v[210:213], v[68:71]
	v_mfma_f32_16x16x32_bf16 v[64:67], v[226:229], v[210:213], v[64:67]
	s_barrier
	ds_read_b128 v[182:185], v171 offset:16384
	ds_read_b128 v[186:189], v171 offset:17408
	ds_read_b128 v[190:193], v171 offset:18432
	ds_read_b128 v[194:197], v171 offset:19456
	ds_read_b128 v[198:201], v171 offset:20480
	ds_read_b128 v[202:205], v171 offset:21504
	ds_read_b128 v[206:209], v171 offset:22528
	ds_read_b128 v[210:213], v171 offset:23552
	s_add_i32 s84, s65, s21
	s_mov_b32 m0, s84
	v_lshl_add_u64 v[158:159], s[54:55], 0, v[138:139]
	global_load_lds_dwordx4 v[158:159], off
	s_add_i32 m0, s84, 0x2000
	v_lshl_add_u64 v[230:231], s[54:55], 0, v[142:143]
	global_load_lds_dwordx4 v[230:231], off
	s_mov_b32 m0, s33
	v_lshl_add_u64 v[232:233], s[56:57], 0, v[136:137]
	global_load_lds_dwordx4 v[232:233], off
	s_mov_b32 m0, s35
	v_lshl_add_u64 v[234:235], s[56:57], 0, v[140:141]
	global_load_lds_dwordx4 v[234:235], off
	s_waitcnt vmcnt(6) lgkmcnt(0)
	s_barrier
	v_mfma_f32_16x16x32_bf16 v[60:63], v[150:153], v[182:185], 0
	v_mfma_f32_16x16x32_bf16 v[56:59], v[174:177], v[182:185], 0
	v_mfma_f32_16x16x32_bf16 v[52:55], v[150:153], v[190:193], 0
	v_mfma_f32_16x16x32_bf16 v[44:47], v[174:177], v[190:193], 0
	v_mfma_f32_16x16x32_bf16 v[36:39], v[150:153], v[198:201], 0
	v_mfma_f32_16x16x32_bf16 v[28:31], v[174:177], v[198:201], 0
	v_mfma_f32_16x16x32_bf16 v[20:23], v[150:153], v[206:209], 0
	v_mfma_f32_16x16x32_bf16 v[12:15], v[174:177], v[206:209], 0
	v_mfma_f32_16x16x32_bf16 v[60:63], v[154:157], v[186:189], v[60:63]
	v_mfma_f32_16x16x32_bf16 v[56:59], v[178:181], v[186:189], v[56:59]
	v_mfma_f32_16x16x32_bf16 v[52:55], v[154:157], v[194:197], v[52:55]
	v_mfma_f32_16x16x32_bf16 v[44:47], v[178:181], v[194:197], v[44:47]
	v_mfma_f32_16x16x32_bf16 v[36:39], v[154:157], v[202:205], v[36:39]
	v_mfma_f32_16x16x32_bf16 v[28:31], v[178:181], v[202:205], v[28:31]
	v_mfma_f32_16x16x32_bf16 v[20:23], v[154:157], v[210:213], v[20:23]
	v_mfma_f32_16x16x32_bf16 v[12:15], v[178:181], v[210:213], v[12:15]
	v_mfma_f32_16x16x32_bf16 v[48:51], v[214:217], v[182:185], 0
	v_mfma_f32_16x16x32_bf16 v[40:43], v[222:225], v[182:185], 0
	v_mfma_f32_16x16x32_bf16 v[32:35], v[214:217], v[190:193], 0
	v_mfma_f32_16x16x32_bf16 v[24:27], v[222:225], v[190:193], 0
	v_mfma_f32_16x16x32_bf16 v[16:19], v[214:217], v[198:201], 0
	v_mfma_f32_16x16x32_bf16 v[8:11], v[222:225], v[198:201], 0
	v_mfma_f32_16x16x32_bf16 v[4:7], v[214:217], v[206:209], 0
	v_mfma_f32_16x16x32_bf16 v[0:3], v[222:225], v[206:209], 0
	v_mfma_f32_16x16x32_bf16 v[48:51], v[218:221], v[186:189], v[48:51]
	v_mfma_f32_16x16x32_bf16 v[40:43], v[226:229], v[186:189], v[40:43]
	v_mfma_f32_16x16x32_bf16 v[32:35], v[218:221], v[194:197], v[32:35]
	v_mfma_f32_16x16x32_bf16 v[24:27], v[226:229], v[194:197], v[24:27]
	v_mfma_f32_16x16x32_bf16 v[16:19], v[218:221], v[202:205], v[16:19]
	v_mfma_f32_16x16x32_bf16 v[8:11], v[226:229], v[202:205], v[8:11]
	v_mfma_f32_16x16x32_bf16 v[4:7], v[218:221], v[210:213], v[4:7]
	v_mfma_f32_16x16x32_bf16 v[0:3], v[226:229], v[210:213], v[0:3]
	s_barrier
; #define PG8_STAGE(bufoff, gbase, voff) do { _Pragma("unroll") for (int _i = 0; _i < 2; ++_i) \
;         __builtin_amdgcn_global_load_lds((const unsigned*)((const char*)(gbase) + (voff)[_i]), (LAS unsigned*)(lds + (bufoff) + ldsw + _i * 8192), 16, 0, 0); } while (0)
; #define PG8_LDA(dst, b, h) do { _Pragma("unroll") for (int m = 0; m < 4; ++m) _Pragma("unroll") for (int k = 0; k < 2; ++k) dst[m][k] = *(const LAS bf16x8*)(lds + PG8_SA(b, h) + aoff + m * 2048 + k * 1024); } while (0)
; #define PG8_LDB(dst, b, h) do { _Pragma("unroll") for (int n = 0; n < 2; ++n) _Pragma("unroll") for (int k = 0; k < 2; ++k) dst[n][k] = *(const LAS bf16x8*)(lds + PG8_SB(b, h) + boff + n * 2048 + k * 1024); } while (0)
; #define PG8_MMA(ai, bj, At, Bt) do { __builtin_amdgcn_s_setprio(1); _Pragma("unroll") for (int m = 0; m < 4; ++m) _Pragma("unroll") for (int n = 0; n < 2; ++n) _Pragma("unroll") for (int k = 0; k < 2; ++k) \
;         acc[ai][bj][m][n] = __builtin_amdgcn_mfma_f32_16x16x32_bf16(Bt[n][k], At[m][k], acc[ai][bj][m][n], 0, 0, 0); __builtin_amdgcn_s_setprio(0); } while (0)
; #define PG8_WAIT_V(n) asm volatile("s_waitcnt vmcnt(" #n ")" ::: "memory")
; #define PG8_WAIT_L(n) asm volatile("s_waitcnt lgkmcnt(" #n ")" ::: "memory")
; #define PG8_BAR __builtin_amdgcn_s_barrier()
; #define PG8_SCHED __builtin_amdgcn_sched_barrier(0)
; template <class Epi>
; __device__ __forceinline__ void gemm_phase(LAS unsigned char* lds, const Gemm g, const StaticOrder& S, const Epi& E) {
;     ...
;             PG8_LDB(B0, 1, 0); PG8_SCHED; PG8_LDA(At, 1, 0); PG8_STAGE(PG8_SA(0, 1), a2 + hstepA, voffA);
;             PG8_WAIT_L(8); PG8_BAR; PG8_WAIT_L(0); PG8_MMA(0, 0, At, B0); PG8_BAR; PG8_SCHED;
;             PG8_LDB(B1, 1, 1); PG8_STAGE(PG8_SB(1, 0), b3, voffB);
;             PG8_BAR; PG8_WAIT_L(0); PG8_MMA(0, 1, At, B1); PG8_BAR;
;             PG8_LDA(At, 1, 1); PG8_STAGE(PG8_SA(1, 0), a3, voffA);
;             PG8_BAR; PG8_WAIT_L(0); PG8_MMA(1, 0, At, B0); PG8_BAR; PG8_SCHED;
;             PG8_STAGE(PG8_SB(1, 1), b3 + hstepB, voffB);
;             PG8_WAIT_V(6); PG8_BAR; PG8_MMA(1, 1, At, B1); PG8_BAR;
	s_add_i32 s84, 0, 0x18000
	v_add_u32_e32 v173, s84, v168
	ds_read_b128 v[150:153], v173
	ds_read_b128 v[154:157], v173 offset:1024
	ds_read_b128 v[174:177], v173 offset:2048
	ds_read_b128 v[178:181], v173 offset:3072
	ds_read_b128 v[182:185], v171 offset:32768
	ds_read_b128 v[186:189], v171 offset:33792
	ds_read_b128 v[190:193], v171 offset:34816
	ds_read_b128 v[194:197], v171 offset:35840
	ds_read_b128 v[198:201], v171 offset:36864
	ds_read_b128 v[202:205], v171 offset:37888
	ds_read_b128 v[206:209], v171 offset:38912
	ds_read_b128 v[210:213], v171 offset:39936
	s_add_i32 s98, 0, 0x1c000
	v_add_u32_e32 v246, s98, v168
	ds_read_b128 v[214:217], v246
	ds_read_b128 v[218:221], v246 offset:1024
	ds_read_b128 v[222:225], v246 offset:2048
	ds_read_b128 v[226:229], v246 offset:3072
	s_add_u32 s100, s54, 0xb0000
	s_addc_u32 s101, s55, 0
	s_add_i32 s99, s66, s21
	s_mov_b32 m0, s99
	v_lshl_add_u64 v[240:241], s[100:101], 0, v[138:139]
	global_load_lds_dwordx4 v[240:241], off
	s_add_i32 m0, s99, 0x2000
	v_lshl_add_u64 v[240:241], s[100:101], 0, v[142:143]
	global_load_lds_dwordx4 v[240:241], off
	s_add_u32 s56, s56, 0x160000
	s_addc_u32 s57, s57, 0
	s_mov_b32 m0, s58
	v_lshl_add_u64 v[244:245], s[56:57], 0, v[136:137]
	global_load_lds_dwordx4 v[244:245], off
	s_mov_b32 m0, s59
	v_lshl_add_u64 v[244:245], s[56:57], 0, v[140:141]
	global_load_lds_dwordx4 v[244:245], off
	s_waitcnt vmcnt(8) lgkmcnt(0)
	s_barrier
	v_mfma_f32_16x16x32_bf16 v[124:127], v[150:153], v[182:185], v[124:127]
	v_mfma_f32_16x16x32_bf16 v[120:123], v[174:177], v[182:185], v[120:123]
	v_mfma_f32_16x16x32_bf16 v[116:119], v[150:153], v[190:193], v[116:119]
	v_mfma_f32_16x16x32_bf16 v[108:111], v[174:177], v[190:193], v[108:111]
	v_mfma_f32_16x16x32_bf16 v[100:103], v[150:153], v[198:201], v[100:103]
	v_mfma_f32_16x16x32_bf16 v[92:95], v[174:177], v[198:201], v[92:95]
	v_mfma_f32_16x16x32_bf16 v[84:87], v[150:153], v[206:209], v[84:87]
	v_mfma_f32_16x16x32_bf16 v[76:79], v[174:177], v[206:209], v[76:79]
	v_mfma_f32_16x16x32_bf16 v[124:127], v[154:157], v[186:189], v[124:127]
	v_mfma_f32_16x16x32_bf16 v[120:123], v[178:181], v[186:189], v[120:123]
	v_mfma_f32_16x16x32_bf16 v[116:119], v[154:157], v[194:197], v[116:119]
	v_mfma_f32_16x16x32_bf16 v[108:111], v[178:181], v[194:197], v[108:111]
	v_mfma_f32_16x16x32_bf16 v[100:103], v[154:157], v[202:205], v[100:103]
	v_mfma_f32_16x16x32_bf16 v[92:95], v[178:181], v[202:205], v[92:95]
	v_mfma_f32_16x16x32_bf16 v[84:87], v[154:157], v[210:213], v[84:87]
	v_mfma_f32_16x16x32_bf16 v[76:79], v[178:181], v[210:213], v[76:79]
	v_mfma_f32_16x16x32_bf16 v[112:115], v[214:217], v[182:185], v[112:115]
	v_mfma_f32_16x16x32_bf16 v[104:107], v[222:225], v[182:185], v[104:107]
	v_mfma_f32_16x16x32_bf16 v[96:99], v[214:217], v[190:193], v[96:99]
	v_mfma_f32_16x16x32_bf16 v[88:91], v[222:225], v[190:193], v[88:91]
	v_mfma_f32_16x16x32_bf16 v[80:83], v[214:217], v[198:201], v[80:83]
	v_mfma_f32_16x16x32_bf16 v[72:75], v[222:225], v[198:201], v[72:75]
	v_mfma_f32_16x16x32_bf16 v[68:71], v[214:217], v[206:209], v[68:71]
	v_mfma_f32_16x16x32_bf16 v[64:67], v[222:225], v[206:209], v[64:67]
	v_mfma_f32_16x16x32_bf16 v[112:115], v[218:221], v[186:189], v[112:115]
	v_mfma_f32_16x16x32_bf16 v[104:107], v[226:229], v[186:189], v[104:107]
	v_mfma_f32_16x16x32_bf16 v[96:99], v[218:221], v[194:197], v[96:99]
	v_mfma_f32_16x16x32_bf16 v[88:91], v[226:229], v[194:197], v[88:91]
	v_mfma_f32_16x16x32_bf16 v[80:83], v[218:221], v[202:205], v[80:83]
	v_mfma_f32_16x16x32_bf16 v[72:75], v[226:229], v[202:205], v[72:75]
	v_mfma_f32_16x16x32_bf16 v[68:71], v[218:221], v[210:213], v[68:71]
	v_mfma_f32_16x16x32_bf16 v[64:67], v[226:229], v[210:213], v[64:67]
	s_barrier
	ds_read_b128 v[182:185], v171 offset:49152
	ds_read_b128 v[186:189], v171 offset:50176
	ds_read_b128 v[190:193], v171 offset:51200
	ds_read_b128 v[194:197], v171 offset:52224
	ds_read_b128 v[198:201], v171 offset:53248
	ds_read_b128 v[202:205], v171 offset:54272
	ds_read_b128 v[206:209], v171 offset:55296
	ds_read_b128 v[210:213], v171 offset:56320
	s_add_i32 s57, s84, s21
	s_mov_b32 m0, s57
	v_lshl_add_u64 v[158:159], v[158:159], 0, s[22:23]
	global_load_lds_dwordx4 v[158:159], off
	s_add_i32 m0, s57, 0x2000
	v_lshl_add_u64 v[158:159], v[230:231], 0, s[22:23]
	global_load_lds_dwordx4 v[158:159], off
	s_mov_b32 m0, s60
	v_lshl_add_u64 v[158:159], v[232:233], 0, s[22:23]
	global_load_lds_dwordx4 v[158:159], off
	s_mov_b32 m0, s61
	v_lshl_add_u64 v[158:159], v[234:235], 0, s[22:23]
	global_load_lds_dwordx4 v[158:159], off
	s_add_u32 s54, s54, 0xb0080
	s_addc_u32 s55, s55, 0
	s_add_i32 s56, s98, s21
	s_mov_b32 m0, s56
	v_lshl_add_u64 v[240:241], s[54:55], 0, v[138:139]
	global_load_lds_dwordx4 v[240:241], off
	s_add_i32 m0, s56, 0x2000
	v_lshl_add_u64 v[240:241], s[54:55], 0, v[142:143]
	global_load_lds_dwordx4 v[240:241], off
	s_waitcnt vmcnt(8) lgkmcnt(0)
	s_barrier
; #define PG8_STAGE(bufoff, gbase, voff) do { _Pragma("unroll") for (int _i = 0; _i < 2; ++_i) \
;         __builtin_amdgcn_global_load_lds((const unsigned*)((const char*)(gbase) + (voff)[_i]), (LAS unsigned*)(lds + (bufoff) + ldsw + _i * 8192), 16, 0, 0); } while (0)
; #define PG8_LDA(dst, b, h) do { _Pragma("unroll") for (int m = 0; m < 4; ++m) _Pragma("unroll") for (int k = 0; k < 2; ++k) dst[m][k] = *(const LAS bf16x8*)(lds + PG8_SA(b, h) + aoff + m * 2048 + k * 1024); } while (0)
; #define PG8_LDB(dst, b, h) do { _Pragma("unroll") for (int n = 0; n < 2; ++n) _Pragma("unroll") for (int k = 0; k < 2; ++k) dst[n][k] = *(const LAS bf16x8*)(lds + PG8_SB(b, h) + boff + n * 2048 + k * 1024); } while (0)
; #define PG8_MMA(ai, bj, At, Bt) do { __builtin_amdgcn_s_setprio(1); _Pragma("unroll") for (int m = 0; m < 4; ++m) _Pragma("unroll") for (int n = 0; n < 2; ++n) _Pragma("unroll") for (int k = 0; k < 2; ++k) \
;         acc[ai][bj][m][n] = __builtin_amdgcn_mfma_f32_16x16x32_bf16(Bt[n][k], At[m][k], acc[ai][bj][m][n], 0, 0, 0); __builtin_amdgcn_s_setprio(0); } while (0)
; #define PG8_WAIT_V(n) asm volatile("s_waitcnt vmcnt(" #n ")" ::: "memory")
; #define PG8_WAIT_L(n) asm volatile("s_waitcnt lgkmcnt(" #n ")" ::: "memory")
; #define PG8_BAR __builtin_amdgcn_s_barrier()
; #define PG8_SCHED __builtin_amdgcn_sched_barrier(0)
; template <class Epi>
; __device__ __forceinline__ void gemm_phase(LAS unsigned char* lds, const Gemm g, const StaticOrder& S, const Epi& E) {
;     ...
;             PG8_LDB(B0, 0, 0); PG8_SCHED; PG8_LDA(At, 0, 0); PG8_STAGE(PG8_SA(1, 1), a1 + hstepA, voffA);
;             PG8_WAIT_L(8); PG8_BAR; PG8_WAIT_L(0); PG8_MMA(0, 0, At, B0); PG8_BAR; PG8_SCHED;
;     ...
;             PG8_WAIT_V(6); PG8_BAR; PG8_MMA(1, 1, At, B1); PG8_BAR;
	v_mfma_f32_16x16x32_bf16 v[60:63], v[150:153], v[182:185], v[60:63]
	v_mfma_f32_16x16x32_bf16 v[56:59], v[174:177], v[182:185], v[56:59]
	v_mfma_f32_16x16x32_bf16 v[52:55], v[150:153], v[190:193], v[52:55]
	v_mfma_f32_16x16x32_bf16 v[44:47], v[174:177], v[190:193], v[44:47]
	v_mfma_f32_16x16x32_bf16 v[36:39], v[150:153], v[198:201], v[36:39]
	v_mfma_f32_16x16x32_bf16 v[28:31], v[174:177], v[198:201], v[28:31]
	v_mfma_f32_16x16x32_bf16 v[20:23], v[150:153], v[206:209], v[20:23]
	v_mfma_f32_16x16x32_bf16 v[12:15], v[174:177], v[206:209], v[12:15]
	v_mfma_f32_16x16x32_bf16 v[60:63], v[154:157], v[186:189], v[60:63]
	v_mfma_f32_16x16x32_bf16 v[56:59], v[178:181], v[186:189], v[56:59]
	v_mfma_f32_16x16x32_bf16 v[52:55], v[154:157], v[194:197], v[52:55]
	v_mfma_f32_16x16x32_bf16 v[44:47], v[178:181], v[194:197], v[44:47]
	v_mfma_f32_16x16x32_bf16 v[36:39], v[154:157], v[202:205], v[36:39]
	v_mfma_f32_16x16x32_bf16 v[28:31], v[178:181], v[202:205], v[28:31]
	v_mfma_f32_16x16x32_bf16 v[20:23], v[154:157], v[210:213], v[20:23]
	v_mfma_f32_16x16x32_bf16 v[12:15], v[178:181], v[210:213], v[12:15]
	v_mfma_f32_16x16x32_bf16 v[48:51], v[214:217], v[182:185], v[48:51]
	v_mfma_f32_16x16x32_bf16 v[40:43], v[222:225], v[182:185], v[40:43]
	v_mfma_f32_16x16x32_bf16 v[32:35], v[214:217], v[190:193], v[32:35]
	v_mfma_f32_16x16x32_bf16 v[24:27], v[222:225], v[190:193], v[24:27]
	v_mfma_f32_16x16x32_bf16 v[16:19], v[214:217], v[198:201], v[16:19]
	v_mfma_f32_16x16x32_bf16 v[8:11], v[222:225], v[198:201], v[8:11]
	v_mfma_f32_16x16x32_bf16 v[4:7], v[214:217], v[206:209], v[4:7]
	v_mfma_f32_16x16x32_bf16 v[0:3], v[222:225], v[206:209], v[0:3]
	v_mfma_f32_16x16x32_bf16 v[48:51], v[218:221], v[186:189], v[48:51]
	v_mfma_f32_16x16x32_bf16 v[40:43], v[226:229], v[186:189], v[40:43]
	v_mfma_f32_16x16x32_bf16 v[32:35], v[218:221], v[194:197], v[32:35]
	v_mfma_f32_16x16x32_bf16 v[24:27], v[226:229], v[194:197], v[24:27]
	v_mfma_f32_16x16x32_bf16 v[16:19], v[218:221], v[202:205], v[16:19]
	v_mfma_f32_16x16x32_bf16 v[8:11], v[226:229], v[202:205], v[8:11]
	v_mfma_f32_16x16x32_bf16 v[4:7], v[218:221], v[210:213], v[4:7]
	v_mfma_f32_16x16x32_bf16 v[0:3], v[226:229], v[210:213], v[0:3]
	s_add_u32 s46, s46, 0x100
	s_addc_u32 s47, s47, 0
	s_add_u32 s41, s41, 0x100
	s_addc_u32 s82, s82, 0
	s_cmp_ge_i32 s83, s81
	s_mov_b32 s54, s83
	s_barrier
.LBB0_910:
	s_add_i32 s83, s54, 2
	s_add_u32 s55, s46, 0xffea0080
	s_addc_u32 s56, s47, -1
	s_cmp_eq_u32 s18, s54
	s_cselect_b32 s54, s0, s41
	s_cselect_b32 s57, s45, s56
	s_cselect_b32 s56, s44, s55
	s_cselect_b32 s55, s1, s82
	ds_read_b128 v[150:153], v170
	ds_read_b128 v[154:157], v170 offset:1024
	ds_read_b128 v[174:177], v170 offset:2048
	ds_read_b128 v[178:181], v170 offset:3072
	ds_read_b128 v[182:185], v171
	ds_read_b128 v[186:189], v171 offset:1024
	ds_read_b128 v[190:193], v171 offset:2048
	ds_read_b128 v[194:197], v171 offset:3072
	ds_read_b128 v[198:201], v171 offset:4096
	ds_read_b128 v[202:205], v171 offset:5120
	ds_read_b128 v[206:209], v171 offset:6144
	ds_read_b128 v[210:213], v171 offset:7168
	ds_read_b128 v[214:217], v172
	ds_read_b128 v[218:221], v172 offset:1024
	ds_read_b128 v[222:225], v172 offset:2048
	ds_read_b128 v[226:229], v172 offset:3072
	s_add_i32 m0, s33, 0xc000
	v_lshl_add_u64 v[158:159], s[46:47], 0, v[144:145]
	global_load_lds_dwordx4 v[158:159], off
	s_add_i32 m0, s33, 0xe000
	v_lshl_add_u64 v[158:159], s[46:47], 0, v[146:147]
	global_load_lds_dwordx4 v[158:159], off
	s_waitcnt vmcnt(8) lgkmcnt(0)
	s_barrier
	v_mfma_f32_16x16x32_bf16 v[124:127], v[150:153], v[182:185], v[124:127]
	v_mfma_f32_16x16x32_bf16 v[120:123], v[174:177], v[182:185], v[120:123]
	v_mfma_f32_16x16x32_bf16 v[116:119], v[150:153], v[190:193], v[116:119]
	v_mfma_f32_16x16x32_bf16 v[108:111], v[174:177], v[190:193], v[108:111]
	v_mfma_f32_16x16x32_bf16 v[100:103], v[150:153], v[198:201], v[100:103]
	v_mfma_f32_16x16x32_bf16 v[92:95], v[174:177], v[198:201], v[92:95]
	v_mfma_f32_16x16x32_bf16 v[84:87], v[150:153], v[206:209], v[84:87]
	v_mfma_f32_16x16x32_bf16 v[76:79], v[174:177], v[206:209], v[76:79]
	v_mfma_f32_16x16x32_bf16 v[124:127], v[154:157], v[186:189], v[124:127]
	v_mfma_f32_16x16x32_bf16 v[120:123], v[178:181], v[186:189], v[120:123]
	v_mfma_f32_16x16x32_bf16 v[116:119], v[154:157], v[194:197], v[116:119]
	v_mfma_f32_16x16x32_bf16 v[108:111], v[178:181], v[194:197], v[108:111]
	v_mfma_f32_16x16x32_bf16 v[100:103], v[154:157], v[202:205], v[100:103]
	v_mfma_f32_16x16x32_bf16 v[92:95], v[178:181], v[202:205], v[92:95]
	v_mfma_f32_16x16x32_bf16 v[84:87], v[154:157], v[210:213], v[84:87]
	v_mfma_f32_16x16x32_bf16 v[76:79], v[178:181], v[210:213], v[76:79]
	v_mfma_f32_16x16x32_bf16 v[112:115], v[214:217], v[182:185], v[112:115]
	v_mfma_f32_16x16x32_bf16 v[104:107], v[222:225], v[182:185], v[104:107]
	v_mfma_f32_16x16x32_bf16 v[96:99], v[214:217], v[190:193], v[96:99]
	v_mfma_f32_16x16x32_bf16 v[88:91], v[222:225], v[190:193], v[88:91]
	v_mfma_f32_16x16x32_bf16 v[80:83], v[214:217], v[198:201], v[80:83]
	v_mfma_f32_16x16x32_bf16 v[72:75], v[222:225], v[198:201], v[72:75]
	v_mfma_f32_16x16x32_bf16 v[68:71], v[214:217], v[206:209], v[68:71]
	v_mfma_f32_16x16x32_bf16 v[64:67], v[222:225], v[206:209], v[64:67]
	v_mfma_f32_16x16x32_bf16 v[112:115], v[218:221], v[186:189], v[112:115]
	v_mfma_f32_16x16x32_bf16 v[104:107], v[226:229], v[186:189], v[104:107]
	v_mfma_f32_16x16x32_bf16 v[96:99], v[218:221], v[194:197], v[96:99]
	v_mfma_f32_16x16x32_bf16 v[88:91], v[226:229], v[194:197], v[88:91]
	v_mfma_f32_16x16x32_bf16 v[80:83], v[218:221], v[202:205], v[80:83]
	v_mfma_f32_16x16x32_bf16 v[72:75], v[226:229], v[202:205], v[72:75]
	v_mfma_f32_16x16x32_bf16 v[68:71], v[218:221], v[210:213], v[68:71]
	v_mfma_f32_16x16x32_bf16 v[64:67], v[226:229], v[210:213], v[64:67]
	s_barrier
; #define PG8_STAGE(bufoff, gbase, voff) do { _Pragma("unroll") for (int _i = 0; _i < 2; ++_i) \
;         __builtin_amdgcn_global_load_lds((const unsigned*)((const char*)(gbase) + (voff)[_i]), (LAS unsigned*)(lds + (bufoff) + ldsw + _i * 8192), 16, 0, 0); } while (0)
; #define PG8_LDA(dst, b, h) do { _Pragma("unroll") for (int m = 0; m < 4; ++m) _Pragma("unroll") for (int k = 0; k < 2; ++k) dst[m][k] = *(const LAS bf16x8*)(lds + PG8_SA(b, h) + aoff + m * 2048 + k * 1024); } while (0)
; #define PG8_LDB(dst, b, h) do { _Pragma("unroll") for (int n = 0; n < 2; ++n) _Pragma("unroll") for (int k = 0; k < 2; ++k) dst[n][k] = *(const LAS bf16x8*)(lds + PG8_SB(b, h) + boff + n * 2048 + k * 1024); } while (0)
; #define PG8_MMA(ai, bj, At, Bt) do { __builtin_amdgcn_s_setprio(1); _Pragma("unroll") for (int m = 0; m < 4; ++m) _Pragma("unroll") for (int n = 0; n < 2; ++n) _Pragma("unroll") for (int k = 0; k < 2; ++k) \
;         acc[ai][bj][m][n] = __builtin_amdgcn_mfma_f32_16x16x32_bf16(Bt[n][k], At[m][k], acc[ai][bj][m][n], 0, 0, 0); __builtin_amdgcn_s_setprio(0); } while (0)
; #define PG8_WAIT_V(n) asm volatile("s_waitcnt vmcnt(" #n ")" ::: "memory")
; #define PG8_BAR __builtin_amdgcn_s_barrier()
; template <class Epi>
; __device__ __forceinline__ void gemm_phase(LAS unsigned char* lds, const Gemm g, const StaticOrder& S, const Epi& E) {
;     ...
;             PG8_LDB(B1, 0, 1); PG8_STAGE(PG8_SB(0, 0), b2, voffB);
;             PG8_BAR; PG8_WAIT_L(0); PG8_MMA(0, 1, At, B1); PG8_BAR;
;             PG8_LDA(At, 0, 1); PG8_STAGE(PG8_SA(0, 0), a2, voffA);
;             PG8_BAR; PG8_WAIT_L(0); PG8_MMA(1, 0, At, B0); PG8_BAR; PG8_SCHED;
;             PG8_STAGE(PG8_SB(0, 1), b2 + hstepB, voffB);
;             PG8_WAIT_V(6); PG8_BAR; PG8_MMA(1, 1, At, B1); PG8_BAR;
;             PG8_LDB(B0, 1, 0); PG8_SCHED; PG8_LDA(At, 1, 0); PG8_STAGE(PG8_SA(0, 1), a2 + hstepA, voffA);
;             PG8_WAIT_L(8); PG8_BAR; PG8_WAIT_L(0); PG8_MMA(0, 0, At, B0); PG8_BAR; PG8_SCHED;
;             PG8_LDB(B1, 1, 1); PG8_STAGE(PG8_SB(1, 0), b3, voffB);
;             PG8_BAR; PG8_WAIT_L(0); PG8_MMA(0, 1, At, B1); PG8_BAR;
;             PG8_LDA(At, 1, 1); PG8_STAGE(PG8_SA(1, 0), a3, voffA);
;             PG8_BAR; PG8_WAIT_L(0); PG8_MMA(1, 0, At, B0); PG8_BAR; PG8_SCHED;
;             PG8_STAGE(PG8_SB(1, 1), b3 + hstepB, voffB);
;             PG8_WAIT_V(6); PG8_BAR; PG8_MMA(1, 1, At, B1); PG8_BAR;
	ds_read_b128 v[182:185], v171 offset:16384
	ds_read_b128 v[186:189], v171 offset:17408
	ds_read_b128 v[190:193], v171 offset:18432
	ds_read_b128 v[194:197], v171 offset:19456
	ds_read_b128 v[198:201], v171 offset:20480
	ds_read_b128 v[202:205], v171 offset:21504
	ds_read_b128 v[206:209], v171 offset:22528
	ds_read_b128 v[210:213], v171 offset:23552
	s_add_i32 s84, s65, s21
	s_mov_b32 m0, s84
	v_lshl_add_u64 v[158:159], s[54:55], 0, v[138:139]
	global_load_lds_dwordx4 v[158:159], off
	s_add_i32 m0, s84, 0x2000
	v_lshl_add_u64 v[230:231], s[54:55], 0, v[142:143]
	global_load_lds_dwordx4 v[230:231], off
	s_mov_b32 m0, s33
	v_lshl_add_u64 v[232:233], s[56:57], 0, v[136:137]
	global_load_lds_dwordx4 v[232:233], off
	s_mov_b32 m0, s35
	v_lshl_add_u64 v[234:235], s[56:57], 0, v[140:141]
	global_load_lds_dwordx4 v[234:235], off
	s_waitcnt vmcnt(6) lgkmcnt(0)
	s_barrier
	v_mfma_f32_16x16x32_bf16 v[60:63], v[150:153], v[182:185], v[60:63]
	v_mfma_f32_16x16x32_bf16 v[56:59], v[174:177], v[182:185], v[56:59]
	v_mfma_f32_16x16x32_bf16 v[52:55], v[150:153], v[190:193], v[52:55]
	v_mfma_f32_16x16x32_bf16 v[44:47], v[174:177], v[190:193], v[44:47]
	v_mfma_f32_16x16x32_bf16 v[36:39], v[150:153], v[198:201], v[36:39]
	v_mfma_f32_16x16x32_bf16 v[28:31], v[174:177], v[198:201], v[28:31]
	v_mfma_f32_16x16x32_bf16 v[20:23], v[150:153], v[206:209], v[20:23]
	v_mfma_f32_16x16x32_bf16 v[12:15], v[174:177], v[206:209], v[12:15]
	v_mfma_f32_16x16x32_bf16 v[60:63], v[154:157], v[186:189], v[60:63]
	v_mfma_f32_16x16x32_bf16 v[56:59], v[178:181], v[186:189], v[56:59]
	v_mfma_f32_16x16x32_bf16 v[52:55], v[154:157], v[194:197], v[52:55]
	v_mfma_f32_16x16x32_bf16 v[44:47], v[178:181], v[194:197], v[44:47]
	v_mfma_f32_16x16x32_bf16 v[36:39], v[154:157], v[202:205], v[36:39]
	v_mfma_f32_16x16x32_bf16 v[28:31], v[178:181], v[202:205], v[28:31]
	v_mfma_f32_16x16x32_bf16 v[20:23], v[154:157], v[210:213], v[20:23]
	v_mfma_f32_16x16x32_bf16 v[12:15], v[178:181], v[210:213], v[12:15]
	v_mfma_f32_16x16x32_bf16 v[48:51], v[214:217], v[182:185], v[48:51]
	v_mfma_f32_16x16x32_bf16 v[40:43], v[222:225], v[182:185], v[40:43]
	v_mfma_f32_16x16x32_bf16 v[32:35], v[214:217], v[190:193], v[32:35]
	v_mfma_f32_16x16x32_bf16 v[24:27], v[222:225], v[190:193], v[24:27]
	v_mfma_f32_16x16x32_bf16 v[16:19], v[214:217], v[198:201], v[16:19]
	v_mfma_f32_16x16x32_bf16 v[8:11], v[222:225], v[198:201], v[8:11]
	v_mfma_f32_16x16x32_bf16 v[4:7], v[214:217], v[206:209], v[4:7]
	v_mfma_f32_16x16x32_bf16 v[0:3], v[222:225], v[206:209], v[0:3]
	v_mfma_f32_16x16x32_bf16 v[48:51], v[218:221], v[186:189], v[48:51]
	v_mfma_f32_16x16x32_bf16 v[40:43], v[226:229], v[186:189], v[40:43]
	v_mfma_f32_16x16x32_bf16 v[32:35], v[218:221], v[194:197], v[32:35]
	v_mfma_f32_16x16x32_bf16 v[24:27], v[226:229], v[194:197], v[24:27]
	v_mfma_f32_16x16x32_bf16 v[16:19], v[218:221], v[202:205], v[16:19]
	v_mfma_f32_16x16x32_bf16 v[8:11], v[226:229], v[202:205], v[8:11]
	v_mfma_f32_16x16x32_bf16 v[4:7], v[218:221], v[210:213], v[4:7]
	v_mfma_f32_16x16x32_bf16 v[0:3], v[226:229], v[210:213], v[0:3]
	s_barrier
	s_add_i32 s84, 0, 0x18000
	v_add_u32_e32 v173, s84, v168
	ds_read_b128 v[150:153], v173
	ds_read_b128 v[154:157], v173 offset:1024
	ds_read_b128 v[174:177], v173 offset:2048
	ds_read_b128 v[178:181], v173 offset:3072
	ds_read_b128 v[182:185], v171 offset:32768
	ds_read_b128 v[186:189], v171 offset:33792
	ds_read_b128 v[190:193], v171 offset:34816
	ds_read_b128 v[194:197], v171 offset:35840
	ds_read_b128 v[198:201], v171 offset:36864
	ds_read_b128 v[202:205], v171 offset:37888
	ds_read_b128 v[206:209], v171 offset:38912
	ds_read_b128 v[210:213], v171 offset:39936
	s_add_i32 s98, 0, 0x1c000
	v_add_u32_e32 v246, s98, v168
	ds_read_b128 v[214:217], v246
	ds_read_b128 v[218:221], v246 offset:1024
	ds_read_b128 v[222:225], v246 offset:2048
	ds_read_b128 v[226:229], v246 offset:3072
	s_add_u32 s100, s54, 0xb0000
	s_addc_u32 s101, s55, 0
	s_add_i32 s99, s66, s21
	s_mov_b32 m0, s99
	v_lshl_add_u64 v[240:241], s[100:101], 0, v[138:139]
	global_load_lds_dwordx4 v[240:241], off
	s_add_i32 m0, s99, 0x2000
	v_lshl_add_u64 v[240:241], s[100:101], 0, v[142:143]
	global_load_lds_dwordx4 v[240:241], off
	s_add_u32 s56, s56, 0x160000
	s_addc_u32 s57, s57, 0
	s_mov_b32 m0, s58
	v_lshl_add_u64 v[244:245], s[56:57], 0, v[136:137]
	global_load_lds_dwordx4 v[244:245], off
	s_mov_b32 m0, s59
	v_lshl_add_u64 v[244:245], s[56:57], 0, v[140:141]
	global_load_lds_dwordx4 v[244:245], off
	s_waitcnt vmcnt(8) lgkmcnt(0)
	s_barrier
	v_mfma_f32_16x16x32_bf16 v[124:127], v[150:153], v[182:185], v[124:127]
	v_mfma_f32_16x16x32_bf16 v[120:123], v[174:177], v[182:185], v[120:123]
	v_mfma_f32_16x16x32_bf16 v[116:119], v[150:153], v[190:193], v[116:119]
	v_mfma_f32_16x16x32_bf16 v[108:111], v[174:177], v[190:193], v[108:111]
	v_mfma_f32_16x16x32_bf16 v[100:103], v[150:153], v[198:201], v[100:103]
	v_mfma_f32_16x16x32_bf16 v[92:95], v[174:177], v[198:201], v[92:95]
	v_mfma_f32_16x16x32_bf16 v[84:87], v[150:153], v[206:209], v[84:87]
	v_mfma_f32_16x16x32_bf16 v[76:79], v[174:177], v[206:209], v[76:79]
	v_mfma_f32_16x16x32_bf16 v[124:127], v[154:157], v[186:189], v[124:127]
	v_mfma_f32_16x16x32_bf16 v[120:123], v[178:181], v[186:189], v[120:123]
	v_mfma_f32_16x16x32_bf16 v[116:119], v[154:157], v[194:197], v[116:119]
	v_mfma_f32_16x16x32_bf16 v[108:111], v[178:181], v[194:197], v[108:111]
	v_mfma_f32_16x16x32_bf16 v[100:103], v[154:157], v[202:205], v[100:103]
	v_mfma_f32_16x16x32_bf16 v[92:95], v[178:181], v[202:205], v[92:95]
	v_mfma_f32_16x16x32_bf16 v[84:87], v[154:157], v[210:213], v[84:87]
	v_mfma_f32_16x16x32_bf16 v[76:79], v[178:181], v[210:213], v[76:79]
	v_mfma_f32_16x16x32_bf16 v[112:115], v[214:217], v[182:185], v[112:115]
	v_mfma_f32_16x16x32_bf16 v[104:107], v[222:225], v[182:185], v[104:107]
	v_mfma_f32_16x16x32_bf16 v[96:99], v[214:217], v[190:193], v[96:99]
	v_mfma_f32_16x16x32_bf16 v[88:91], v[222:225], v[190:193], v[88:91]
	v_mfma_f32_16x16x32_bf16 v[80:83], v[214:217], v[198:201], v[80:83]
	v_mfma_f32_16x16x32_bf16 v[72:75], v[222:225], v[198:201], v[72:75]
	v_mfma_f32_16x16x32_bf16 v[68:71], v[214:217], v[206:209], v[68:71]
	v_mfma_f32_16x16x32_bf16 v[64:67], v[222:225], v[206:209], v[64:67]
	v_mfma_f32_16x16x32_bf16 v[112:115], v[218:221], v[186:189], v[112:115]
	v_mfma_f32_16x16x32_bf16 v[104:107], v[226:229], v[186:189], v[104:107]
	v_mfma_f32_16x16x32_bf16 v[96:99], v[218:221], v[194:197], v[96:99]
	v_mfma_f32_16x16x32_bf16 v[88:91], v[226:229], v[194:197], v[88:91]
	v_mfma_f32_16x16x32_bf16 v[80:83], v[218:221], v[202:205], v[80:83]
	v_mfma_f32_16x16x32_bf16 v[72:75], v[226:229], v[202:205], v[72:75]
	v_mfma_f32_16x16x32_bf16 v[68:71], v[218:221], v[210:213], v[68:71]
	v_mfma_f32_16x16x32_bf16 v[64:67], v[226:229], v[210:213], v[64:67]
	s_barrier
; #define PG8_STAGE(bufoff, gbase, voff) do { _Pragma("unroll") for (int _i = 0; _i < 2; ++_i) \
;         __builtin_amdgcn_global_load_lds((const unsigned*)((const char*)(gbase) + (voff)[_i]), (LAS unsigned*)(lds + (bufoff) + ldsw + _i * 8192), 16, 0, 0); } while (0)
; #define PG8_LDA(dst, b, h) do { _Pragma("unroll") for (int m = 0; m < 4; ++m) _Pragma("unroll") for (int k = 0; k < 2; ++k) dst[m][k] = *(const LAS bf16x8*)(lds + PG8_SA(b, h) + aoff + m * 2048 + k * 1024); } while (0)
; #define PG8_MMA(ai, bj, At, Bt) do { __builtin_amdgcn_s_setprio(1); _Pragma("unroll") for (int m = 0; m < 4; ++m) _Pragma("unroll") for (int n = 0; n < 2; ++n) _Pragma("unroll") for (int k = 0; k < 2; ++k) \
;         acc[ai][bj][m][n] = __builtin_amdgcn_mfma_f32_16x16x32_bf16(Bt[n][k], At[m][k], acc[ai][bj][m][n], 0, 0, 0); __builtin_amdgcn_s_setprio(0); } while (0)
; #define PG8_WAIT_V(n) asm volatile("s_waitcnt vmcnt(" #n ")" ::: "memory")
; #define PG8_WAIT_L(n) asm volatile("s_waitcnt lgkmcnt(" #n ")" ::: "memory")
; #define PG8_BAR __builtin_amdgcn_s_barrier()
; #define PG8_SCHED __builtin_amdgcn_sched_barrier(0)
; template <class Epi>
; __device__ __forceinline__ void gemm_phase(LAS unsigned char* lds, const Gemm g, const StaticOrder& S, const Epi& E) {
;     ...
;             PG8_LDA(At, 1, 1); PG8_STAGE(PG8_SA(1, 0), a3, voffA);
;             PG8_BAR; PG8_WAIT_L(0); PG8_MMA(1, 0, At, B0); PG8_BAR; PG8_SCHED;
;             PG8_STAGE(PG8_SB(1, 1), b3 + hstepB, voffB);
;             PG8_WAIT_V(6); PG8_BAR; PG8_MMA(1, 1, At, B1); PG8_BAR;
	ds_read_b128 v[182:185], v171 offset:49152
	ds_read_b128 v[186:189], v171 offset:50176
	ds_read_b128 v[190:193], v171 offset:51200
	ds_read_b128 v[194:197], v171 offset:52224
	ds_read_b128 v[198:201], v171 offset:53248
	ds_read_b128 v[202:205], v171 offset:54272
	ds_read_b128 v[206:209], v171 offset:55296
	ds_read_b128 v[210:213], v171 offset:56320
	s_add_i32 s57, s84, s21
	s_mov_b32 m0, s57
	v_lshl_add_u64 v[158:159], v[158:159], 0, s[22:23]
	global_load_lds_dwordx4 v[158:159], off
	s_add_i32 m0, s57, 0x2000
	v_lshl_add_u64 v[158:159], v[230:231], 0, s[22:23]
	global_load_lds_dwordx4 v[158:159], off
	s_mov_b32 m0, s60
	v_lshl_add_u64 v[158:159], v[232:233], 0, s[22:23]
	global_load_lds_dwordx4 v[158:159], off
	s_mov_b32 m0, s61
	v_lshl_add_u64 v[158:159], v[234:235], 0, s[22:23]
	global_load_lds_dwordx4 v[158:159], off
	s_add_u32 s54, s54, 0xb0080
	s_addc_u32 s55, s55, 0
	s_add_i32 s56, s98, s21
	s_mov_b32 m0, s56
	v_lshl_add_u64 v[240:241], s[54:55], 0, v[138:139]
	global_load_lds_dwordx4 v[240:241], off
	s_add_i32 m0, s56, 0x2000
	v_lshl_add_u64 v[240:241], s[54:55], 0, v[142:143]
	global_load_lds_dwordx4 v[240:241], off
	s_waitcnt vmcnt(8) lgkmcnt(0)
	s_barrier
	v_mfma_f32_16x16x32_bf16 v[60:63], v[150:153], v[182:185], v[60:63]
	v_mfma_f32_16x16x32_bf16 v[56:59], v[174:177], v[182:185], v[56:59]
	v_mfma_f32_16x16x32_bf16 v[52:55], v[150:153], v[190:193], v[52:55]
	v_mfma_f32_16x16x32_bf16 v[44:47], v[174:177], v[190:193], v[44:47]
	v_mfma_f32_16x16x32_bf16 v[36:39], v[150:153], v[198:201], v[36:39]
	v_mfma_f32_16x16x32_bf16 v[28:31], v[174:177], v[198:201], v[28:31]
	v_mfma_f32_16x16x32_bf16 v[20:23], v[150:153], v[206:209], v[20:23]
	v_mfma_f32_16x16x32_bf16 v[12:15], v[174:177], v[206:209], v[12:15]
	v_mfma_f32_16x16x32_bf16 v[60:63], v[154:157], v[186:189], v[60:63]
	v_mfma_f32_16x16x32_bf16 v[56:59], v[178:181], v[186:189], v[56:59]
	v_mfma_f32_16x16x32_bf16 v[52:55], v[154:157], v[194:197], v[52:55]
	v_mfma_f32_16x16x32_bf16 v[44:47], v[178:181], v[194:197], v[44:47]
	v_mfma_f32_16x16x32_bf16 v[36:39], v[154:157], v[202:205], v[36:39]
	v_mfma_f32_16x16x32_bf16 v[28:31], v[178:181], v[202:205], v[28:31]
	v_mfma_f32_16x16x32_bf16 v[20:23], v[154:157], v[210:213], v[20:23]
	v_mfma_f32_16x16x32_bf16 v[12:15], v[178:181], v[210:213], v[12:15]
	v_mfma_f32_16x16x32_bf16 v[48:51], v[214:217], v[182:185], v[48:51]
	v_mfma_f32_16x16x32_bf16 v[40:43], v[222:225], v[182:185], v[40:43]
	v_mfma_f32_16x16x32_bf16 v[32:35], v[214:217], v[190:193], v[32:35]
	v_mfma_f32_16x16x32_bf16 v[24:27], v[222:225], v[190:193], v[24:27]
	v_mfma_f32_16x16x32_bf16 v[16:19], v[214:217], v[198:201], v[16:19]
	v_mfma_f32_16x16x32_bf16 v[8:11], v[222:225], v[198:201], v[8:11]
	v_mfma_f32_16x16x32_bf16 v[4:7], v[214:217], v[206:209], v[4:7]
	v_mfma_f32_16x16x32_bf16 v[0:3], v[222:225], v[206:209], v[0:3]
	v_mfma_f32_16x16x32_bf16 v[48:51], v[218:221], v[186:189], v[48:51]
	v_mfma_f32_16x16x32_bf16 v[40:43], v[226:229], v[186:189], v[40:43]
	v_mfma_f32_16x16x32_bf16 v[32:35], v[218:221], v[194:197], v[32:35]
	v_mfma_f32_16x16x32_bf16 v[24:27], v[226:229], v[194:197], v[24:27]
	v_mfma_f32_16x16x32_bf16 v[16:19], v[218:221], v[202:205], v[16:19]
	v_mfma_f32_16x16x32_bf16 v[8:11], v[226:229], v[202:205], v[8:11]
	v_mfma_f32_16x16x32_bf16 v[4:7], v[218:221], v[210:213], v[4:7]
	v_mfma_f32_16x16x32_bf16 v[0:3], v[226:229], v[210:213], v[0:3]
	s_add_u32 s46, s46, 0x100
	s_addc_u32 s47, s47, 0
	s_add_u32 s41, s41, 0x100
	s_addc_u32 s82, s82, 0
	s_cmp_ge_i32 s83, s81
	s_mov_b32 s54, s83
	s_barrier
	s_cbranch_scc0 .LBB0_910
;     __device__ __forceinline__ void operator()(const f32x4 (&acc)[2][2][4][2], const Unit& u, int wr, int wc, int fr, int fq) const {
;     ...
;         if (u.part) {
;             float* base = tailacc + (size_t)(u.part - 1) * slab - (size_t)tail_row0 * tail_ld;
; #pragma unroll
;             for (int ai = 0; ai < 2; ++ai)
; #pragma unroll
;                 for (int m = 0; m < 4; ++m) { float* rowp = base + (size_t)(row0 + ai * HALF + m * 16) * tail_ld + col0;
; #pragma unroll
;                     for (int bj = 0; bj < 2; ++bj)
; #pragma unroll
;                         for (int n = 0; n < 2; ++n) *(f32x4*)(rowp + bj * HALF + 4 * n) = acc[ai][bj][m][n]; }
	v_lshl_add_u32 v158, s78, 8, v167
	v_lshl_or_b32 v150, s79, 8, v169
	v_or_b32_e32 v156, 16, v158
	v_or_b32_e32 v154, 32, v158
	v_or_b32_e32 v152, 48, v158
	s_cmp_lg_u32 s80, 0
	v_ashrrev_i32_e32 v151, 31, v150
	v_ashrrev_i32_e32 v159, 31, v158
	v_ashrrev_i32_e32 v157, 31, v156
	v_ashrrev_i32_e32 v155, 31, v154
	v_ashrrev_i32_e32 v153, 31, v152
	s_cbranch_scc0 .LBB0_913
	s_add_i32 s18, s80, -1
	s_lshl_b64 s[46:47], s[18:19], 21
	s_add_u32 s46, s92, s46
	s_addc_u32 s47, s93, s47
	v_lshl_add_u64 v[174:175], v[150:151], 2, s[46:47]
	s_brev_b32 s46, 63
	s_mov_b32 s47, -1
	v_lshl_add_u64 v[174:175], v[174:175], 0, s[46:47]
	v_lshlrev_b64 v[176:177], 12, v[158:159]
	v_lshlrev_b64 v[178:179], 12, v[156:157]
	v_lshl_add_u64 v[176:177], v[174:175], 0, v[176:177]
	v_lshl_add_u64 v[178:179], v[174:175], 0, v[178:179]
	global_store_dwordx4 v[176:177], v[124:127], off
	global_store_dwordx4 v[176:177], v[120:123], off offset:16
	global_store_dwordx4 v[176:177], v[112:115], off offset:512
	global_store_dwordx4 v[176:177], v[104:107], off offset:528
	global_store_dwordx4 v[178:179], v[116:119], off
	global_store_dwordx4 v[178:179], v[108:111], off offset:16
	global_store_dwordx4 v[178:179], v[96:99], off offset:512
	global_store_dwordx4 v[178:179], v[88:91], off offset:528
	v_lshlrev_b64 v[178:179], 12, v[154:155]
	v_lshl_add_u64 v[178:179], v[174:175], 0, v[178:179]
	global_store_dwordx4 v[178:179], v[100:103], off
	global_store_dwordx4 v[178:179], v[92:95], off offset:16
	global_store_dwordx4 v[178:179], v[80:83], off offset:512
	global_store_dwordx4 v[178:179], v[72:75], off offset:528
	v_lshlrev_b64 v[178:179], 12, v[152:153]
	s_mov_b32 s18, 0x80000
	v_lshl_add_u64 v[174:175], v[174:175], 0, v[178:179]
	v_add_co_u32_e32 v178, vcc, s18, v176
	s_mov_b64 s[46:47], 0x80000
	s_nop 0
	v_addc_co_u32_e32 v179, vcc, 0, v177, vcc
	global_store_dwordx4 v[174:175], v[84:87], off
	global_store_dwordx4 v[174:175], v[76:79], off offset:16
	global_store_dwordx4 v[174:175], v[68:71], off offset:512
	global_store_dwordx4 v[174:175], v[64:67], off offset:528
	v_lshl_add_u64 v[174:175], v[176:177], 0, s[46:47]
	global_store_dwordx4 v[178:179], v[60:63], off
	global_store_dwordx4 v[174:175], v[56:59], off offset:16
	global_store_dwordx4 v[174:175], v[48:51], off offset:512
	global_store_dwordx4 v[174:175], v[40:43], off offset:528
	v_add_co_u32_e32 v178, vcc, s67, v176
	s_mov_b64 s[46:47], 0x90000
	s_nop 0
	v_addc_co_u32_e32 v179, vcc, 0, v177, vcc
	v_lshl_add_u64 v[174:175], v[176:177], 0, s[46:47]
	global_store_dwordx4 v[178:179], v[52:55], off
	global_store_dwordx4 v[174:175], v[44:47], off offset:16
	global_store_dwordx4 v[174:175], v[32:35], off offset:512
	global_store_dwordx4 v[174:175], v[24:27], off offset:528
	v_add_co_u32_e32 v178, vcc, s68, v176
	v_lshl_add_u64 v[174:175], v[176:177], 0, s[24:25]
	s_nop 0
	v_addc_co_u32_e32 v179, vcc, 0, v177, vcc
	s_mov_b64 s[46:47], 0xb0000
	global_store_dwordx4 v[178:179], v[36:39], off
	global_store_dwordx4 v[174:175], v[28:31], off offset:16
	global_store_dwordx4 v[174:175], v[16:19], off offset:512
	global_store_dwordx4 v[174:175], v[8:11], off offset:528
	v_lshl_add_u64 v[174:175], v[176:177], 0, s[46:47]
	v_add_co_u32_e32 v176, vcc, 0xb0000, v176
	s_nop 1
	v_addc_co_u32_e32 v177, vcc, 0, v177, vcc
	global_store_dwordx4 v[176:177], v[20:23], off
	global_store_dwordx4 v[174:175], v[12:15], off offset:16
	global_store_dwordx4 v[174:175], v[4:7], off offset:512
	global_store_dwordx4 v[174:175], v[0:3], off offset:528
	s_cbranch_execnz .LBB0_895
	s_branch .LBB0_894

; #define PG8_STAGE(bufoff, gbase, voff) do { _Pragma("unroll") for (int _i = 0; _i < 2; ++_i) \
;         __builtin_amdgcn_global_load_lds((const unsigned*)((const char*)(gbase) + (voff)[_i]), (LAS unsigned*)(lds + (bufoff) + ldsw + _i * 8192), 16, 0, 0); } while (0)
; #define PG8_LDA(dst, b, h) do { _Pragma("unroll") for (int m = 0; m < 4; ++m) _Pragma("unroll") for (int k = 0; k < 2; ++k) dst[m][k] = *(const LAS bf16x8*)(lds + PG8_SA(b, h) + aoff + m * 2048 + k * 1024); } while (0)
; #define PG8_LDB(dst, b, h) do { _Pragma("unroll") for (int n = 0; n < 2; ++n) _Pragma("unroll") for (int k = 0; k < 2; ++k) dst[n][k] = *(const LAS bf16x8*)(lds + PG8_SB(b, h) + boff + n * 2048 + k * 1024); } while (0)
; #define PG8_WAIT_V(n) asm volatile("s_waitcnt vmcnt(" #n ")" ::: "memory")
; #define PG8_WAIT_L(n) asm volatile("s_waitcnt lgkmcnt(" #n ")" ::: "memory")
; #define PG8_BAR __builtin_amdgcn_s_barrier()
; #define PG8_SCHED __builtin_amdgcn_sched_barrier(0)
; template <class Epi>
; __device__ __forceinline__ void gemm_phase(LAS unsigned char* lds, const Gemm g, const StaticOrder& S, const Epi& E) {
;     ...
;         const bool has_next = S.next(ui + 1, nxt);
;         const char* nA = has_next ? (const char*)g.A + (size_t)nxt.pm * tstepA + (size_t)nxt.kt0 * kstep : cA; const char* nB = has_next ? (const char*)g.Bt + (size_t)nxt.pn * tstepB + (size_t)nxt.kt0 * kstep : cB;
;         const int nt = cur.nkt;
;         for (int t = 0; t < nt; t += 2) {
;             const bool last = (t == nt - 2);
;             const char* a1 = cA + (size_t)(t + 1) * kstep;
;             const char* a2 = last ? nA : cA + (size_t)(t + 2) * kstep; const char* b2 = last ? nB : cB + (size_t)(t + 2) * kstep;
;             const char* a3 = a2 + kstep; const char* b3 = b2 + kstep;
;             PG8_LDB(B0, 0, 0); PG8_SCHED; PG8_LDA(At, 0, 0); PG8_STAGE(PG8_SA(1, 1), a1 + hstepA, voffA);
;             PG8_WAIT_L(8); PG8_BAR; PG8_WAIT_L(0); PG8_MMA(0, 0, At, B0); PG8_BAR; PG8_SCHED;
;             PG8_LDB(B1, 0, 1); PG8_STAGE(PG8_SB(0, 0), b2, voffB);
;             PG8_BAR; PG8_WAIT_L(0); PG8_MMA(0, 1, At, B1); PG8_BAR;
;             PG8_LDA(At, 0, 1); PG8_STAGE(PG8_SA(0, 0), a2, voffA);
;             PG8_BAR; PG8_WAIT_L(0); PG8_MMA(1, 0, At, B0); PG8_BAR; PG8_SCHED;
;             PG8_STAGE(PG8_SB(0, 1), b2 + hstepB, voffB);
;             PG8_WAIT_V(6); PG8_BAR; PG8_MMA(1, 1, At, B1); PG8_BAR;
.LBB0_1145:
	s_add_i32 s39, s76, -2
	s_add_u32 s50, s50, 0x40080
	s_addc_u32 s51, s51, 0
	s_add_u32 s41, s54, 0x100
	s_addc_u32 s43, s55, 0
	s_mov_b32 s45, 0
	s_add_i32 s77, s45, 2
	s_add_u32 s54, s50, 0xfffc0080
	s_addc_u32 s55, s51, -1
	s_cmp_eq_u32 s39, s45
	s_cselect_b32 s57, s49, s55
	s_cselect_b32 s56, s48, s54
	s_cselect_b32 s55, s1, s43
	s_cselect_b32 s54, s0, s41
	ds_read_b128 v[150:153], v129
	ds_read_b128 v[154:157], v129 offset:1024
	ds_read_b128 v[158:161], v129 offset:2048
	ds_read_b128 v[166:169], v129 offset:3072
	ds_read_b128 v[170:173], v163
	ds_read_b128 v[174:177], v163 offset:1024
	ds_read_b128 v[178:181], v163 offset:2048
	ds_read_b128 v[182:185], v163 offset:3072
	ds_read_b128 v[186:189], v163 offset:4096
	ds_read_b128 v[190:193], v163 offset:5120
	ds_read_b128 v[194:197], v163 offset:6144
	ds_read_b128 v[198:201], v163 offset:7168
	ds_read_b128 v[202:205], v164
	ds_read_b128 v[206:209], v164 offset:1024
	ds_read_b128 v[210:213], v164 offset:2048
	ds_read_b128 v[214:217], v164 offset:3072
	s_add_i32 m0, s33, 0xc000
	v_lshl_add_u64 v[242:243], s[50:51], 0, v[144:145]
	global_load_lds_dwordx4 v[242:243], off
	s_add_i32 m0, s33, 0xe000
	v_lshl_add_u64 v[242:243], s[50:51], 0, v[146:147]
	global_load_lds_dwordx4 v[242:243], off
	s_waitcnt vmcnt(8) lgkmcnt(0)
	s_barrier
	v_mfma_f32_16x16x32_bf16 v[124:127], v[150:153], v[170:173], 0
	v_mfma_f32_16x16x32_bf16 v[120:123], v[158:161], v[170:173], 0
	v_mfma_f32_16x16x32_bf16 v[116:119], v[150:153], v[178:181], 0
	v_mfma_f32_16x16x32_bf16 v[108:111], v[158:161], v[178:181], 0
	v_mfma_f32_16x16x32_bf16 v[100:103], v[150:153], v[186:189], 0
	v_mfma_f32_16x16x32_bf16 v[92:95], v[158:161], v[186:189], 0
	v_mfma_f32_16x16x32_bf16 v[84:87], v[150:153], v[194:197], 0
	v_mfma_f32_16x16x32_bf16 v[76:79], v[158:161], v[194:197], 0
	v_mfma_f32_16x16x32_bf16 v[124:127], v[154:157], v[174:177], v[124:127]
	v_mfma_f32_16x16x32_bf16 v[120:123], v[166:169], v[174:177], v[120:123]
	v_mfma_f32_16x16x32_bf16 v[116:119], v[154:157], v[182:185], v[116:119]
	v_mfma_f32_16x16x32_bf16 v[108:111], v[166:169], v[182:185], v[108:111]
	v_mfma_f32_16x16x32_bf16 v[100:103], v[154:157], v[190:193], v[100:103]
	v_mfma_f32_16x16x32_bf16 v[92:95], v[166:169], v[190:193], v[92:95]
	v_mfma_f32_16x16x32_bf16 v[84:87], v[154:157], v[198:201], v[84:87]
	v_mfma_f32_16x16x32_bf16 v[76:79], v[166:169], v[198:201], v[76:79]
	v_mfma_f32_16x16x32_bf16 v[112:115], v[202:205], v[170:173], 0
	v_mfma_f32_16x16x32_bf16 v[104:107], v[210:213], v[170:173], 0
	v_mfma_f32_16x16x32_bf16 v[96:99], v[202:205], v[178:181], 0
	v_mfma_f32_16x16x32_bf16 v[88:91], v[210:213], v[178:181], 0
	v_mfma_f32_16x16x32_bf16 v[80:83], v[202:205], v[186:189], 0
	v_mfma_f32_16x16x32_bf16 v[72:75], v[210:213], v[186:189], 0
	v_mfma_f32_16x16x32_bf16 v[68:71], v[202:205], v[194:197], 0
	v_mfma_f32_16x16x32_bf16 v[64:67], v[210:213], v[194:197], 0
	v_mfma_f32_16x16x32_bf16 v[112:115], v[206:209], v[174:177], v[112:115]
	v_mfma_f32_16x16x32_bf16 v[104:107], v[214:217], v[174:177], v[104:107]
	v_mfma_f32_16x16x32_bf16 v[96:99], v[206:209], v[182:185], v[96:99]
	v_mfma_f32_16x16x32_bf16 v[88:91], v[214:217], v[182:185], v[88:91]
	v_mfma_f32_16x16x32_bf16 v[80:83], v[206:209], v[190:193], v[80:83]
	v_mfma_f32_16x16x32_bf16 v[72:75], v[214:217], v[190:193], v[72:75]
	v_mfma_f32_16x16x32_bf16 v[68:71], v[206:209], v[198:201], v[68:71]
	v_mfma_f32_16x16x32_bf16 v[64:67], v[214:217], v[198:201], v[64:67]
	s_barrier
	ds_read_b128 v[170:173], v163 offset:16384
	ds_read_b128 v[174:177], v163 offset:17408
	ds_read_b128 v[178:181], v163 offset:18432
	ds_read_b128 v[182:185], v163 offset:19456
	ds_read_b128 v[186:189], v163 offset:20480
	ds_read_b128 v[190:193], v163 offset:21504
	ds_read_b128 v[194:197], v163 offset:22528
	ds_read_b128 v[198:201], v163 offset:23552
	s_add_i32 s45, s66, s21
	s_mov_b32 m0, s45
	v_lshl_add_u64 v[218:219], s[54:55], 0, v[138:139]
	global_load_lds_dwordx4 v[218:219], off
	s_add_i32 m0, s45, 0x2000
	v_lshl_add_u64 v[220:221], s[54:55], 0, v[142:143]
	global_load_lds_dwordx4 v[220:221], off
	s_mov_b32 m0, s33
	v_lshl_add_u64 v[222:223], s[56:57], 0, v[136:137]
	global_load_lds_dwordx4 v[222:223], off
	s_mov_b32 m0, s35
	v_lshl_add_u64 v[224:225], s[56:57], 0, v[140:141]
	global_load_lds_dwordx4 v[224:225], off
	s_waitcnt vmcnt(6) lgkmcnt(0)
	s_barrier
	v_mfma_f32_16x16x32_bf16 v[60:63], v[150:153], v[170:173], 0
	v_mfma_f32_16x16x32_bf16 v[56:59], v[158:161], v[170:173], 0
	v_mfma_f32_16x16x32_bf16 v[52:55], v[150:153], v[178:181], 0
	v_mfma_f32_16x16x32_bf16 v[44:47], v[158:161], v[178:181], 0
	v_mfma_f32_16x16x32_bf16 v[36:39], v[150:153], v[186:189], 0
	v_mfma_f32_16x16x32_bf16 v[28:31], v[158:161], v[186:189], 0
	v_mfma_f32_16x16x32_bf16 v[20:23], v[150:153], v[194:197], 0
	v_mfma_f32_16x16x32_bf16 v[12:15], v[158:161], v[194:197], 0
	v_mfma_f32_16x16x32_bf16 v[60:63], v[154:157], v[174:177], v[60:63]
	v_mfma_f32_16x16x32_bf16 v[56:59], v[166:169], v[174:177], v[56:59]
	v_mfma_f32_16x16x32_bf16 v[52:55], v[154:157], v[182:185], v[52:55]
	v_mfma_f32_16x16x32_bf16 v[44:47], v[166:169], v[182:185], v[44:47]
	v_mfma_f32_16x16x32_bf16 v[36:39], v[154:157], v[190:193], v[36:39]
	v_mfma_f32_16x16x32_bf16 v[28:31], v[166:169], v[190:193], v[28:31]
	v_mfma_f32_16x16x32_bf16 v[20:23], v[154:157], v[198:201], v[20:23]
	v_mfma_f32_16x16x32_bf16 v[12:15], v[166:169], v[198:201], v[12:15]
	v_mfma_f32_16x16x32_bf16 v[48:51], v[202:205], v[170:173], 0
	v_mfma_f32_16x16x32_bf16 v[40:43], v[210:213], v[170:173], 0
	v_mfma_f32_16x16x32_bf16 v[32:35], v[202:205], v[178:181], 0
	v_mfma_f32_16x16x32_bf16 v[24:27], v[210:213], v[178:181], 0
	v_mfma_f32_16x16x32_bf16 v[16:19], v[202:205], v[186:189], 0
	v_mfma_f32_16x16x32_bf16 v[8:11], v[210:213], v[186:189], 0
	v_mfma_f32_16x16x32_bf16 v[4:7], v[202:205], v[194:197], 0
	v_mfma_f32_16x16x32_bf16 v[0:3], v[210:213], v[194:197], 0
	v_mfma_f32_16x16x32_bf16 v[48:51], v[206:209], v[174:177], v[48:51]
	v_mfma_f32_16x16x32_bf16 v[40:43], v[214:217], v[174:177], v[40:43]
	v_mfma_f32_16x16x32_bf16 v[32:35], v[206:209], v[182:185], v[32:35]
	v_mfma_f32_16x16x32_bf16 v[24:27], v[214:217], v[182:185], v[24:27]
	v_mfma_f32_16x16x32_bf16 v[16:19], v[206:209], v[190:193], v[16:19]
	v_mfma_f32_16x16x32_bf16 v[8:11], v[214:217], v[190:193], v[8:11]
	v_mfma_f32_16x16x32_bf16 v[4:7], v[206:209], v[198:201], v[4:7]
	v_mfma_f32_16x16x32_bf16 v[0:3], v[214:217], v[198:201], v[0:3]
	s_barrier
; #define PG8_STAGE(bufoff, gbase, voff) do { _Pragma("unroll") for (int _i = 0; _i < 2; ++_i) \
;         __builtin_amdgcn_global_load_lds((const unsigned*)((const char*)(gbase) + (voff)[_i]), (LAS unsigned*)(lds + (bufoff) + ldsw + _i * 8192), 16, 0, 0); } while (0)
; #define PG8_LDA(dst, b, h) do { _Pragma("unroll") for (int m = 0; m < 4; ++m) _Pragma("unroll") for (int k = 0; k < 2; ++k) dst[m][k] = *(const LAS bf16x8*)(lds + PG8_SA(b, h) + aoff + m * 2048 + k * 1024); } while (0)
; #define PG8_WAIT_V(n) asm volatile("s_waitcnt vmcnt(" #n ")" ::: "memory")
; #define PG8_WAIT_L(n) asm volatile("s_waitcnt lgkmcnt(" #n ")" ::: "memory")
; template <class Epi>
; __device__ __forceinline__ void gemm_phase(LAS unsigned char* lds, const Gemm g, const StaticOrder& S, const Epi& E) {
;     ...
;         for (int t = 0; t < nt; t += 2) {
;             const bool last = (t == nt - 2);
;             const char* a1 = cA + (size_t)(t + 1) * kstep;
;             const char* a2 = last ? nA : cA + (size_t)(t + 2) * kstep; const char* b2 = last ? nB : cB + (size_t)(t + 2) * kstep;
;             const char* a3 = a2 + kstep; const char* b3 = b2 + kstep;
;             PG8_LDB(B0, 0, 0); PG8_SCHED; PG8_LDA(At, 0, 0); PG8_STAGE(PG8_SA(1, 1), a1 + hstepA, voffA);
;             PG8_WAIT_L(8); PG8_BAR; PG8_WAIT_L(0); PG8_MMA(0, 0, At, B0); PG8_BAR; PG8_SCHED;
;             PG8_LDB(B1, 0, 1); PG8_STAGE(PG8_SB(0, 0), b2, voffB);
;             PG8_BAR; PG8_WAIT_L(0); PG8_MMA(0, 1, At, B1); PG8_BAR;
;             PG8_LDA(At, 0, 1); PG8_STAGE(PG8_SA(0, 0), a2, voffA);
;             PG8_BAR; PG8_WAIT_L(0); PG8_MMA(1, 0, At, B0); PG8_BAR; PG8_SCHED;
;             PG8_STAGE(PG8_SB(0, 1), b2 + hstepB, voffB);
;             PG8_WAIT_V(6); PG8_BAR; PG8_MMA(1, 1, At, B1); PG8_BAR;
;             PG8_LDB(B0, 1, 0); PG8_SCHED; PG8_LDA(At, 1, 0); PG8_STAGE(PG8_SA(0, 1), a2 + hstepA, voffA);
;             PG8_WAIT_L(8); PG8_BAR; PG8_WAIT_L(0); PG8_MMA(0, 0, At, B0); PG8_BAR; PG8_SCHED;
;             PG8_LDB(B1, 1, 1); PG8_STAGE(PG8_SB(1, 0), b3, voffB);
;             PG8_BAR; PG8_WAIT_L(0); PG8_MMA(0, 1, At, B1); PG8_BAR;
;             PG8_LDA(At, 1, 1); PG8_STAGE(PG8_SA(1, 0), a3, voffA);
;             PG8_BAR; PG8_WAIT_L(0); PG8_MMA(1, 0, At, B0); PG8_BAR; PG8_SCHED;
;             PG8_STAGE(PG8_SB(1, 1), b3 + hstepB, voffB);
;             PG8_WAIT_V(6); PG8_BAR; PG8_MMA(1, 1, At, B1); PG8_BAR;
	s_add_i32 s45, 0, 0x18000
	v_add_u32_e32 v165, s45, v135
	ds_read_b128 v[150:153], v165
	ds_read_b128 v[154:157], v165 offset:1024
	ds_read_b128 v[158:161], v165 offset:2048
	ds_read_b128 v[166:169], v165 offset:3072
	ds_read_b128 v[170:173], v163 offset:32768
	ds_read_b128 v[174:177], v163 offset:33792
	ds_read_b128 v[178:181], v163 offset:34816
	ds_read_b128 v[182:185], v163 offset:35840
	ds_read_b128 v[186:189], v163 offset:36864
	ds_read_b128 v[190:193], v163 offset:37888
	ds_read_b128 v[194:197], v163 offset:38912
	ds_read_b128 v[198:201], v163 offset:39936
	s_add_i32 s98, 0, 0x1c000
	v_add_u32_e32 v246, s98, v135
	ds_read_b128 v[202:205], v246
	ds_read_b128 v[206:209], v246 offset:1024
	ds_read_b128 v[210:213], v246 offset:2048
	ds_read_b128 v[214:217], v246 offset:3072
	s_add_u32 s100, s54, 0x40000
	s_addc_u32 s101, s55, 0
	s_add_i32 s99, s67, s21
	s_mov_b32 m0, s99
	v_lshl_add_u64 v[240:241], s[100:101], 0, v[138:139]
	global_load_lds_dwordx4 v[240:241], off
	s_add_i32 m0, s99, 0x2000
	v_lshl_add_u64 v[240:241], s[100:101], 0, v[142:143]
	global_load_lds_dwordx4 v[240:241], off
	s_add_u32 s56, s56, 0x40000
	s_addc_u32 s57, s57, 0
	s_mov_b32 m0, s58
	v_lshl_add_u64 v[244:245], s[56:57], 0, v[136:137]
	global_load_lds_dwordx4 v[244:245], off
	s_mov_b32 m0, s59
	v_lshl_add_u64 v[244:245], s[56:57], 0, v[140:141]
	global_load_lds_dwordx4 v[244:245], off
	s_waitcnt vmcnt(8) lgkmcnt(0)
	s_barrier
	v_mfma_f32_16x16x32_bf16 v[124:127], v[150:153], v[170:173], v[124:127]
	v_mfma_f32_16x16x32_bf16 v[120:123], v[158:161], v[170:173], v[120:123]
	v_mfma_f32_16x16x32_bf16 v[116:119], v[150:153], v[178:181], v[116:119]
	v_mfma_f32_16x16x32_bf16 v[108:111], v[158:161], v[178:181], v[108:111]
	v_mfma_f32_16x16x32_bf16 v[100:103], v[150:153], v[186:189], v[100:103]
	v_mfma_f32_16x16x32_bf16 v[92:95], v[158:161], v[186:189], v[92:95]
	v_mfma_f32_16x16x32_bf16 v[84:87], v[150:153], v[194:197], v[84:87]
	v_mfma_f32_16x16x32_bf16 v[76:79], v[158:161], v[194:197], v[76:79]
	v_mfma_f32_16x16x32_bf16 v[124:127], v[154:157], v[174:177], v[124:127]
	v_mfma_f32_16x16x32_bf16 v[120:123], v[166:169], v[174:177], v[120:123]
	v_mfma_f32_16x16x32_bf16 v[116:119], v[154:157], v[182:185], v[116:119]
	v_mfma_f32_16x16x32_bf16 v[108:111], v[166:169], v[182:185], v[108:111]
	v_mfma_f32_16x16x32_bf16 v[100:103], v[154:157], v[190:193], v[100:103]
	v_mfma_f32_16x16x32_bf16 v[92:95], v[166:169], v[190:193], v[92:95]
	v_mfma_f32_16x16x32_bf16 v[84:87], v[154:157], v[198:201], v[84:87]
	v_mfma_f32_16x16x32_bf16 v[76:79], v[166:169], v[198:201], v[76:79]
	v_mfma_f32_16x16x32_bf16 v[112:115], v[202:205], v[170:173], v[112:115]
	v_mfma_f32_16x16x32_bf16 v[104:107], v[210:213], v[170:173], v[104:107]
	v_mfma_f32_16x16x32_bf16 v[96:99], v[202:205], v[178:181], v[96:99]
	v_mfma_f32_16x16x32_bf16 v[88:91], v[210:213], v[178:181], v[88:91]
	v_mfma_f32_16x16x32_bf16 v[80:83], v[202:205], v[186:189], v[80:83]
	v_mfma_f32_16x16x32_bf16 v[72:75], v[210:213], v[186:189], v[72:75]
	v_mfma_f32_16x16x32_bf16 v[68:71], v[202:205], v[194:197], v[68:71]
	v_mfma_f32_16x16x32_bf16 v[64:67], v[210:213], v[194:197], v[64:67]
	v_mfma_f32_16x16x32_bf16 v[112:115], v[206:209], v[174:177], v[112:115]
	v_mfma_f32_16x16x32_bf16 v[104:107], v[214:217], v[174:177], v[104:107]
	v_mfma_f32_16x16x32_bf16 v[96:99], v[206:209], v[182:185], v[96:99]
	v_mfma_f32_16x16x32_bf16 v[88:91], v[214:217], v[182:185], v[88:91]
	v_mfma_f32_16x16x32_bf16 v[80:83], v[206:209], v[190:193], v[80:83]
	v_mfma_f32_16x16x32_bf16 v[72:75], v[214:217], v[190:193], v[72:75]
	v_mfma_f32_16x16x32_bf16 v[68:71], v[206:209], v[198:201], v[68:71]
	v_mfma_f32_16x16x32_bf16 v[64:67], v[214:217], v[198:201], v[64:67]
	s_barrier
	ds_read_b128 v[170:173], v163 offset:49152
	ds_read_b128 v[174:177], v163 offset:50176
	ds_read_b128 v[178:181], v163 offset:51200
	ds_read_b128 v[182:185], v163 offset:52224
	ds_read_b128 v[186:189], v163 offset:53248
	ds_read_b128 v[190:193], v163 offset:54272
	ds_read_b128 v[194:197], v163 offset:55296
	ds_read_b128 v[198:201], v163 offset:56320
	s_add_i32 s45, s45, s21
	s_mov_b32 m0, s45
	v_lshl_add_u64 v[218:219], v[218:219], 0, s[12:13]
	global_load_lds_dwordx4 v[218:219], off
	s_add_i32 m0, s45, 0x2000
	v_lshl_add_u64 v[218:219], v[220:221], 0, s[12:13]
	global_load_lds_dwordx4 v[218:219], off
	s_mov_b32 m0, s60
	v_lshl_add_u64 v[218:219], v[222:223], 0, s[12:13]
	global_load_lds_dwordx4 v[218:219], off
	s_mov_b32 m0, s61
	v_lshl_add_u64 v[218:219], v[224:225], 0, s[12:13]
	global_load_lds_dwordx4 v[218:219], off
	s_add_u32 s54, s54, 0x40080
	s_addc_u32 s55, s55, 0
	s_add_i32 s45, s98, s21
	s_mov_b32 m0, s45
	v_lshl_add_u64 v[240:241], s[54:55], 0, v[138:139]
	global_load_lds_dwordx4 v[240:241], off
	s_add_i32 m0, s45, 0x2000
	v_lshl_add_u64 v[240:241], s[54:55], 0, v[142:143]
	global_load_lds_dwordx4 v[240:241], off
	s_waitcnt vmcnt(8) lgkmcnt(0)
	s_barrier
; #define PG8_STAGE(bufoff, gbase, voff) do { _Pragma("unroll") for (int _i = 0; _i < 2; ++_i) \
;         __builtin_amdgcn_global_load_lds((const unsigned*)((const char*)(gbase) + (voff)[_i]), (LAS unsigned*)(lds + (bufoff) + ldsw + _i * 8192), 16, 0, 0); } while (0)
; #define PG8_LDA(dst, b, h) do { _Pragma("unroll") for (int m = 0; m < 4; ++m) _Pragma("unroll") for (int k = 0; k < 2; ++k) dst[m][k] = *(const LAS bf16x8*)(lds + PG8_SA(b, h) + aoff + m * 2048 + k * 1024); } while (0)
; #define PG8_LDB(dst, b, h) do { _Pragma("unroll") for (int n = 0; n < 2; ++n) _Pragma("unroll") for (int k = 0; k < 2; ++k) dst[n][k] = *(const LAS bf16x8*)(lds + PG8_SB(b, h) + boff + n * 2048 + k * 1024); } while (0)
; #define PG8_BAR __builtin_amdgcn_s_barrier()
; template <class Epi>
; __device__ __forceinline__ void gemm_phase(LAS unsigned char* lds, const Gemm g, const StaticOrder& S, const Epi& E) {
;     ...
;         const bool has_next = S.next(ui + 1, nxt);
;         const char* nA = has_next ? (const char*)g.A + (size_t)nxt.pm * tstepA + (size_t)nxt.kt0 * kstep : cA; const char* nB = has_next ? (const char*)g.Bt + (size_t)nxt.pn * tstepB + (size_t)nxt.kt0 * kstep : cB;
;         const int nt = cur.nkt;
;         for (int t = 0; t < nt; t += 2) {
;             const bool last = (t == nt - 2);
;             const char* a1 = cA + (size_t)(t + 1) * kstep;
;             const char* a2 = last ? nA : cA + (size_t)(t + 2) * kstep; const char* b2 = last ? nB : cB + (size_t)(t + 2) * kstep;
;             const char* a3 = a2 + kstep; const char* b3 = b2 + kstep;
;             PG8_LDB(B0, 0, 0); PG8_SCHED; PG8_LDA(At, 0, 0); PG8_STAGE(PG8_SA(1, 1), a1 + hstepA, voffA);
;             PG8_WAIT_L(8); PG8_BAR; PG8_WAIT_L(0); PG8_MMA(0, 0, At, B0); PG8_BAR; PG8_SCHED;
;             PG8_LDB(B1, 0, 1); PG8_STAGE(PG8_SB(0, 0), b2, voffB);
;             PG8_BAR; PG8_WAIT_L(0); PG8_MMA(0, 1, At, B1); PG8_BAR;
;             PG8_LDA(At, 0, 1); PG8_STAGE(PG8_SA(0, 0), a2, voffA);
;             PG8_BAR; PG8_WAIT_L(0); PG8_MMA(1, 0, At, B0); PG8_BAR; PG8_SCHED;
;             PG8_STAGE(PG8_SB(0, 1), b2 + hstepB, voffB);
;             PG8_WAIT_V(6); PG8_BAR; PG8_MMA(1, 1, At, B1); PG8_BAR;
;             PG8_LDB(B0, 1, 0); PG8_SCHED; PG8_LDA(At, 1, 0); PG8_STAGE(PG8_SA(0, 1), a2 + hstepA, voffA);
;             PG8_WAIT_L(8); PG8_BAR; PG8_WAIT_L(0); PG8_MMA(0, 0, At, B0); PG8_BAR; PG8_SCHED;
	v_mfma_f32_16x16x32_bf16 v[60:63], v[150:153], v[170:173], v[60:63]
	v_mfma_f32_16x16x32_bf16 v[56:59], v[158:161], v[170:173], v[56:59]
	v_mfma_f32_16x16x32_bf16 v[52:55], v[150:153], v[178:181], v[52:55]
	v_mfma_f32_16x16x32_bf16 v[44:47], v[158:161], v[178:181], v[44:47]
	v_mfma_f32_16x16x32_bf16 v[36:39], v[150:153], v[186:189], v[36:39]
	v_mfma_f32_16x16x32_bf16 v[28:31], v[158:161], v[186:189], v[28:31]
	v_mfma_f32_16x16x32_bf16 v[20:23], v[150:153], v[194:197], v[20:23]
	v_mfma_f32_16x16x32_bf16 v[12:15], v[158:161], v[194:197], v[12:15]
	v_mfma_f32_16x16x32_bf16 v[60:63], v[154:157], v[174:177], v[60:63]
	v_mfma_f32_16x16x32_bf16 v[56:59], v[166:169], v[174:177], v[56:59]
	v_mfma_f32_16x16x32_bf16 v[52:55], v[154:157], v[182:185], v[52:55]
	v_mfma_f32_16x16x32_bf16 v[44:47], v[166:169], v[182:185], v[44:47]
	v_mfma_f32_16x16x32_bf16 v[36:39], v[154:157], v[190:193], v[36:39]
	v_mfma_f32_16x16x32_bf16 v[28:31], v[166:169], v[190:193], v[28:31]
	v_mfma_f32_16x16x32_bf16 v[20:23], v[154:157], v[198:201], v[20:23]
	v_mfma_f32_16x16x32_bf16 v[12:15], v[166:169], v[198:201], v[12:15]
	v_mfma_f32_16x16x32_bf16 v[48:51], v[202:205], v[170:173], v[48:51]
	v_mfma_f32_16x16x32_bf16 v[40:43], v[210:213], v[170:173], v[40:43]
	v_mfma_f32_16x16x32_bf16 v[32:35], v[202:205], v[178:181], v[32:35]
	v_mfma_f32_16x16x32_bf16 v[24:27], v[210:213], v[178:181], v[24:27]
	v_mfma_f32_16x16x32_bf16 v[16:19], v[202:205], v[186:189], v[16:19]
	v_mfma_f32_16x16x32_bf16 v[8:11], v[210:213], v[186:189], v[8:11]
	v_mfma_f32_16x16x32_bf16 v[4:7], v[202:205], v[194:197], v[4:7]
	v_mfma_f32_16x16x32_bf16 v[0:3], v[210:213], v[194:197], v[0:3]
	v_mfma_f32_16x16x32_bf16 v[48:51], v[206:209], v[174:177], v[48:51]
	v_mfma_f32_16x16x32_bf16 v[40:43], v[214:217], v[174:177], v[40:43]
	v_mfma_f32_16x16x32_bf16 v[32:35], v[206:209], v[182:185], v[32:35]
	v_mfma_f32_16x16x32_bf16 v[24:27], v[214:217], v[182:185], v[24:27]
	v_mfma_f32_16x16x32_bf16 v[16:19], v[206:209], v[190:193], v[16:19]
	v_mfma_f32_16x16x32_bf16 v[8:11], v[214:217], v[190:193], v[8:11]
	v_mfma_f32_16x16x32_bf16 v[4:7], v[206:209], v[198:201], v[4:7]
	v_mfma_f32_16x16x32_bf16 v[0:3], v[214:217], v[198:201], v[0:3]
	s_add_u32 s50, s50, 0x100
	s_addc_u32 s51, s51, 0
	s_add_u32 s41, s41, 0x100
	s_addc_u32 s43, s43, 0
	s_cmp_ge_i32 s77, s76
	s_mov_b32 s45, s77
	s_barrier
.LBB0_1146:
	s_add_i32 s77, s45, 2
	s_add_u32 s54, s50, 0xfffc0080
	s_addc_u32 s55, s51, -1
	s_cmp_eq_u32 s39, s45
	s_cselect_b32 s57, s49, s55
	s_cselect_b32 s56, s48, s54
	s_cselect_b32 s55, s1, s43
	s_cselect_b32 s54, s0, s41
	ds_read_b128 v[150:153], v129
	ds_read_b128 v[154:157], v129 offset:1024
	ds_read_b128 v[158:161], v129 offset:2048
	ds_read_b128 v[166:169], v129 offset:3072
	ds_read_b128 v[170:173], v163
	ds_read_b128 v[174:177], v163 offset:1024
	ds_read_b128 v[178:181], v163 offset:2048
	ds_read_b128 v[182:185], v163 offset:3072
	ds_read_b128 v[186:189], v163 offset:4096
	ds_read_b128 v[190:193], v163 offset:5120
	ds_read_b128 v[194:197], v163 offset:6144
	ds_read_b128 v[198:201], v163 offset:7168
	ds_read_b128 v[202:205], v164
	ds_read_b128 v[206:209], v164 offset:1024
	ds_read_b128 v[210:213], v164 offset:2048
	ds_read_b128 v[214:217], v164 offset:3072
	s_add_i32 m0, s33, 0xc000
	v_lshl_add_u64 v[242:243], s[50:51], 0, v[144:145]
	global_load_lds_dwordx4 v[242:243], off
	s_add_i32 m0, s33, 0xe000
	v_lshl_add_u64 v[242:243], s[50:51], 0, v[146:147]
	global_load_lds_dwordx4 v[242:243], off
	s_waitcnt vmcnt(8) lgkmcnt(0)
	s_barrier
	v_mfma_f32_16x16x32_bf16 v[124:127], v[150:153], v[170:173], v[124:127]
	v_mfma_f32_16x16x32_bf16 v[120:123], v[158:161], v[170:173], v[120:123]
	v_mfma_f32_16x16x32_bf16 v[116:119], v[150:153], v[178:181], v[116:119]
	v_mfma_f32_16x16x32_bf16 v[108:111], v[158:161], v[178:181], v[108:111]
	v_mfma_f32_16x16x32_bf16 v[100:103], v[150:153], v[186:189], v[100:103]
	v_mfma_f32_16x16x32_bf16 v[92:95], v[158:161], v[186:189], v[92:95]
	v_mfma_f32_16x16x32_bf16 v[84:87], v[150:153], v[194:197], v[84:87]
	v_mfma_f32_16x16x32_bf16 v[76:79], v[158:161], v[194:197], v[76:79]
	v_mfma_f32_16x16x32_bf16 v[124:127], v[154:157], v[174:177], v[124:127]
	v_mfma_f32_16x16x32_bf16 v[120:123], v[166:169], v[174:177], v[120:123]
	v_mfma_f32_16x16x32_bf16 v[116:119], v[154:157], v[182:185], v[116:119]
	v_mfma_f32_16x16x32_bf16 v[108:111], v[166:169], v[182:185], v[108:111]
	v_mfma_f32_16x16x32_bf16 v[100:103], v[154:157], v[190:193], v[100:103]
	v_mfma_f32_16x16x32_bf16 v[92:95], v[166:169], v[190:193], v[92:95]
	v_mfma_f32_16x16x32_bf16 v[84:87], v[154:157], v[198:201], v[84:87]
	v_mfma_f32_16x16x32_bf16 v[76:79], v[166:169], v[198:201], v[76:79]
	v_mfma_f32_16x16x32_bf16 v[112:115], v[202:205], v[170:173], v[112:115]
	v_mfma_f32_16x16x32_bf16 v[104:107], v[210:213], v[170:173], v[104:107]
	v_mfma_f32_16x16x32_bf16 v[96:99], v[202:205], v[178:181], v[96:99]
	v_mfma_f32_16x16x32_bf16 v[88:91], v[210:213], v[178:181], v[88:91]
	v_mfma_f32_16x16x32_bf16 v[80:83], v[202:205], v[186:189], v[80:83]
	v_mfma_f32_16x16x32_bf16 v[72:75], v[210:213], v[186:189], v[72:75]
	v_mfma_f32_16x16x32_bf16 v[68:71], v[202:205], v[194:197], v[68:71]
	v_mfma_f32_16x16x32_bf16 v[64:67], v[210:213], v[194:197], v[64:67]
	v_mfma_f32_16x16x32_bf16 v[112:115], v[206:209], v[174:177], v[112:115]
	v_mfma_f32_16x16x32_bf16 v[104:107], v[214:217], v[174:177], v[104:107]
	v_mfma_f32_16x16x32_bf16 v[96:99], v[206:209], v[182:185], v[96:99]
	v_mfma_f32_16x16x32_bf16 v[88:91], v[214:217], v[182:185], v[88:91]
	v_mfma_f32_16x16x32_bf16 v[80:83], v[206:209], v[190:193], v[80:83]
	v_mfma_f32_16x16x32_bf16 v[72:75], v[214:217], v[190:193], v[72:75]
	v_mfma_f32_16x16x32_bf16 v[68:71], v[206:209], v[198:201], v[68:71]
	v_mfma_f32_16x16x32_bf16 v[64:67], v[214:217], v[198:201], v[64:67]
	s_barrier
; #define PG8_STAGE(bufoff, gbase, voff) do { _Pragma("unroll") for (int _i = 0; _i < 2; ++_i) \
;         __builtin_amdgcn_global_load_lds((const unsigned*)((const char*)(gbase) + (voff)[_i]), (LAS unsigned*)(lds + (bufoff) + ldsw + _i * 8192), 16, 0, 0); } while (0)
; #define PG8_LDA(dst, b, h) do { _Pragma("unroll") for (int m = 0; m < 4; ++m) _Pragma("unroll") for (int k = 0; k < 2; ++k) dst[m][k] = *(const LAS bf16x8*)(lds + PG8_SA(b, h) + aoff + m * 2048 + k * 1024); } while (0)
; #define PG8_LDB(dst, b, h) do { _Pragma("unroll") for (int n = 0; n < 2; ++n) _Pragma("unroll") for (int k = 0; k < 2; ++k) dst[n][k] = *(const LAS bf16x8*)(lds + PG8_SB(b, h) + boff + n * 2048 + k * 1024); } while (0)
; #define PG8_MMA(ai, bj, At, Bt) do { __builtin_amdgcn_s_setprio(1); _Pragma("unroll") for (int m = 0; m < 4; ++m) _Pragma("unroll") for (int n = 0; n < 2; ++n) _Pragma("unroll") for (int k = 0; k < 2; ++k) \
;         acc[ai][bj][m][n] = __builtin_amdgcn_mfma_f32_16x16x32_bf16(Bt[n][k], At[m][k], acc[ai][bj][m][n], 0, 0, 0); __builtin_amdgcn_s_setprio(0); } while (0)
; #define PG8_WAIT_V(n) asm volatile("s_waitcnt vmcnt(" #n ")" ::: "memory")
; #define PG8_BAR __builtin_amdgcn_s_barrier()
; template <class Epi>
; __device__ __forceinline__ void gemm_phase(LAS unsigned char* lds, const Gemm g, const StaticOrder& S, const Epi& E) {
;     ...
;             PG8_LDB(B1, 0, 1); PG8_STAGE(PG8_SB(0, 0), b2, voffB);
;             PG8_BAR; PG8_WAIT_L(0); PG8_MMA(0, 1, At, B1); PG8_BAR;
;             PG8_LDA(At, 0, 1); PG8_STAGE(PG8_SA(0, 0), a2, voffA);
;             PG8_BAR; PG8_WAIT_L(0); PG8_MMA(1, 0, At, B0); PG8_BAR; PG8_SCHED;
;             PG8_STAGE(PG8_SB(0, 1), b2 + hstepB, voffB);
;             PG8_WAIT_V(6); PG8_BAR; PG8_MMA(1, 1, At, B1); PG8_BAR;
;             PG8_LDB(B0, 1, 0); PG8_SCHED; PG8_LDA(At, 1, 0); PG8_STAGE(PG8_SA(0, 1), a2 + hstepA, voffA);
;             PG8_WAIT_L(8); PG8_BAR; PG8_WAIT_L(0); PG8_MMA(0, 0, At, B0); PG8_BAR; PG8_SCHED;
;             PG8_LDB(B1, 1, 1); PG8_STAGE(PG8_SB(1, 0), b3, voffB);
;             PG8_BAR; PG8_WAIT_L(0); PG8_MMA(0, 1, At, B1); PG8_BAR;
;             PG8_LDA(At, 1, 1); PG8_STAGE(PG8_SA(1, 0), a3, voffA);
;             PG8_BAR; PG8_WAIT_L(0); PG8_MMA(1, 0, At, B0); PG8_BAR; PG8_SCHED;
;             PG8_STAGE(PG8_SB(1, 1), b3 + hstepB, voffB);
;             PG8_WAIT_V(6); PG8_BAR; PG8_MMA(1, 1, At, B1); PG8_BAR;
	ds_read_b128 v[170:173], v163 offset:16384
	ds_read_b128 v[174:177], v163 offset:17408
	ds_read_b128 v[178:181], v163 offset:18432
	ds_read_b128 v[182:185], v163 offset:19456
	ds_read_b128 v[186:189], v163 offset:20480
	ds_read_b128 v[190:193], v163 offset:21504
	ds_read_b128 v[194:197], v163 offset:22528
	ds_read_b128 v[198:201], v163 offset:23552
	s_add_i32 s45, s66, s21
	s_mov_b32 m0, s45
	v_lshl_add_u64 v[218:219], s[54:55], 0, v[138:139]
	global_load_lds_dwordx4 v[218:219], off
	s_add_i32 m0, s45, 0x2000
	v_lshl_add_u64 v[220:221], s[54:55], 0, v[142:143]
	global_load_lds_dwordx4 v[220:221], off
	s_mov_b32 m0, s33
	v_lshl_add_u64 v[222:223], s[56:57], 0, v[136:137]
	global_load_lds_dwordx4 v[222:223], off
	s_mov_b32 m0, s35
	v_lshl_add_u64 v[224:225], s[56:57], 0, v[140:141]
	global_load_lds_dwordx4 v[224:225], off
	s_waitcnt vmcnt(6) lgkmcnt(0)
	s_barrier
	v_mfma_f32_16x16x32_bf16 v[60:63], v[150:153], v[170:173], v[60:63]
	v_mfma_f32_16x16x32_bf16 v[56:59], v[158:161], v[170:173], v[56:59]
	v_mfma_f32_16x16x32_bf16 v[52:55], v[150:153], v[178:181], v[52:55]
	v_mfma_f32_16x16x32_bf16 v[44:47], v[158:161], v[178:181], v[44:47]
	v_mfma_f32_16x16x32_bf16 v[36:39], v[150:153], v[186:189], v[36:39]
	v_mfma_f32_16x16x32_bf16 v[28:31], v[158:161], v[186:189], v[28:31]
	v_mfma_f32_16x16x32_bf16 v[20:23], v[150:153], v[194:197], v[20:23]
	v_mfma_f32_16x16x32_bf16 v[12:15], v[158:161], v[194:197], v[12:15]
	v_mfma_f32_16x16x32_bf16 v[60:63], v[154:157], v[174:177], v[60:63]
	v_mfma_f32_16x16x32_bf16 v[56:59], v[166:169], v[174:177], v[56:59]
	v_mfma_f32_16x16x32_bf16 v[52:55], v[154:157], v[182:185], v[52:55]
	v_mfma_f32_16x16x32_bf16 v[44:47], v[166:169], v[182:185], v[44:47]
	v_mfma_f32_16x16x32_bf16 v[36:39], v[154:157], v[190:193], v[36:39]
	v_mfma_f32_16x16x32_bf16 v[28:31], v[166:169], v[190:193], v[28:31]
	v_mfma_f32_16x16x32_bf16 v[20:23], v[154:157], v[198:201], v[20:23]
	v_mfma_f32_16x16x32_bf16 v[12:15], v[166:169], v[198:201], v[12:15]
	v_mfma_f32_16x16x32_bf16 v[48:51], v[202:205], v[170:173], v[48:51]
	v_mfma_f32_16x16x32_bf16 v[40:43], v[210:213], v[170:173], v[40:43]
	v_mfma_f32_16x16x32_bf16 v[32:35], v[202:205], v[178:181], v[32:35]
	v_mfma_f32_16x16x32_bf16 v[24:27], v[210:213], v[178:181], v[24:27]
	v_mfma_f32_16x16x32_bf16 v[16:19], v[202:205], v[186:189], v[16:19]
	v_mfma_f32_16x16x32_bf16 v[8:11], v[210:213], v[186:189], v[8:11]
	v_mfma_f32_16x16x32_bf16 v[4:7], v[202:205], v[194:197], v[4:7]
	v_mfma_f32_16x16x32_bf16 v[0:3], v[210:213], v[194:197], v[0:3]
	v_mfma_f32_16x16x32_bf16 v[48:51], v[206:209], v[174:177], v[48:51]
	v_mfma_f32_16x16x32_bf16 v[40:43], v[214:217], v[174:177], v[40:43]
	v_mfma_f32_16x16x32_bf16 v[32:35], v[206:209], v[182:185], v[32:35]
	v_mfma_f32_16x16x32_bf16 v[24:27], v[214:217], v[182:185], v[24:27]
	v_mfma_f32_16x16x32_bf16 v[16:19], v[206:209], v[190:193], v[16:19]
	v_mfma_f32_16x16x32_bf16 v[8:11], v[214:217], v[190:193], v[8:11]
	v_mfma_f32_16x16x32_bf16 v[4:7], v[206:209], v[198:201], v[4:7]
	v_mfma_f32_16x16x32_bf16 v[0:3], v[214:217], v[198:201], v[0:3]
	s_barrier
	s_add_i32 s45, 0, 0x18000
	v_add_u32_e32 v165, s45, v135
	ds_read_b128 v[150:153], v165
	ds_read_b128 v[154:157], v165 offset:1024
	ds_read_b128 v[158:161], v165 offset:2048
	ds_read_b128 v[166:169], v165 offset:3072
	ds_read_b128 v[170:173], v163 offset:32768
	ds_read_b128 v[174:177], v163 offset:33792
	ds_read_b128 v[178:181], v163 offset:34816
	ds_read_b128 v[182:185], v163 offset:35840
	ds_read_b128 v[186:189], v163 offset:36864
	ds_read_b128 v[190:193], v163 offset:37888
	ds_read_b128 v[194:197], v163 offset:38912
	ds_read_b128 v[198:201], v163 offset:39936
	s_add_i32 s98, 0, 0x1c000
	v_add_u32_e32 v246, s98, v135
	ds_read_b128 v[202:205], v246
	ds_read_b128 v[206:209], v246 offset:1024
	ds_read_b128 v[210:213], v246 offset:2048
	ds_read_b128 v[214:217], v246 offset:3072
	s_add_u32 s100, s54, 0x40000
	s_addc_u32 s101, s55, 0
	s_add_i32 s99, s67, s21
	s_mov_b32 m0, s99
	v_lshl_add_u64 v[240:241], s[100:101], 0, v[138:139]
	global_load_lds_dwordx4 v[240:241], off
	s_add_i32 m0, s99, 0x2000
	v_lshl_add_u64 v[240:241], s[100:101], 0, v[142:143]
	global_load_lds_dwordx4 v[240:241], off
	s_add_u32 s56, s56, 0x40000
	s_addc_u32 s57, s57, 0
	s_mov_b32 m0, s58
	v_lshl_add_u64 v[244:245], s[56:57], 0, v[136:137]
	global_load_lds_dwordx4 v[244:245], off
	s_mov_b32 m0, s59
	v_lshl_add_u64 v[244:245], s[56:57], 0, v[140:141]
	global_load_lds_dwordx4 v[244:245], off
	s_waitcnt vmcnt(8) lgkmcnt(0)
	s_barrier
	v_mfma_f32_16x16x32_bf16 v[124:127], v[150:153], v[170:173], v[124:127]
	v_mfma_f32_16x16x32_bf16 v[120:123], v[158:161], v[170:173], v[120:123]
	v_mfma_f32_16x16x32_bf16 v[116:119], v[150:153], v[178:181], v[116:119]
	v_mfma_f32_16x16x32_bf16 v[108:111], v[158:161], v[178:181], v[108:111]
	v_mfma_f32_16x16x32_bf16 v[100:103], v[150:153], v[186:189], v[100:103]
	v_mfma_f32_16x16x32_bf16 v[92:95], v[158:161], v[186:189], v[92:95]
	v_mfma_f32_16x16x32_bf16 v[84:87], v[150:153], v[194:197], v[84:87]
	v_mfma_f32_16x16x32_bf16 v[76:79], v[158:161], v[194:197], v[76:79]
	v_mfma_f32_16x16x32_bf16 v[124:127], v[154:157], v[174:177], v[124:127]
	v_mfma_f32_16x16x32_bf16 v[120:123], v[166:169], v[174:177], v[120:123]
	v_mfma_f32_16x16x32_bf16 v[116:119], v[154:157], v[182:185], v[116:119]
	v_mfma_f32_16x16x32_bf16 v[108:111], v[166:169], v[182:185], v[108:111]
	v_mfma_f32_16x16x32_bf16 v[100:103], v[154:157], v[190:193], v[100:103]
	v_mfma_f32_16x16x32_bf16 v[92:95], v[166:169], v[190:193], v[92:95]
	v_mfma_f32_16x16x32_bf16 v[84:87], v[154:157], v[198:201], v[84:87]
	v_mfma_f32_16x16x32_bf16 v[76:79], v[166:169], v[198:201], v[76:79]
	v_mfma_f32_16x16x32_bf16 v[112:115], v[202:205], v[170:173], v[112:115]
	v_mfma_f32_16x16x32_bf16 v[104:107], v[210:213], v[170:173], v[104:107]
	v_mfma_f32_16x16x32_bf16 v[96:99], v[202:205], v[178:181], v[96:99]
	v_mfma_f32_16x16x32_bf16 v[88:91], v[210:213], v[178:181], v[88:91]
	v_mfma_f32_16x16x32_bf16 v[80:83], v[202:205], v[186:189], v[80:83]
	v_mfma_f32_16x16x32_bf16 v[72:75], v[210:213], v[186:189], v[72:75]
	v_mfma_f32_16x16x32_bf16 v[68:71], v[202:205], v[194:197], v[68:71]
	v_mfma_f32_16x16x32_bf16 v[64:67], v[210:213], v[194:197], v[64:67]
	v_mfma_f32_16x16x32_bf16 v[112:115], v[206:209], v[174:177], v[112:115]
	v_mfma_f32_16x16x32_bf16 v[104:107], v[214:217], v[174:177], v[104:107]
	v_mfma_f32_16x16x32_bf16 v[96:99], v[206:209], v[182:185], v[96:99]
	v_mfma_f32_16x16x32_bf16 v[88:91], v[214:217], v[182:185], v[88:91]
	v_mfma_f32_16x16x32_bf16 v[80:83], v[206:209], v[190:193], v[80:83]
	v_mfma_f32_16x16x32_bf16 v[72:75], v[214:217], v[190:193], v[72:75]
	v_mfma_f32_16x16x32_bf16 v[68:71], v[206:209], v[198:201], v[68:71]
	v_mfma_f32_16x16x32_bf16 v[64:67], v[214:217], v[198:201], v[64:67]
	s_barrier
; #define PG8_STAGE(bufoff, gbase, voff) do { _Pragma("unroll") for (int _i = 0; _i < 2; ++_i) \
;         __builtin_amdgcn_global_load_lds((const unsigned*)((const char*)(gbase) + (voff)[_i]), (LAS unsigned*)(lds + (bufoff) + ldsw + _i * 8192), 16, 0, 0); } while (0)
; #define PG8_MMA(ai, bj, At, Bt) do { __builtin_amdgcn_s_setprio(1); _Pragma("unroll") for (int m = 0; m < 4; ++m) _Pragma("unroll") for (int n = 0; n < 2; ++n) _Pragma("unroll") for (int k = 0; k < 2; ++k) \
;         acc[ai][bj][m][n] = __builtin_amdgcn_mfma_f32_16x16x32_bf16(Bt[n][k], At[m][k], acc[ai][bj][m][n], 0, 0, 0); __builtin_amdgcn_s_setprio(0); } while (0)
; #define PG8_WAIT_V(n) asm volatile("s_waitcnt vmcnt(" #n ")" ::: "memory")
; #define PG8_BAR __builtin_amdgcn_s_barrier()
;     __device__ __forceinline__ void operator()(const f32x4 (&acc)[2][2][4][2], const Unit& u, int wr, int wc, int fr, int fq) const {
;     ...
;         if (u.part) {
;             float* base = tailacc + (size_t)(u.part - 1) * slab - (size_t)tail_row0 * tail_ld;
; #pragma unroll
;             for (int ai = 0; ai < 2; ++ai)
; #pragma unroll
;                 for (int m = 0; m < 4; ++m) { float* rowp = base + (size_t)(row0 + ai * HALF + m * 16) * tail_ld + col0;
; #pragma unroll
;                     for (int bj = 0; bj < 2; ++bj)
; #pragma unroll
;                         for (int n = 0; n < 2; ++n) *(f32x4*)(rowp + bj * HALF + 4 * n) = acc[ai][bj][m][n]; }
;             return;
; template <class Epi>
; __device__ __forceinline__ void gemm_phase(LAS unsigned char* lds, const Gemm g, const StaticOrder& S, const Epi& E) {
;     ...
;             PG8_STAGE(PG8_SB(1, 1), b3 + hstepB, voffB);
;             PG8_WAIT_V(6); PG8_BAR; PG8_MMA(1, 1, At, B1); PG8_BAR;
;         }
;         E(acc, cur, wr, wc, fr, fq);
	ds_read_b128 v[170:173], v163 offset:49152
	ds_read_b128 v[174:177], v163 offset:50176
	ds_read_b128 v[178:181], v163 offset:51200
	ds_read_b128 v[182:185], v163 offset:52224
	ds_read_b128 v[186:189], v163 offset:53248
	ds_read_b128 v[190:193], v163 offset:54272
	ds_read_b128 v[194:197], v163 offset:55296
	ds_read_b128 v[198:201], v163 offset:56320
	s_add_i32 s45, s45, s21
	s_mov_b32 m0, s45
	v_lshl_add_u64 v[218:219], v[218:219], 0, s[12:13]
	global_load_lds_dwordx4 v[218:219], off
	s_add_i32 m0, s45, 0x2000
	v_lshl_add_u64 v[218:219], v[220:221], 0, s[12:13]
	global_load_lds_dwordx4 v[218:219], off
	s_mov_b32 m0, s60
	v_lshl_add_u64 v[218:219], v[222:223], 0, s[12:13]
	global_load_lds_dwordx4 v[218:219], off
	s_mov_b32 m0, s61
	v_lshl_add_u64 v[218:219], v[224:225], 0, s[12:13]
	global_load_lds_dwordx4 v[218:219], off
	s_add_u32 s54, s54, 0x40080
	s_addc_u32 s55, s55, 0
	s_add_i32 s45, s98, s21
	s_mov_b32 m0, s45
	v_lshl_add_u64 v[240:241], s[54:55], 0, v[138:139]
	global_load_lds_dwordx4 v[240:241], off
	s_add_i32 m0, s45, 0x2000
	v_lshl_add_u64 v[240:241], s[54:55], 0, v[142:143]
	global_load_lds_dwordx4 v[240:241], off
	s_waitcnt vmcnt(8) lgkmcnt(0)
	s_barrier
	v_mfma_f32_16x16x32_bf16 v[60:63], v[150:153], v[170:173], v[60:63]
	v_mfma_f32_16x16x32_bf16 v[56:59], v[158:161], v[170:173], v[56:59]
	v_mfma_f32_16x16x32_bf16 v[52:55], v[150:153], v[178:181], v[52:55]
	v_mfma_f32_16x16x32_bf16 v[44:47], v[158:161], v[178:181], v[44:47]
	v_mfma_f32_16x16x32_bf16 v[36:39], v[150:153], v[186:189], v[36:39]
	v_mfma_f32_16x16x32_bf16 v[28:31], v[158:161], v[186:189], v[28:31]
	v_mfma_f32_16x16x32_bf16 v[20:23], v[150:153], v[194:197], v[20:23]
	v_mfma_f32_16x16x32_bf16 v[12:15], v[158:161], v[194:197], v[12:15]
	v_mfma_f32_16x16x32_bf16 v[60:63], v[154:157], v[174:177], v[60:63]
	v_mfma_f32_16x16x32_bf16 v[56:59], v[166:169], v[174:177], v[56:59]
	v_mfma_f32_16x16x32_bf16 v[52:55], v[154:157], v[182:185], v[52:55]
	v_mfma_f32_16x16x32_bf16 v[44:47], v[166:169], v[182:185], v[44:47]
	v_mfma_f32_16x16x32_bf16 v[36:39], v[154:157], v[190:193], v[36:39]
	v_mfma_f32_16x16x32_bf16 v[28:31], v[166:169], v[190:193], v[28:31]
	v_mfma_f32_16x16x32_bf16 v[20:23], v[154:157], v[198:201], v[20:23]
	v_mfma_f32_16x16x32_bf16 v[12:15], v[166:169], v[198:201], v[12:15]
	v_mfma_f32_16x16x32_bf16 v[48:51], v[202:205], v[170:173], v[48:51]
	v_mfma_f32_16x16x32_bf16 v[40:43], v[210:213], v[170:173], v[40:43]
	v_mfma_f32_16x16x32_bf16 v[32:35], v[202:205], v[178:181], v[32:35]
	v_mfma_f32_16x16x32_bf16 v[24:27], v[210:213], v[178:181], v[24:27]
	v_mfma_f32_16x16x32_bf16 v[16:19], v[202:205], v[186:189], v[16:19]
	v_mfma_f32_16x16x32_bf16 v[8:11], v[210:213], v[186:189], v[8:11]
	v_mfma_f32_16x16x32_bf16 v[4:7], v[202:205], v[194:197], v[4:7]
	v_mfma_f32_16x16x32_bf16 v[0:3], v[210:213], v[194:197], v[0:3]
	v_mfma_f32_16x16x32_bf16 v[48:51], v[206:209], v[174:177], v[48:51]
	v_mfma_f32_16x16x32_bf16 v[40:43], v[214:217], v[174:177], v[40:43]
	v_mfma_f32_16x16x32_bf16 v[32:35], v[206:209], v[182:185], v[32:35]
	v_mfma_f32_16x16x32_bf16 v[24:27], v[214:217], v[182:185], v[24:27]
	v_mfma_f32_16x16x32_bf16 v[16:19], v[206:209], v[190:193], v[16:19]
	v_mfma_f32_16x16x32_bf16 v[8:11], v[214:217], v[190:193], v[8:11]
	v_mfma_f32_16x16x32_bf16 v[4:7], v[206:209], v[198:201], v[4:7]
	v_mfma_f32_16x16x32_bf16 v[0:3], v[214:217], v[198:201], v[0:3]
	s_add_u32 s50, s50, 0x100
	s_addc_u32 s51, s51, 0
	s_add_u32 s41, s41, 0x100
	s_addc_u32 s43, s43, 0
	s_cmp_ge_i32 s77, s76
	s_mov_b32 s45, s77
	s_barrier
	s_cbranch_scc0 .LBB0_1146
	v_lshl_add_u32 v150, s8, 8, v133
	v_lshl_or_b32 v154, s44, 8, v162
	s_cmp_lg_u32 s75, 0
	v_ashrrev_i32_e32 v155, 31, v154
	v_or_b32_e32 v160, 16, v150
	v_or_b32_e32 v158, 32, v150
	v_or_b32_e32 v156, 48, v150
	s_cbranch_scc0 .LBB0_1149
	s_add_i32 s8, s75, -1
	s_lshl_b64 s[44:45], s[8:9], 21
	s_add_u32 s44, s92, s44
	s_addc_u32 s45, s93, s45
	v_lshl_add_u64 v[152:153], v[154:155], 2, s[44:45]
	v_ashrrev_i32_e32 v151, 31, v150
	v_ashrrev_i32_e32 v161, 31, v160
	v_lshl_add_u64 v[152:153], v[152:153], 0, s[22:23]
	v_lshlrev_b64 v[166:167], 12, v[150:151]
	v_lshlrev_b64 v[168:169], 12, v[160:161]
	v_lshl_add_u64 v[166:167], v[152:153], 0, v[166:167]
	v_lshl_add_u64 v[168:169], v[152:153], 0, v[168:169]
	v_ashrrev_i32_e32 v159, 31, v158
	global_store_dwordx4 v[166:167], v[124:127], off
	global_store_dwordx4 v[166:167], v[120:123], off offset:16
	global_store_dwordx4 v[166:167], v[112:115], off offset:512
	global_store_dwordx4 v[166:167], v[104:107], off offset:528
	global_store_dwordx4 v[168:169], v[116:119], off
	global_store_dwordx4 v[168:169], v[108:111], off offset:16
	global_store_dwordx4 v[168:169], v[96:99], off offset:512
	global_store_dwordx4 v[168:169], v[88:91], off offset:528
	v_lshlrev_b64 v[168:169], 12, v[158:159]
	v_lshl_add_u64 v[168:169], v[152:153], 0, v[168:169]
	v_ashrrev_i32_e32 v157, 31, v156
	global_store_dwordx4 v[168:169], v[100:103], off
	global_store_dwordx4 v[168:169], v[92:95], off offset:16
	global_store_dwordx4 v[168:169], v[80:83], off offset:512
	global_store_dwordx4 v[168:169], v[72:75], off offset:528
	v_lshlrev_b64 v[168:169], 12, v[156:157]
	v_lshl_add_u64 v[152:153], v[152:153], 0, v[168:169]
	v_add_co_u32_e32 v168, vcc, s68, v166
	global_store_dwordx4 v[152:153], v[84:87], off
	global_store_dwordx4 v[152:153], v[76:79], off offset:16
	global_store_dwordx4 v[152:153], v[68:71], off offset:512
	global_store_dwordx4 v[152:153], v[64:67], off offset:528
	v_addc_co_u32_e32 v169, vcc, 0, v167, vcc
	v_lshl_add_u64 v[152:153], v[166:167], 0, s[24:25]
	global_store_dwordx4 v[168:169], v[60:63], off
	global_store_dwordx4 v[152:153], v[56:59], off offset:16
	global_store_dwordx4 v[152:153], v[48:51], off offset:512
	global_store_dwordx4 v[152:153], v[40:43], off offset:528
	v_add_co_u32_e32 v168, vcc, s69, v166
	v_lshl_add_u64 v[152:153], v[166:167], 0, s[26:27]
	s_nop 0
	v_addc_co_u32_e32 v169, vcc, 0, v167, vcc
	global_store_dwordx4 v[168:169], v[52:55], off
	global_store_dwordx4 v[152:153], v[44:47], off offset:16
	global_store_dwordx4 v[152:153], v[32:35], off offset:512
	global_store_dwordx4 v[152:153], v[24:27], off offset:528
	v_add_co_u32_e32 v168, vcc, s70, v166
	v_lshl_add_u64 v[152:153], v[166:167], 0, s[28:29]
	s_nop 0
	v_addc_co_u32_e32 v169, vcc, 0, v167, vcc
	global_store_dwordx4 v[168:169], v[36:39], off
	global_store_dwordx4 v[152:153], v[28:31], off offset:16
	global_store_dwordx4 v[152:153], v[16:19], off offset:512
	global_store_dwordx4 v[152:153], v[8:11], off offset:528
	v_lshl_add_u64 v[152:153], v[166:167], 0, s[36:37]
	v_add_co_u32_e32 v166, vcc, 0xb0000, v166
	s_nop 1
	v_addc_co_u32_e32 v167, vcc, 0, v167, vcc
	global_store_dwordx4 v[166:167], v[20:23], off
	global_store_dwordx4 v[152:153], v[12:15], off offset:16
	global_store_dwordx4 v[152:153], v[4:7], off offset:512
	global_store_dwordx4 v[152:153], v[0:3], off offset:528
	s_cbranch_execnz .LBB0_1131
	s_branch .LBB0_1130
